# speedup vs baseline: 1.0370x; 1.0029x over previous
; DEV f32x4 mfma16(bf16x8 a, bf16x8 b, f32x4 c) { return __builtin_amdgcn_mfma_f32_16x16x32_bf16(a, b, c, 0, 0, 0); }
; DEV void gemm_tile(const u16* __restrict__ A, size_t lda, const u16* __restrict__ Bt, size_t ldb, int K,
;                    u16* sA, u16* sB, f32x4 (&acc)[8][4]) {
;     ...
;   for (int kt = 0; kt < nk; ++kt) {
;     const int st = kt & 1;
;     if (kt + 1 < nk) S_STORE(st ^ 1)
;     if (kt + 2 < nk) G_LOAD((kt + 2) << 5)
;     {
;       const u16* pa = sAr + st * 12288;
;       const u16* pb = sBr + st * 12288;
;       bf16x8 b[4];
; #pragma unroll
;       for (int ni = 0; ni < 4; ++ni) b[ni] = *(const bf16x8*)(pb + ni * 16 * 32);
; #pragma unroll
;       for (int mh = 0; mh < 2; ++mh) {
;         bf16x8 a[4];
; #pragma unroll
;         for (int mi = 0; mi < 4; ++mi) a[mi] = *(const bf16x8*)(pa + (mh * 64 + mi * 16) * 32);
; #pragma unroll
;         for (int mi = 0; mi < 4; ++mi)
; #pragma unroll
;           for (int ni = 0; ni < 4; ++ni) acc[mh * 4 + mi][ni] = mfma16(a[mi], b[ni], acc[mh * 4 + mi][ni]);
;       }
;     }
;     __syncthreads();
.LBB0_122:
	v_add_u32_e32 v229, s8, v158
	v_add_u32_e32 v228, s8, v156
	ds_read_b128 v[92:95], v229 offset:16384
	ds_read_b128 v[160:163], v228
	ds_read_b128 v[100:103], v229 offset:17408
	ds_read_b128 v[116:119], v229 offset:18432
	ds_read_b128 v[104:107], v229 offset:19456
	ds_read_b128 v[164:167], v228 offset:1024
	ds_read_b128 v[168:171], v228 offset:2048
	ds_read_b128 v[232:235], v228 offset:3072
	s_waitcnt lgkmcnt(6)
	v_mfma_f32_16x16x32_bf16 v[148:151], v[160:163], v[92:95], v[148:151]
	s_waitcnt lgkmcnt(5)
	v_mfma_f32_16x16x32_bf16 v[144:147], v[160:163], v[100:103], v[144:147]
	s_waitcnt lgkmcnt(4)
	v_mfma_f32_16x16x32_bf16 v[140:143], v[160:163], v[116:119], v[140:143]
	s_waitcnt lgkmcnt(3)
	v_mfma_f32_16x16x32_bf16 v[136:139], v[160:163], v[104:107], v[136:139]
	ds_read_b128 v[236:239], v228 offset:4096
	ds_read_b128 v[240:243], v228 offset:5120
	s_waitcnt lgkmcnt(4)
	v_mfma_f32_16x16x32_bf16 v[132:135], v[164:167], v[92:95], v[132:135]
	s_add_i32 m0, s9, 0x0
	v_mfma_f32_16x16x32_bf16 v[128:131], v[164:167], v[100:103], v[128:131]
	global_load_lds_dwordx4 v[112:113], off
	v_lshl_add_u64 v[112:113], v[112:113], 0, 64
	global_load_dwordx4 v[252:255], v[112:113], off
	v_lshl_add_u64 v[112:113], v[112:113], 0, 64
	v_mfma_f32_16x16x32_bf16 v[124:127], v[164:167], v[116:119], v[124:127]
	s_add_i32 m0, s9, 0x1000
	v_mfma_f32_16x16x32_bf16 v[120:123], v[164:167], v[104:107], v[120:123]
	global_load_lds_dwordx4 v[114:115], off
	v_lshl_add_u64 v[114:115], v[114:115], 0, 64
	global_load_dwordx4 v[208:211], v[114:115], off
	v_lshl_add_u64 v[114:115], v[114:115], 0, 64
	s_waitcnt lgkmcnt(3)
	v_mfma_f32_16x16x32_bf16 v[96:99], v[168:171], v[92:95], v[96:99]
	s_add_i32 m0, s9, 0x2000
	v_mfma_f32_16x16x32_bf16 v[88:91], v[168:171], v[100:103], v[88:91]
	global_load_lds_dwordx4 v[172:173], off
	v_lshl_add_u64 v[172:173], v[172:173], 0, 64
	global_load_dwordx4 v[212:215], v[172:173], off
	v_lshl_add_u64 v[172:173], v[172:173], 0, 64
	v_mfma_f32_16x16x32_bf16 v[84:87], v[168:171], v[116:119], v[84:87]
	s_add_i32 m0, s9, 0x3000
	v_mfma_f32_16x16x32_bf16 v[80:83], v[168:171], v[104:107], v[80:83]
	ds_read_b128 v[244:247], v228 offset:6144
	ds_read_b128 v[160:163], v228 offset:7168
	s_waitcnt lgkmcnt(4)
	v_mfma_f32_16x16x32_bf16 v[76:79], v[232:235], v[92:95], v[76:79]
	global_load_lds_dwordx4 v[108:109], off
	v_lshl_add_u64 v[108:109], v[108:109], 0, 64
	global_load_dwordx4 v[216:219], v[108:109], off
	v_lshl_add_u64 v[108:109], v[108:109], 0, 64
	v_mfma_f32_16x16x32_bf16 v[72:75], v[232:235], v[100:103], v[72:75]
	s_add_i32 m0, s9, 0x4000
	v_mfma_f32_16x16x32_bf16 v[68:71], v[232:235], v[116:119], v[68:71]
	global_load_lds_dwordx4 v[110:111], off
	v_lshl_add_u64 v[110:111], v[110:111], 0, 64
	global_load_dwordx4 v[220:223], v[110:111], off
	v_lshl_add_u64 v[110:111], v[110:111], 0, 64
	v_mfma_f32_16x16x32_bf16 v[64:67], v[232:235], v[104:107], v[64:67]
	s_add_i32 m0, s9, 0x5000
	s_waitcnt lgkmcnt(3)
	v_mfma_f32_16x16x32_bf16 v[60:63], v[236:239], v[92:95], v[60:63]
	global_load_lds_dwordx4 v[174:175], off
	v_lshl_add_u64 v[174:175], v[174:175], 0, 64
	global_load_dwordx4 v[224:227], v[174:175], off
	v_lshl_add_u64 v[174:175], v[174:175], 0, 64
	v_mfma_f32_16x16x32_bf16 v[56:59], v[236:239], v[100:103], v[56:59]
	s_add_i32 s9, s8, s5
	s_add_i32 s8, s8, 0x6000
	v_mfma_f32_16x16x32_bf16 v[52:55], v[236:239], v[116:119], v[52:55]
	s_cmp_eq_u32 s8, 0x12000
	s_cselect_b32 s8, 0, s8
	v_mfma_f32_16x16x32_bf16 v[48:51], v[236:239], v[104:107], v[48:51]
	s_add_u32 s6, s6, 64
	s_addc_u32 s7, s7, 0
	s_cmpk_lg_i32 s6, 0xf80
	s_waitcnt lgkmcnt(2)
	v_mfma_f32_16x16x32_bf16 v[44:47], v[240:243], v[92:95], v[44:47]
	v_mfma_f32_16x16x32_bf16 v[40:43], v[240:243], v[100:103], v[40:43]
	v_mfma_f32_16x16x32_bf16 v[36:39], v[240:243], v[116:119], v[36:39]
	v_mfma_f32_16x16x32_bf16 v[32:35], v[240:243], v[104:107], v[32:35]
	s_waitcnt lgkmcnt(1)
	v_mfma_f32_16x16x32_bf16 v[28:31], v[244:247], v[92:95], v[28:31]
	v_mfma_f32_16x16x32_bf16 v[24:27], v[244:247], v[100:103], v[24:27]
	v_mfma_f32_16x16x32_bf16 v[20:23], v[244:247], v[116:119], v[20:23]
	v_mfma_f32_16x16x32_bf16 v[16:19], v[244:247], v[104:107], v[16:19]
	s_waitcnt lgkmcnt(0)
	s_waitcnt vmcnt(12)
	s_barrier
	v_mfma_f32_16x16x32_bf16 v[12:15], v[160:163], v[92:95], v[12:15]
	v_mfma_f32_16x16x32_bf16 v[8:11], v[160:163], v[100:103], v[8:11]
	v_mfma_f32_16x16x32_bf16 v[4:7], v[160:163], v[116:119], v[4:7]
	v_mfma_f32_16x16x32_bf16 v[0:3], v[160:163], v[104:107], v[0:3]
	v_add_u32_e32 v229, s8, v158
	v_add_u32_e32 v228, s8, v156
	ds_read_b128 v[92:95], v229 offset:16384
	ds_read_b128 v[160:163], v228
	ds_read_b128 v[100:103], v229 offset:17408
	ds_read_b128 v[116:119], v229 offset:18432
	ds_read_b128 v[104:107], v229 offset:19456
	ds_read_b128 v[164:167], v228 offset:1024
	ds_read_b128 v[168:171], v228 offset:2048
	ds_read_b128 v[232:235], v228 offset:3072
	s_waitcnt lgkmcnt(6)
	v_mfma_f32_16x16x32_bf16 v[148:151], v[160:163], v[92:95], v[148:151]
	s_waitcnt lgkmcnt(5)
	v_mfma_f32_16x16x32_bf16 v[144:147], v[160:163], v[100:103], v[144:147]
	s_waitcnt lgkmcnt(4)
	v_mfma_f32_16x16x32_bf16 v[140:143], v[160:163], v[116:119], v[140:143]
	s_waitcnt lgkmcnt(3)
	v_mfma_f32_16x16x32_bf16 v[136:139], v[160:163], v[104:107], v[136:139]
	ds_read_b128 v[236:239], v228 offset:4096
	ds_read_b128 v[240:243], v228 offset:5120
	s_waitcnt lgkmcnt(4)
	v_mfma_f32_16x16x32_bf16 v[132:135], v[164:167], v[92:95], v[132:135]
	v_mfma_f32_16x16x32_bf16 v[128:131], v[164:167], v[100:103], v[128:131]
	v_mfma_f32_16x16x32_bf16 v[124:127], v[164:167], v[116:119], v[124:127]
	v_mfma_f32_16x16x32_bf16 v[120:123], v[164:167], v[104:107], v[120:123]
	s_waitcnt lgkmcnt(3)
; DEV f32x4 mfma16(bf16x8 a, bf16x8 b, f32x4 c) { return __builtin_amdgcn_mfma_f32_16x16x32_bf16(a, b, c, 0, 0, 0); }
; DEV void gemm_tile(const u16* __restrict__ A, size_t lda, const u16* __restrict__ Bt, size_t ldb, int K,
;                    u16* sA, u16* sB, f32x4 (&acc)[8][4]) {
;     ...
;   for (int kt = 0; kt < nk; ++kt) {
;     const int st = kt & 1;
;     if (kt + 1 < nk) S_STORE(st ^ 1)
;     if (kt + 2 < nk) G_LOAD((kt + 2) << 5)
;     {
;       const u16* pa = sAr + st * 12288;
;       const u16* pb = sBr + st * 12288;
;       bf16x8 b[4];
; #pragma unroll
;       for (int ni = 0; ni < 4; ++ni) b[ni] = *(const bf16x8*)(pb + ni * 16 * 32);
; #pragma unroll
;       for (int mh = 0; mh < 2; ++mh) {
;         bf16x8 a[4];
; #pragma unroll
;         for (int mi = 0; mi < 4; ++mi) a[mi] = *(const bf16x8*)(pa + (mh * 64 + mi * 16) * 32);
; #pragma unroll
;         for (int mi = 0; mi < 4; ++mi)
; #pragma unroll
;           for (int ni = 0; ni < 4; ++ni) acc[mh * 4 + mi][ni] = mfma16(a[mi], b[ni], acc[mh * 4 + mi][ni]);
;       }
;     }
;     __syncthreads();
	v_mfma_f32_16x16x32_bf16 v[96:99], v[168:171], v[92:95], v[96:99]
	v_mfma_f32_16x16x32_bf16 v[88:91], v[168:171], v[100:103], v[88:91]
	v_mfma_f32_16x16x32_bf16 v[84:87], v[168:171], v[116:119], v[84:87]
	v_mfma_f32_16x16x32_bf16 v[80:83], v[168:171], v[104:107], v[80:83]
	ds_read_b128 v[244:247], v228 offset:6144
	ds_read_b128 v[160:163], v228 offset:7168
	s_waitcnt lgkmcnt(4)
	v_mfma_f32_16x16x32_bf16 v[76:79], v[232:235], v[92:95], v[76:79]
	s_waitcnt vmcnt(0)
	v_add_u32_e32 v231, s9, v230
	v_mfma_f32_16x16x32_bf16 v[72:75], v[232:235], v[100:103], v[72:75]
	ds_write_b128 v231, v[252:255]
	v_mfma_f32_16x16x32_bf16 v[68:71], v[232:235], v[116:119], v[68:71]
	ds_write_b128 v231, v[208:211] offset:4096
	v_mfma_f32_16x16x32_bf16 v[64:67], v[232:235], v[104:107], v[64:67]
	ds_write_b128 v231, v[212:215] offset:8192
	s_waitcnt lgkmcnt(6)
	v_mfma_f32_16x16x32_bf16 v[60:63], v[236:239], v[92:95], v[60:63]
	ds_write_b128 v231, v[216:219] offset:12288
	v_mfma_f32_16x16x32_bf16 v[56:59], v[236:239], v[100:103], v[56:59]
	ds_write_b128 v231, v[220:223] offset:16384
	v_mfma_f32_16x16x32_bf16 v[52:55], v[236:239], v[116:119], v[52:55]
	ds_write_b128 v231, v[224:227] offset:20480
	v_mfma_f32_16x16x32_bf16 v[48:51], v[236:239], v[104:107], v[48:51]
	s_add_i32 s9, s8, s5
	s_add_i32 s8, s8, 0x6000
	s_waitcnt lgkmcnt(8)
	v_mfma_f32_16x16x32_bf16 v[44:47], v[240:243], v[92:95], v[44:47]
	s_cmp_eq_u32 s8, 0x12000
	s_cselect_b32 s8, 0, s8
	v_mfma_f32_16x16x32_bf16 v[40:43], v[240:243], v[100:103], v[40:43]
	s_add_u32 s6, s6, 64
	s_addc_u32 s7, s7, 0
	s_cmpk_lg_i32 s6, 0xf80
	v_mfma_f32_16x16x32_bf16 v[36:39], v[240:243], v[116:119], v[36:39]
	v_mfma_f32_16x16x32_bf16 v[32:35], v[240:243], v[104:107], v[32:35]
	s_waitcnt lgkmcnt(7)
	v_mfma_f32_16x16x32_bf16 v[28:31], v[244:247], v[92:95], v[28:31]
	v_mfma_f32_16x16x32_bf16 v[24:27], v[244:247], v[100:103], v[24:27]
	v_mfma_f32_16x16x32_bf16 v[20:23], v[244:247], v[116:119], v[20:23]
	v_mfma_f32_16x16x32_bf16 v[16:19], v[244:247], v[104:107], v[16:19]
	s_waitcnt lgkmcnt(6)
	s_waitcnt lgkmcnt(0)
	s_barrier
	v_mfma_f32_16x16x32_bf16 v[12:15], v[160:163], v[92:95], v[12:15]
	v_mfma_f32_16x16x32_bf16 v[8:11], v[160:163], v[100:103], v[8:11]
	v_mfma_f32_16x16x32_bf16 v[4:7], v[160:163], v[116:119], v[4:7]
	v_mfma_f32_16x16x32_bf16 v[0:3], v[160:163], v[104:107], v[0:3]
	s_cbranch_scc1 .LBB0_122
	ds_read_b128 v[92:95], v158 offset:16384
	ds_read_b128 v[100:103], v158 offset:17408
	ds_read_b128 v[104:107], v158 offset:18432
	ds_read_b128 v[108:111], v158 offset:19456
	ds_read_b128 v[112:115], v156
	ds_read_b128 v[116:119], v156 offset:1024
	ds_read_b128 v[152:155], v156 offset:2048
	ds_read_b128 v[160:163], v156 offset:3072
	s_movk_i32 s5, 0xb49
	s_waitcnt lgkmcnt(3)
	v_mfma_f32_16x16x32_bf16 v[148:151], v[112:115], v[92:95], v[148:151]
	v_mfma_f32_16x16x32_bf16 v[144:147], v[112:115], v[100:103], v[144:147]
	v_mfma_f32_16x16x32_bf16 v[140:143], v[112:115], v[104:107], v[140:143]
	v_mfma_f32_16x16x32_bf16 v[112:115], v[112:115], v[108:111], v[136:139]
	s_waitcnt lgkmcnt(2)
	v_mfma_f32_16x16x32_bf16 v[132:135], v[116:119], v[92:95], v[132:135]
	v_mfma_f32_16x16x32_bf16 v[128:131], v[116:119], v[100:103], v[128:131]
	v_mfma_f32_16x16x32_bf16 v[136:139], v[116:119], v[104:107], v[124:127]
	v_mfma_f32_16x16x32_bf16 v[164:167], v[116:119], v[108:111], v[120:123]
	s_waitcnt lgkmcnt(1)
	v_mfma_f32_16x16x32_bf16 v[168:171], v[152:155], v[92:95], v[96:99]
	s_nop 2
	ds_read_b128 v[96:99], v156 offset:4096
	ds_read_b128 v[116:119], v156 offset:5120
	ds_read_b128 v[120:123], v156 offset:6144
	ds_read_b128 v[124:127], v156 offset:7168
	s_waitcnt lgkmcnt(0)
	s_waitcnt vmcnt(0)
	s_barrier
	v_mfma_f32_16x16x32_bf16 v[88:91], v[152:155], v[100:103], v[88:91]
	v_mfma_f32_16x16x32_bf16 v[84:87], v[152:155], v[104:107], v[84:87]
	v_mfma_f32_16x16x32_bf16 v[80:83], v[152:155], v[108:111], v[80:83]
	v_mfma_f32_16x16x32_bf16 v[76:79], v[160:163], v[92:95], v[76:79]
	v_mfma_f32_16x16x32_bf16 v[72:75], v[160:163], v[100:103], v[72:75]
	v_mfma_f32_16x16x32_bf16 v[68:71], v[160:163], v[104:107], v[68:71]
	v_mfma_f32_16x16x32_bf16 v[64:67], v[160:163], v[108:111], v[64:67]
	v_mfma_f32_16x16x32_bf16 v[60:63], v[96:99], v[92:95], v[60:63]
	v_mfma_f32_16x16x32_bf16 v[56:59], v[96:99], v[100:103], v[56:59]
	v_mfma_f32_16x16x32_bf16 v[52:55], v[96:99], v[104:107], v[52:55]
	v_mfma_f32_16x16x32_bf16 v[48:51], v[96:99], v[108:111], v[48:51]
	v_mfma_f32_16x16x32_bf16 v[44:47], v[116:119], v[92:95], v[44:47]
	v_mfma_f32_16x16x32_bf16 v[28:31], v[120:123], v[92:95], v[28:31]
	v_mfma_f32_16x16x32_bf16 v[12:15], v[124:127], v[92:95], v[12:15]
	ds_read_b128 v[152:155], v158 offset:40960
	ds_read_b128 v[160:163], v158 offset:41984
	ds_read_b128 v[172:175], v158 offset:43008
	ds_read_b128 v[192:195], v158 offset:44032
	ds_read_b128 v[92:95], v156 offset:24576
	ds_read_b128 v[96:99], v156 offset:25600
	ds_read_b128 v[196:199], v156 offset:26624
	ds_read_b128 v[200:203], v156 offset:27648
	v_mfma_f32_16x16x32_bf16 v[40:43], v[116:119], v[100:103], v[40:43]
	v_mfma_f32_16x16x32_bf16 v[36:39], v[116:119], v[104:107], v[36:39]
	v_mfma_f32_16x16x32_bf16 v[32:35], v[116:119], v[108:111], v[32:35]
	v_mfma_f32_16x16x32_bf16 v[24:27], v[120:123], v[100:103], v[24:27]
	v_mfma_f32_16x16x32_bf16 v[20:23], v[120:123], v[104:107], v[20:23]
	v_mfma_f32_16x16x32_bf16 v[16:19], v[120:123], v[108:111], v[16:19]
	v_mfma_f32_16x16x32_bf16 v[8:11], v[124:127], v[100:103], v[8:11]
	v_mfma_f32_16x16x32_bf16 v[4:7], v[124:127], v[104:107], v[4:7]
	v_mfma_f32_16x16x32_bf16 v[0:3], v[124:127], v[108:111], v[0:3]
	s_waitcnt lgkmcnt(3)
	v_mfma_f32_16x16x32_bf16 v[116:119], v[92:95], v[172:175], v[140:143]
	s_waitcnt lgkmcnt(2)
	v_mfma_f32_16x16x32_bf16 v[108:111], v[96:99], v[152:155], v[132:135]
	v_mfma_f32_16x16x32_bf16 v[104:107], v[96:99], v[160:163], v[128:131]
	v_mfma_f32_16x16x32_bf16 v[100:103], v[96:99], v[172:175], v[136:139]
	s_nop 1
	ds_read_b128 v[128:131], v156 offset:28672
	ds_read_b128 v[132:135], v156 offset:29696
	ds_read_b128 v[136:139], v156 offset:30720
	ds_read_b128 v[140:143], v156 offset:31744
	s_waitcnt lgkmcnt(0)
	s_barrier
; DEV int TID() { int t = threadIdx.x; asm volatile("" : "+v"(t)); return t; }
; DEV f32x4 mfma16(bf16x8 a, bf16x8 b, f32x4 c) { return __builtin_amdgcn_mfma_f32_16x16x32_bf16(a, b, c, 0, 0, 0); }
; DEV void gemm_tile(const u16* __restrict__ A, size_t lda, const u16* __restrict__ Bt, size_t ldb, int K,
;                    u16* sA, u16* sB, f32x4 (&acc)[8][4]) {
;     ...
;         for (int mi = 0; mi < 4; ++mi) a[mi] = *(const bf16x8*)(pa + (mh * 64 + mi * 16) * 32);
; #pragma unroll
;         for (int mi = 0; mi < 4; ++mi)
; #pragma unroll
;           for (int ni = 0; ni < 4; ++ni) acc[mh * 4 + mi][ni] = mfma16(a[mi], b[ni], acc[mh * 4 + mi][ni]);
; DEV void store_tile_bf16(const f32x4 (&acc)[8][4], u16* __restrict__ OUT, size_t ld, int m0, int n0, int ncols,
;                          unsigned char* smem) {
;   const int tid = TID(), lane = tid & 63, wid = tid >> 6;
;   const int wr = wid >> 1, wc = wid & 1, fr = lane & 15, fq = lane >> 4;
;   u16* st = (u16*)(smem + wid * 9216);
; #pragma unroll
;   for (int mh = 0; mh < 2; ++mh) {
; #pragma unroll
;     for (int mi = 0; mi < 4; ++mi)
; #pragma unroll
;       for (int ni = 0; ni < 4; ++ni)
; #pragma unroll
;         for (int j = 0; j < 4; ++j) st[(mi * 16 + fq * 4 + j) * 72 + ni * 16 + fr] = f2bf(acc[mh * 4 + mi][ni][j]);
;     const int chunk = lane & 7;
;     const int c0 = n0 + wc * 64 + chunk * 8;
; #pragma unroll
;     for (int itr = 0; itr < 8; ++itr) {
;       const int rl = (lane >> 3) + 8 * itr;
;       const u32x4 v = *(const u32x4*)(st + rl * 72 + chunk * 8);
;       if (c0 + 8 <= ncols) *(u32x4*)(OUT + (size_t)(m0 + wr * 128 + mh * 64 + rl) * ld + c0) = v;
;     }
;   }
; }
	v_mfma_f32_16x16x32_bf16 v[60:63], v[128:131], v[152:155], v[60:63]
	v_mfma_f32_16x16x32_bf16 v[56:59], v[128:131], v[160:163], v[56:59]
	v_mfma_f32_16x16x32_bf16 v[52:55], v[128:131], v[172:175], v[52:55]
	v_mfma_f32_16x16x32_bf16 v[48:51], v[128:131], v[192:195], v[48:51]
	v_mov_b32_e32 v129, v178
	v_mfma_f32_16x16x32_bf16 v[124:127], v[92:95], v[152:155], v[148:151]
	v_lshrrev_b32_e32 v128, 6, v129
	v_mul_lo_u32 v131, v128, s75
	v_lshrrev_b32_e32 v128, 2, v129
	v_mfma_f32_16x16x32_bf16 v[44:47], v[132:135], v[152:155], v[44:47]
	v_and_b32_e32 v130, 15, v129
	v_lshl_or_b32 v130, v130, 1, v131
	v_mfma_f32_16x16x32_bf16 v[40:43], v[132:135], v[160:163], v[40:43]
	v_mfma_f32_16x16x32_bf16 v[36:39], v[132:135], v[172:175], v[36:39]
	v_mfma_f32_16x16x32_bf16 v[32:35], v[132:135], v[192:195], v[32:35]
	v_lshlrev_b32_e32 v133, 3, v129
	v_and_b32_e32 v132, 12, v128
	v_and_b32_e32 v128, 64, v129
	v_and_b32_e32 v133, 56, v133
	v_or3_b32 v128, v128, s14, v133
	v_lshl_or_b32 v131, v133, 1, v131
	v_bfe_u32 v133, v129, 3, 3
	v_and_b32_e32 v129, 0xffffff80, v129
	v_add_u32_e32 v134, s4, v129
	v_bfe_u32 v135, v124, 16, 1
	s_movk_i32 s4, 0x90
	v_add3_u32 v135, v124, v135, s71
	v_mad_u32_u24 v124, v132, s4, v130
	v_bfe_u32 v130, v125, 16, 1
	v_add3_u32 v125, v125, v130, s71
	v_mfma_f32_16x16x32_bf16 v[120:123], v[92:95], v[160:163], v[144:147]
	ds_write_b16_d16_hi v124, v125 offset:144
	v_bfe_u32 v125, v126, 16, 1
	v_add3_u32 v125, v126, v125, s71
	ds_write_b16_d16_hi v124, v125 offset:288
	v_bfe_u32 v125, v127, 16, 1
	v_add3_u32 v125, v127, v125, s71
	ds_write_b16_d16_hi v124, v125 offset:432
	s_nop 0
	v_bfe_u32 v125, v120, 16, 1
	v_add3_u32 v120, v120, v125, s71
	ds_write_b16_d16_hi v124, v120 offset:32
	v_bfe_u32 v120, v121, 16, 1
	v_add3_u32 v120, v121, v120, s71
	ds_write_b16_d16_hi v124, v120 offset:176
	v_bfe_u32 v120, v122, 16, 1
	v_add3_u32 v120, v122, v120, s71
	ds_write_b16_d16_hi v124, v120 offset:320
	v_bfe_u32 v120, v123, 16, 1
	v_add3_u32 v120, v123, v120, s71
	ds_write_b16_d16_hi v124, v120 offset:464
	v_bfe_u32 v120, v116, 16, 1
	v_add3_u32 v116, v116, v120, s71
	ds_write_b16_d16_hi v124, v116 offset:64
	v_bfe_u32 v116, v117, 16, 1
	v_add3_u32 v116, v117, v116, s71
	v_mfma_f32_16x16x32_bf16 v[112:115], v[92:95], v[192:195], v[112:115]
	ds_write_b16_d16_hi v124, v116 offset:208
	v_bfe_u32 v116, v118, 16, 1
	v_add3_u32 v116, v118, v116, s71
	ds_write_b16_d16_hi v124, v116 offset:352
	v_bfe_u32 v116, v119, 16, 1
	v_add3_u32 v116, v119, v116, s71
	ds_write_b16_d16_hi v124, v116 offset:496
	s_nop 0
	v_bfe_u32 v116, v112, 16, 1
	v_add3_u32 v112, v112, v116, s71
	ds_write_b16_d16_hi v124, v112 offset:96
	v_bfe_u32 v112, v113, 16, 1
	v_add3_u32 v112, v113, v112, s71
	ds_write_b16_d16_hi v124, v112 offset:240
	v_bfe_u32 v112, v114, 16, 1
	v_add3_u32 v112, v114, v112, s71
	ds_write_b16_d16_hi v124, v112 offset:384
	v_bfe_u32 v112, v115, 16, 1
	v_add3_u32 v112, v115, v112, s71
	ds_write_b16_d16_hi v124, v112 offset:528
	v_bfe_u32 v112, v108, 16, 1
	v_add3_u32 v108, v108, v112, s71
	ds_write_b16_d16_hi v124, v108 offset:2304
	v_bfe_u32 v108, v109, 16, 1
	v_add3_u32 v108, v109, v108, s71
	ds_write_b16_d16_hi v124, v108 offset:2448
	v_bfe_u32 v108, v110, 16, 1
	v_add3_u32 v108, v110, v108, s71
	ds_write_b16_d16_hi v124, v108 offset:2592
	v_bfe_u32 v108, v111, 16, 1
	v_add3_u32 v108, v111, v108, s71
	ds_write_b16_d16_hi v124, v108 offset:2736
	v_bfe_u32 v108, v104, 16, 1
	v_add3_u32 v104, v104, v108, s71
	ds_write_b16_d16_hi v124, v104 offset:2336
	v_bfe_u32 v104, v105, 16, 1
	v_add3_u32 v104, v105, v104, s71
	ds_write_b16_d16_hi v124, v104 offset:2480
	v_bfe_u32 v104, v106, 16, 1
	v_add3_u32 v104, v106, v104, s71
	ds_write_b16_d16_hi v124, v104 offset:2624
	v_bfe_u32 v104, v107, 16, 1
	v_add3_u32 v104, v107, v104, s71
	ds_write_b16_d16_hi v124, v104 offset:2768
	v_bfe_u32 v104, v100, 16, 1
	v_add3_u32 v100, v100, v104, s71
	ds_write_b16_d16_hi v124, v100 offset:2368
	v_bfe_u32 v100, v101, 16, 1
	v_add3_u32 v100, v101, v100, s71
	v_mfma_f32_16x16x32_bf16 v[96:99], v[96:99], v[192:195], v[164:167]
	ds_write_b16_d16_hi v124, v100 offset:2512
	v_bfe_u32 v100, v102, 16, 1
	v_add3_u32 v100, v102, v100, s71
	ds_write_b16_d16_hi v124, v100 offset:2656
	v_bfe_u32 v100, v103, 16, 1
	v_add3_u32 v100, v103, v100, s71
	ds_write_b16_d16_hi v124, v100 offset:2800
	s_nop 0
	v_bfe_u32 v100, v96, 16, 1
	v_add3_u32 v96, v96, v100, s71
	ds_write_b16_d16_hi v124, v96 offset:2400
	v_bfe_u32 v96, v97, 16, 1
	v_add3_u32 v96, v97, v96, s71
	v_mfma_f32_16x16x32_bf16 v[92:95], v[196:199], v[152:155], v[168:171]
	ds_write_b16_d16_hi v124, v96 offset:2544
	v_bfe_u32 v96, v98, 16, 1
	v_add3_u32 v96, v98, v96, s71
	ds_write_b16_d16_hi v124, v96 offset:2688
	v_bfe_u32 v96, v99, 16, 1
	v_add3_u32 v96, v99, v96, s71
	ds_write_b16_d16_hi v124, v96 offset:2832
	s_nop 0
	v_bfe_u32 v96, v92, 16, 1
	v_add3_u32 v92, v92, v96, s71
	ds_write_b16_d16_hi v124, v92 offset:4608
	v_bfe_u32 v92, v93, 16, 1
	v_add3_u32 v92, v93, v92, s71
	v_mfma_f32_16x16x32_bf16 v[88:91], v[196:199], v[160:163], v[88:91]
	ds_write_b16_d16_hi v124, v92 offset:4752
	v_bfe_u32 v92, v94, 16, 1
	v_add3_u32 v92, v94, v92, s71
	ds_write_b16_d16_hi v124, v92 offset:4896
	v_bfe_u32 v92, v95, 16, 1
	v_add3_u32 v92, v95, v92, s71
	ds_write_b16_d16_hi v124, v92 offset:5040
	s_nop 0
	v_bfe_u32 v92, v88, 16, 1
	v_add3_u32 v88, v88, v92, s71
	ds_write_b16_d16_hi v124, v88 offset:4640
	v_bfe_u32 v88, v89, 16, 1
	v_add3_u32 v88, v89, v88, s71
; DEV int TID() { int t = threadIdx.x; asm volatile("" : "+v"(t)); return t; }
; DEV void store_tile_bf16(const f32x4 (&acc)[8][4], u16* __restrict__ OUT, size_t ld, int m0, int n0, int ncols,
;                          unsigned char* smem) {
;   const int tid = TID(), lane = tid & 63, wid = tid >> 6;
;   const int wr = wid >> 1, wc = wid & 1, fr = lane & 15, fq = lane >> 4;
;   u16* st = (u16*)(smem + wid * 9216);
; #pragma unroll
;   for (int mh = 0; mh < 2; ++mh) {
; #pragma unroll
;     for (int mi = 0; mi < 4; ++mi)
; #pragma unroll
;       for (int ni = 0; ni < 4; ++ni)
; #pragma unroll
;         for (int j = 0; j < 4; ++j) st[(mi * 16 + fq * 4 + j) * 72 + ni * 16 + fr] = f2bf(acc[mh * 4 + mi][ni][j]);
;     const int chunk = lane & 7;
;     const int c0 = n0 + wc * 64 + chunk * 8;
; #pragma unroll
;     for (int itr = 0; itr < 8; ++itr) {
;       const int rl = (lane >> 3) + 8 * itr;
;       const u32x4 v = *(const u32x4*)(st + rl * 72 + chunk * 8);
;       if (c0 + 8 <= ncols) *(u32x4*)(OUT + (size_t)(m0 + wr * 128 + mh * 64 + rl) * ld + c0) = v;
;     }
;   }
; }
	v_mfma_f32_16x16x32_bf16 v[84:87], v[196:199], v[172:175], v[84:87]
	ds_write_b16_d16_hi v124, v88 offset:4784
	v_bfe_u32 v88, v90, 16, 1
	v_add3_u32 v88, v90, v88, s71
	ds_write_b16_d16_hi v124, v88 offset:4928
	v_bfe_u32 v88, v91, 16, 1
	v_add3_u32 v88, v91, v88, s71
	ds_write_b16_d16_hi v124, v88 offset:5072
	s_nop 0
	v_bfe_u32 v88, v84, 16, 1
	v_add3_u32 v84, v84, v88, s71
	ds_write_b16_d16_hi v124, v84 offset:4672
	v_bfe_u32 v84, v85, 16, 1
	v_add3_u32 v84, v85, v84, s71
	v_mfma_f32_16x16x32_bf16 v[80:83], v[196:199], v[192:195], v[80:83]
	ds_write_b16_d16_hi v124, v84 offset:4816
	v_bfe_u32 v84, v86, 16, 1
	v_add3_u32 v84, v86, v84, s71
	ds_write_b16_d16_hi v124, v84 offset:4960
	v_bfe_u32 v84, v87, 16, 1
	v_add3_u32 v84, v87, v84, s71
	ds_write_b16_d16_hi v124, v84 offset:5104
	s_nop 0
	v_bfe_u32 v84, v80, 16, 1
	v_add3_u32 v80, v80, v84, s71
	ds_write_b16_d16_hi v124, v80 offset:4704
	v_bfe_u32 v80, v81, 16, 1
	v_add3_u32 v80, v81, v80, s71
	v_mfma_f32_16x16x32_bf16 v[76:79], v[200:203], v[152:155], v[76:79]
	ds_write_b16_d16_hi v124, v80 offset:4848
	v_bfe_u32 v80, v82, 16, 1
	v_add3_u32 v80, v82, v80, s71
	ds_write_b16_d16_hi v124, v80 offset:4992
	v_bfe_u32 v80, v83, 16, 1
	v_add3_u32 v80, v83, v80, s71
	ds_write_b16_d16_hi v124, v80 offset:5136
	s_nop 0
	v_bfe_u32 v80, v76, 16, 1
	v_add3_u32 v76, v76, v80, s71
	ds_write_b16_d16_hi v124, v76 offset:6912
	v_bfe_u32 v76, v77, 16, 1
	v_add3_u32 v76, v77, v76, s71
	v_mfma_f32_16x16x32_bf16 v[72:75], v[200:203], v[160:163], v[72:75]
	ds_write_b16_d16_hi v124, v76 offset:7056
	v_bfe_u32 v76, v78, 16, 1
	v_add3_u32 v76, v78, v76, s71
	ds_write_b16_d16_hi v124, v76 offset:7200
	v_bfe_u32 v76, v79, 16, 1
	v_add3_u32 v76, v79, v76, s71
	ds_write_b16_d16_hi v124, v76 offset:7344
	s_nop 0
	v_bfe_u32 v76, v72, 16, 1
	v_add3_u32 v72, v72, v76, s71
	ds_write_b16_d16_hi v124, v72 offset:6944
	v_bfe_u32 v72, v73, 16, 1
	v_add3_u32 v72, v73, v72, s71
	v_mfma_f32_16x16x32_bf16 v[68:71], v[200:203], v[172:175], v[68:71]
	ds_write_b16_d16_hi v124, v72 offset:7088
	v_bfe_u32 v72, v74, 16, 1
	v_add3_u32 v72, v74, v72, s71
	ds_write_b16_d16_hi v124, v72 offset:7232
	v_bfe_u32 v72, v75, 16, 1
	v_add3_u32 v72, v75, v72, s71
	ds_write_b16_d16_hi v124, v72 offset:7376
	s_nop 0
	v_bfe_u32 v72, v68, 16, 1
	v_add3_u32 v68, v68, v72, s71
	ds_write_b16_d16_hi v124, v68 offset:6976
	v_bfe_u32 v68, v69, 16, 1
	v_add3_u32 v68, v69, v68, s71
	v_mfma_f32_16x16x32_bf16 v[64:67], v[200:203], v[192:195], v[64:67]
	ds_write_b16_d16_hi v124, v68 offset:7120
	v_bfe_u32 v68, v70, 16, 1
	v_add3_u32 v68, v70, v68, s71
	ds_write_b16_d16_hi v124, v68 offset:7264
	v_bfe_u32 v68, v71, 16, 1
	v_add3_u32 v68, v71, v68, s71
	ds_write_b16_d16_hi v124, v68 offset:7408
	s_nop 0
	v_bfe_u32 v68, v64, 16, 1
	v_add3_u32 v64, v64, v68, s71
	ds_write_b16_d16_hi v124, v64 offset:7008
	v_bfe_u32 v64, v65, 16, 1
	v_add3_u32 v64, v65, v64, s71
	ds_write_b16_d16_hi v124, v64 offset:7152
	v_bfe_u32 v64, v66, 16, 1
	v_mfma_f32_16x16x32_bf16 v[28:31], v[136:139], v[152:155], v[28:31]
	v_add3_u32 v64, v66, v64, s71
	ds_write_b16_d16_hi v124, v64 offset:7296
	v_bfe_u32 v64, v67, 16, 1
	v_mfma_f32_16x16x32_bf16 v[24:27], v[136:139], v[160:163], v[24:27]
	v_ashrrev_i32_e32 v129, 31, v128
	v_add3_u32 v64, v67, v64, s71
	v_cmp_gt_i32_e32 vcc, s5, v128
	v_mfma_f32_16x16x32_bf16 v[20:23], v[136:139], v[172:175], v[20:23]
	v_lshl_add_u64 v[128:129], v[128:129], 1, s[68:69]
	ds_write_b16_d16_hi v124, v64 offset:7440
	v_mad_u32_u24 v65, v133, s4, v131
	v_mfma_f32_16x16x32_bf16 v[16:19], v[136:139], v[192:195], v[16:19]
	v_or_b32_e32 v64, v134, v133
	ds_write_b16_d16_hi v124, v135
	v_mfma_f32_16x16x32_bf16 v[12:15], v[140:143], v[152:155], v[12:15]
	v_mfma_f32_16x16x32_bf16 v[8:11], v[140:143], v[160:163], v[8:11]
	v_mfma_f32_16x16x32_bf16 v[4:7], v[140:143], v[172:175], v[4:7]
	v_mfma_f32_16x16x32_bf16 v[0:3], v[140:143], v[192:195], v[0:3]
	s_and_saveexec_b64 s[4:5], vcc
	s_cbranch_execz .LBB0_125
	ds_read_b128 v[66:69], v65
	v_mad_i64_i32 v[70:71], s[6:7], v64, s80, v[128:129]
	s_waitcnt lgkmcnt(0)
	global_store_dwordx4 v[70:71], v[66:69], off
	ds_read_b128 v[66:69], v65 offset:1152
	v_or_b32_e32 v70, 8, v64
	v_mad_i64_i32 v[70:71], s[6:7], v70, s80, v[128:129]
	s_waitcnt lgkmcnt(0)
	global_store_dwordx4 v[70:71], v[66:69], off
	ds_read_b128 v[66:69], v65 offset:2304
	v_or_b32_e32 v70, 16, v64
	v_mad_i64_i32 v[70:71], s[6:7], v70, s80, v[128:129]
	s_waitcnt lgkmcnt(0)
	global_store_dwordx4 v[70:71], v[66:69], off
	ds_read_b128 v[66:69], v65 offset:3456
	v_or_b32_e32 v70, 24, v64
	v_mad_i64_i32 v[70:71], s[6:7], v70, s80, v[128:129]
	s_waitcnt lgkmcnt(0)
	global_store_dwordx4 v[70:71], v[66:69], off
	ds_read_b128 v[66:69], v65 offset:4608
	v_or_b32_e32 v70, 32, v64
	v_mad_i64_i32 v[70:71], s[6:7], v70, s80, v[128:129]
	s_waitcnt lgkmcnt(0)
	global_store_dwordx4 v[70:71], v[66:69], off
	ds_read_b128 v[66:69], v65 offset:5760
	v_or_b32_e32 v70, 40, v64
	v_mad_i64_i32 v[70:71], s[6:7], v70, s80, v[128:129]
	s_waitcnt lgkmcnt(0)
	global_store_dwordx4 v[70:71], v[66:69], off
	ds_read_b128 v[66:69], v65 offset:6912
	v_or_b32_e32 v70, 48, v64
	v_mad_i64_i32 v[70:71], s[6:7], v70, s80, v[128:129]
	s_waitcnt lgkmcnt(0)
	global_store_dwordx4 v[70:71], v[66:69], off
	ds_read_b128 v[66:69], v65 offset:8064
	v_or_b32_e32 v70, 56, v64
	v_mad_i64_i32 v[70:71], s[6:7], v70, s80, v[128:129]
	s_waitcnt lgkmcnt(0)
	global_store_dwordx4 v[70:71], v[66:69], off

; DEV f32x4 mfma16(bf16x8 a, bf16x8 b, f32x4 c) { return __builtin_amdgcn_mfma_f32_16x16x32_bf16(a, b, c, 0, 0, 0); }
; DEV void gemm_tile(const u16* __restrict__ A, size_t lda, const u16* __restrict__ Bt, size_t ldb, int K,
;                    u16* sA, u16* sB, f32x4 (&acc)[8][4]) {
;     ...
;   for (int kt = 0; kt < nk; ++kt) {
;     const int st = kt & 1;
;     if (kt + 1 < nk) S_STORE(st ^ 1)
;     if (kt + 2 < nk) G_LOAD((kt + 2) << 5)
;     {
;       const u16* pa = sAr + st * 12288;
;       const u16* pb = sBr + st * 12288;
;       bf16x8 b[4];
; #pragma unroll
;       for (int ni = 0; ni < 4; ++ni) b[ni] = *(const bf16x8*)(pb + ni * 16 * 32);
; #pragma unroll
;       for (int mh = 0; mh < 2; ++mh) {
;         bf16x8 a[4];
; #pragma unroll
;         for (int mi = 0; mi < 4; ++mi) a[mi] = *(const bf16x8*)(pa + (mh * 64 + mi * 16) * 32);
; #pragma unroll
;         for (int mi = 0; mi < 4; ++mi)
; #pragma unroll
;           for (int ni = 0; ni < 4; ++ni) acc[mh * 4 + mi][ni] = mfma16(a[mi], b[ni], acc[mh * 4 + mi][ni]);
;       }
;     }
;     __syncthreads();
.LBB0_162:
	v_add_u32_e32 v229, s7, v158
	v_add_u32_e32 v228, s7, v156
	ds_read_b128 v[92:95], v229 offset:16384
	ds_read_b128 v[160:163], v228
	ds_read_b128 v[100:103], v229 offset:17408
	ds_read_b128 v[116:119], v229 offset:18432
	ds_read_b128 v[104:107], v229 offset:19456
	ds_read_b128 v[164:167], v228 offset:1024
	ds_read_b128 v[168:171], v228 offset:2048
	ds_read_b128 v[232:235], v228 offset:3072
	s_waitcnt lgkmcnt(6)
	v_mfma_f32_16x16x32_bf16 v[148:151], v[160:163], v[92:95], v[148:151]
	s_waitcnt lgkmcnt(5)
	v_mfma_f32_16x16x32_bf16 v[144:147], v[160:163], v[100:103], v[144:147]
	s_waitcnt lgkmcnt(4)
	v_mfma_f32_16x16x32_bf16 v[140:143], v[160:163], v[116:119], v[140:143]
	s_waitcnt lgkmcnt(3)
	v_mfma_f32_16x16x32_bf16 v[136:139], v[160:163], v[104:107], v[136:139]
	ds_read_b128 v[236:239], v228 offset:4096
	ds_read_b128 v[240:243], v228 offset:5120
	s_waitcnt lgkmcnt(4)
	v_mfma_f32_16x16x32_bf16 v[132:135], v[164:167], v[92:95], v[132:135]
	s_add_i32 m0, s10, 0x0
	v_mfma_f32_16x16x32_bf16 v[128:131], v[164:167], v[100:103], v[128:131]
	global_load_lds_dwordx4 v[112:113], off
	v_lshl_add_u64 v[112:113], v[112:113], 0, 64
	global_load_dwordx4 v[252:255], v[112:113], off
	v_lshl_add_u64 v[112:113], v[112:113], 0, 64
	v_mfma_f32_16x16x32_bf16 v[124:127], v[164:167], v[116:119], v[124:127]
	s_add_i32 m0, s10, 0x1000
	v_mfma_f32_16x16x32_bf16 v[120:123], v[164:167], v[104:107], v[120:123]
	global_load_lds_dwordx4 v[114:115], off
	v_lshl_add_u64 v[114:115], v[114:115], 0, 64
	global_load_dwordx4 v[208:211], v[114:115], off
	v_lshl_add_u64 v[114:115], v[114:115], 0, 64
	s_waitcnt lgkmcnt(3)
	v_mfma_f32_16x16x32_bf16 v[96:99], v[168:171], v[92:95], v[96:99]
	s_add_i32 m0, s10, 0x2000
	v_mfma_f32_16x16x32_bf16 v[88:91], v[168:171], v[100:103], v[88:91]
	global_load_lds_dwordx4 v[172:173], off
	v_lshl_add_u64 v[172:173], v[172:173], 0, 64
	global_load_dwordx4 v[212:215], v[172:173], off
	v_lshl_add_u64 v[172:173], v[172:173], 0, 64
	v_mfma_f32_16x16x32_bf16 v[84:87], v[168:171], v[116:119], v[84:87]
	s_add_i32 m0, s10, 0x3000
	v_mfma_f32_16x16x32_bf16 v[80:83], v[168:171], v[104:107], v[80:83]
	ds_read_b128 v[244:247], v228 offset:6144
	ds_read_b128 v[160:163], v228 offset:7168
	s_waitcnt lgkmcnt(4)
	v_mfma_f32_16x16x32_bf16 v[76:79], v[232:235], v[92:95], v[76:79]
	global_load_lds_dwordx4 v[108:109], off
	v_lshl_add_u64 v[108:109], v[108:109], 0, 64
	global_load_dwordx4 v[216:219], v[108:109], off
	v_lshl_add_u64 v[108:109], v[108:109], 0, 64
	v_mfma_f32_16x16x32_bf16 v[72:75], v[232:235], v[100:103], v[72:75]
	s_add_i32 m0, s10, 0x4000
	v_mfma_f32_16x16x32_bf16 v[68:71], v[232:235], v[116:119], v[68:71]
	global_load_lds_dwordx4 v[110:111], off
	v_lshl_add_u64 v[110:111], v[110:111], 0, 64
	global_load_dwordx4 v[220:223], v[110:111], off
	v_lshl_add_u64 v[110:111], v[110:111], 0, 64
	v_mfma_f32_16x16x32_bf16 v[64:67], v[232:235], v[104:107], v[64:67]
	s_add_i32 m0, s10, 0x5000
	s_waitcnt lgkmcnt(3)
	v_mfma_f32_16x16x32_bf16 v[60:63], v[236:239], v[92:95], v[60:63]
	global_load_lds_dwordx4 v[174:175], off
	v_lshl_add_u64 v[174:175], v[174:175], 0, 64
	global_load_dwordx4 v[224:227], v[174:175], off
	v_lshl_add_u64 v[174:175], v[174:175], 0, 64
	v_mfma_f32_16x16x32_bf16 v[56:59], v[236:239], v[100:103], v[56:59]
	s_add_i32 s10, s7, s5
	s_add_i32 s7, s7, 0x6000
	v_mfma_f32_16x16x32_bf16 v[52:55], v[236:239], v[116:119], v[52:55]
	s_cmp_eq_u32 s7, 0x12000
	s_cselect_b32 s7, 0, s7
	v_mfma_f32_16x16x32_bf16 v[48:51], v[236:239], v[104:107], v[48:51]
	s_add_u32 s8, s8, 64
	s_addc_u32 s9, s9, 0
	s_cmpk_lg_i32 s8, 0xf80
	s_waitcnt lgkmcnt(2)
	v_mfma_f32_16x16x32_bf16 v[44:47], v[240:243], v[92:95], v[44:47]
	v_mfma_f32_16x16x32_bf16 v[40:43], v[240:243], v[100:103], v[40:43]
	v_mfma_f32_16x16x32_bf16 v[36:39], v[240:243], v[116:119], v[36:39]
	v_mfma_f32_16x16x32_bf16 v[32:35], v[240:243], v[104:107], v[32:35]
	s_waitcnt lgkmcnt(1)
	v_mfma_f32_16x16x32_bf16 v[28:31], v[244:247], v[92:95], v[28:31]
	v_mfma_f32_16x16x32_bf16 v[24:27], v[244:247], v[100:103], v[24:27]
	v_mfma_f32_16x16x32_bf16 v[20:23], v[244:247], v[116:119], v[20:23]
	v_mfma_f32_16x16x32_bf16 v[16:19], v[244:247], v[104:107], v[16:19]
	s_waitcnt lgkmcnt(0)
	s_waitcnt vmcnt(12)
	s_barrier
	v_mfma_f32_16x16x32_bf16 v[12:15], v[160:163], v[92:95], v[12:15]
	v_mfma_f32_16x16x32_bf16 v[8:11], v[160:163], v[100:103], v[8:11]
	v_mfma_f32_16x16x32_bf16 v[4:7], v[160:163], v[116:119], v[4:7]
	v_mfma_f32_16x16x32_bf16 v[0:3], v[160:163], v[104:107], v[0:3]
	v_add_u32_e32 v229, s7, v158
	v_add_u32_e32 v228, s7, v156
	ds_read_b128 v[92:95], v229 offset:16384
	ds_read_b128 v[160:163], v228
	ds_read_b128 v[100:103], v229 offset:17408
	ds_read_b128 v[116:119], v229 offset:18432
	ds_read_b128 v[104:107], v229 offset:19456
	ds_read_b128 v[164:167], v228 offset:1024
	ds_read_b128 v[168:171], v228 offset:2048
	ds_read_b128 v[232:235], v228 offset:3072
	s_waitcnt lgkmcnt(6)
	v_mfma_f32_16x16x32_bf16 v[148:151], v[160:163], v[92:95], v[148:151]
	s_waitcnt lgkmcnt(5)
	v_mfma_f32_16x16x32_bf16 v[144:147], v[160:163], v[100:103], v[144:147]
	s_waitcnt lgkmcnt(4)
	v_mfma_f32_16x16x32_bf16 v[140:143], v[160:163], v[116:119], v[140:143]
	s_waitcnt lgkmcnt(3)
	v_mfma_f32_16x16x32_bf16 v[136:139], v[160:163], v[104:107], v[136:139]
	ds_read_b128 v[236:239], v228 offset:4096
	ds_read_b128 v[240:243], v228 offset:5120
	s_waitcnt lgkmcnt(4)
	v_mfma_f32_16x16x32_bf16 v[132:135], v[164:167], v[92:95], v[132:135]
	v_mfma_f32_16x16x32_bf16 v[128:131], v[164:167], v[100:103], v[128:131]
	v_mfma_f32_16x16x32_bf16 v[124:127], v[164:167], v[116:119], v[124:127]
	v_mfma_f32_16x16x32_bf16 v[120:123], v[164:167], v[104:107], v[120:123]
	s_waitcnt lgkmcnt(3)
; DEV f32x4 mfma16(bf16x8 a, bf16x8 b, f32x4 c) { return __builtin_amdgcn_mfma_f32_16x16x32_bf16(a, b, c, 0, 0, 0); }
; DEV void gemm_tile(const u16* __restrict__ A, size_t lda, const u16* __restrict__ Bt, size_t ldb, int K,
;                    u16* sA, u16* sB, f32x4 (&acc)[8][4]) {
;     ...
;   for (int kt = 0; kt < nk; ++kt) {
;     const int st = kt & 1;
;     if (kt + 1 < nk) S_STORE(st ^ 1)
;     if (kt + 2 < nk) G_LOAD((kt + 2) << 5)
;     {
;       const u16* pa = sAr + st * 12288;
;       const u16* pb = sBr + st * 12288;
;       bf16x8 b[4];
; #pragma unroll
;       for (int ni = 0; ni < 4; ++ni) b[ni] = *(const bf16x8*)(pb + ni * 16 * 32);
; #pragma unroll
;       for (int mh = 0; mh < 2; ++mh) {
;         bf16x8 a[4];
; #pragma unroll
;         for (int mi = 0; mi < 4; ++mi) a[mi] = *(const bf16x8*)(pa + (mh * 64 + mi * 16) * 32);
; #pragma unroll
;         for (int mi = 0; mi < 4; ++mi)
; #pragma unroll
;           for (int ni = 0; ni < 4; ++ni) acc[mh * 4 + mi][ni] = mfma16(a[mi], b[ni], acc[mh * 4 + mi][ni]);
;       }
;     }
;     __syncthreads();
	v_mfma_f32_16x16x32_bf16 v[96:99], v[168:171], v[92:95], v[96:99]
	v_mfma_f32_16x16x32_bf16 v[88:91], v[168:171], v[100:103], v[88:91]
	v_mfma_f32_16x16x32_bf16 v[84:87], v[168:171], v[116:119], v[84:87]
	v_mfma_f32_16x16x32_bf16 v[80:83], v[168:171], v[104:107], v[80:83]
	ds_read_b128 v[244:247], v228 offset:6144
	ds_read_b128 v[160:163], v228 offset:7168
	s_waitcnt lgkmcnt(4)
	v_mfma_f32_16x16x32_bf16 v[76:79], v[232:235], v[92:95], v[76:79]
	s_waitcnt vmcnt(0)
	v_add_u32_e32 v231, s10, v230
	v_mfma_f32_16x16x32_bf16 v[72:75], v[232:235], v[100:103], v[72:75]
	ds_write_b128 v231, v[252:255]
	v_mfma_f32_16x16x32_bf16 v[68:71], v[232:235], v[116:119], v[68:71]
	ds_write_b128 v231, v[208:211] offset:4096
	v_mfma_f32_16x16x32_bf16 v[64:67], v[232:235], v[104:107], v[64:67]
	ds_write_b128 v231, v[212:215] offset:8192
	s_waitcnt lgkmcnt(6)
	v_mfma_f32_16x16x32_bf16 v[60:63], v[236:239], v[92:95], v[60:63]
	ds_write_b128 v231, v[216:219] offset:12288
	v_mfma_f32_16x16x32_bf16 v[56:59], v[236:239], v[100:103], v[56:59]
	ds_write_b128 v231, v[220:223] offset:16384
	v_mfma_f32_16x16x32_bf16 v[52:55], v[236:239], v[116:119], v[52:55]
	ds_write_b128 v231, v[224:227] offset:20480
	v_mfma_f32_16x16x32_bf16 v[48:51], v[236:239], v[104:107], v[48:51]
	s_add_i32 s10, s7, s5
	s_add_i32 s7, s7, 0x6000
	s_waitcnt lgkmcnt(8)
	v_mfma_f32_16x16x32_bf16 v[44:47], v[240:243], v[92:95], v[44:47]
	s_cmp_eq_u32 s7, 0x12000
	s_cselect_b32 s7, 0, s7
	v_mfma_f32_16x16x32_bf16 v[40:43], v[240:243], v[100:103], v[40:43]
	s_add_u32 s8, s8, 64
	s_addc_u32 s9, s9, 0
	s_cmpk_lg_i32 s8, 0xf80
	v_mfma_f32_16x16x32_bf16 v[36:39], v[240:243], v[116:119], v[36:39]
	v_mfma_f32_16x16x32_bf16 v[32:35], v[240:243], v[104:107], v[32:35]
	s_waitcnt lgkmcnt(7)
	v_mfma_f32_16x16x32_bf16 v[28:31], v[244:247], v[92:95], v[28:31]
	v_mfma_f32_16x16x32_bf16 v[24:27], v[244:247], v[100:103], v[24:27]
	v_mfma_f32_16x16x32_bf16 v[20:23], v[244:247], v[116:119], v[20:23]
	v_mfma_f32_16x16x32_bf16 v[16:19], v[244:247], v[104:107], v[16:19]
	s_waitcnt lgkmcnt(6)
	s_waitcnt lgkmcnt(0)
	s_barrier
	v_mfma_f32_16x16x32_bf16 v[12:15], v[160:163], v[92:95], v[12:15]
	v_mfma_f32_16x16x32_bf16 v[8:11], v[160:163], v[100:103], v[8:11]
	v_mfma_f32_16x16x32_bf16 v[4:7], v[160:163], v[116:119], v[4:7]
	v_mfma_f32_16x16x32_bf16 v[0:3], v[160:163], v[104:107], v[0:3]
	s_cbranch_scc1 .LBB0_162
	ds_read_b128 v[92:95], v158 offset:16384
	ds_read_b128 v[100:103], v158 offset:17408
	ds_read_b128 v[104:107], v158 offset:18432
	ds_read_b128 v[108:111], v158 offset:19456
	ds_read_b128 v[112:115], v156
	ds_read_b128 v[116:119], v156 offset:1024
	ds_read_b128 v[152:155], v156 offset:2048
	ds_read_b128 v[160:163], v156 offset:3072
	s_movk_i32 s5, 0x11f9
	s_waitcnt lgkmcnt(3)
	v_mfma_f32_16x16x32_bf16 v[148:151], v[112:115], v[92:95], v[148:151]
	v_mfma_f32_16x16x32_bf16 v[144:147], v[112:115], v[100:103], v[144:147]
	v_mfma_f32_16x16x32_bf16 v[140:143], v[112:115], v[104:107], v[140:143]
	v_mfma_f32_16x16x32_bf16 v[112:115], v[112:115], v[108:111], v[136:139]
	s_waitcnt lgkmcnt(2)
	v_mfma_f32_16x16x32_bf16 v[132:135], v[116:119], v[92:95], v[132:135]
	v_mfma_f32_16x16x32_bf16 v[128:131], v[116:119], v[100:103], v[128:131]
	v_mfma_f32_16x16x32_bf16 v[136:139], v[116:119], v[104:107], v[124:127]
	v_mfma_f32_16x16x32_bf16 v[164:167], v[116:119], v[108:111], v[120:123]
	s_waitcnt lgkmcnt(1)
	v_mfma_f32_16x16x32_bf16 v[168:171], v[152:155], v[92:95], v[96:99]
	s_nop 2
	ds_read_b128 v[96:99], v156 offset:4096
	ds_read_b128 v[116:119], v156 offset:5120
	ds_read_b128 v[120:123], v156 offset:6144
	ds_read_b128 v[124:127], v156 offset:7168
	s_waitcnt lgkmcnt(0)
	s_waitcnt vmcnt(0)
	s_barrier
	v_mfma_f32_16x16x32_bf16 v[88:91], v[152:155], v[100:103], v[88:91]
	v_mfma_f32_16x16x32_bf16 v[84:87], v[152:155], v[104:107], v[84:87]
	v_mfma_f32_16x16x32_bf16 v[80:83], v[152:155], v[108:111], v[80:83]
	v_mfma_f32_16x16x32_bf16 v[76:79], v[160:163], v[92:95], v[76:79]
	v_mfma_f32_16x16x32_bf16 v[72:75], v[160:163], v[100:103], v[72:75]
	v_mfma_f32_16x16x32_bf16 v[68:71], v[160:163], v[104:107], v[68:71]
	v_mfma_f32_16x16x32_bf16 v[64:67], v[160:163], v[108:111], v[64:67]
	v_mfma_f32_16x16x32_bf16 v[60:63], v[96:99], v[92:95], v[60:63]
	v_mfma_f32_16x16x32_bf16 v[56:59], v[96:99], v[100:103], v[56:59]
	v_mfma_f32_16x16x32_bf16 v[52:55], v[96:99], v[104:107], v[52:55]
	v_mfma_f32_16x16x32_bf16 v[48:51], v[96:99], v[108:111], v[48:51]
	v_mfma_f32_16x16x32_bf16 v[44:47], v[116:119], v[92:95], v[44:47]
	v_mfma_f32_16x16x32_bf16 v[28:31], v[120:123], v[92:95], v[28:31]
	v_mfma_f32_16x16x32_bf16 v[12:15], v[124:127], v[92:95], v[12:15]
	ds_read_b128 v[152:155], v158 offset:40960
	ds_read_b128 v[160:163], v158 offset:41984
	ds_read_b128 v[172:175], v158 offset:43008
	ds_read_b128 v[192:195], v158 offset:44032
	ds_read_b128 v[92:95], v156 offset:24576
	ds_read_b128 v[96:99], v156 offset:25600
	ds_read_b128 v[196:199], v156 offset:26624
	ds_read_b128 v[200:203], v156 offset:27648
	v_mfma_f32_16x16x32_bf16 v[40:43], v[116:119], v[100:103], v[40:43]
	v_mfma_f32_16x16x32_bf16 v[36:39], v[116:119], v[104:107], v[36:39]
	v_mfma_f32_16x16x32_bf16 v[32:35], v[116:119], v[108:111], v[32:35]
	v_mfma_f32_16x16x32_bf16 v[24:27], v[120:123], v[100:103], v[24:27]
	v_mfma_f32_16x16x32_bf16 v[20:23], v[120:123], v[104:107], v[20:23]
	v_mfma_f32_16x16x32_bf16 v[16:19], v[120:123], v[108:111], v[16:19]
	v_mfma_f32_16x16x32_bf16 v[8:11], v[124:127], v[100:103], v[8:11]
	v_mfma_f32_16x16x32_bf16 v[4:7], v[124:127], v[104:107], v[4:7]
	v_mfma_f32_16x16x32_bf16 v[0:3], v[124:127], v[108:111], v[0:3]
	s_waitcnt lgkmcnt(3)
	v_mfma_f32_16x16x32_bf16 v[116:119], v[92:95], v[172:175], v[140:143]
	s_waitcnt lgkmcnt(2)
	v_mfma_f32_16x16x32_bf16 v[108:111], v[96:99], v[152:155], v[132:135]
	v_mfma_f32_16x16x32_bf16 v[104:107], v[96:99], v[160:163], v[128:131]
	v_mfma_f32_16x16x32_bf16 v[100:103], v[96:99], v[172:175], v[136:139]
	s_nop 1
	ds_read_b128 v[128:131], v156 offset:28672
	ds_read_b128 v[132:135], v156 offset:29696
	ds_read_b128 v[136:139], v156 offset:30720
	ds_read_b128 v[140:143], v156 offset:31744
	s_waitcnt lgkmcnt(0)
	s_barrier
; DEV int TID() { int t = threadIdx.x; asm volatile("" : "+v"(t)); return t; }
; DEV f32x4 mfma16(bf16x8 a, bf16x8 b, f32x4 c) { return __builtin_amdgcn_mfma_f32_16x16x32_bf16(a, b, c, 0, 0, 0); }
; DEV void gemm_tile(const u16* __restrict__ A, size_t lda, const u16* __restrict__ Bt, size_t ldb, int K,
;                    u16* sA, u16* sB, f32x4 (&acc)[8][4]) {
;     ...
;         for (int mi = 0; mi < 4; ++mi) a[mi] = *(const bf16x8*)(pa + (mh * 64 + mi * 16) * 32);
; #pragma unroll
;         for (int mi = 0; mi < 4; ++mi)
; #pragma unroll
;           for (int ni = 0; ni < 4; ++ni) acc[mh * 4 + mi][ni] = mfma16(a[mi], b[ni], acc[mh * 4 + mi][ni]);
; DEV void store_tile_bf16(const f32x4 (&acc)[8][4], u16* __restrict__ OUT, size_t ld, int m0, int n0, int ncols,
;                          unsigned char* smem) {
;   const int tid = TID(), lane = tid & 63, wid = tid >> 6;
;   const int wr = wid >> 1, wc = wid & 1, fr = lane & 15, fq = lane >> 4;
;   u16* st = (u16*)(smem + wid * 9216);
; #pragma unroll
;   for (int mh = 0; mh < 2; ++mh) {
; #pragma unroll
;     for (int mi = 0; mi < 4; ++mi)
; #pragma unroll
;       for (int ni = 0; ni < 4; ++ni)
; #pragma unroll
;         for (int j = 0; j < 4; ++j) st[(mi * 16 + fq * 4 + j) * 72 + ni * 16 + fr] = f2bf(acc[mh * 4 + mi][ni][j]);
;     const int chunk = lane & 7;
;     const int c0 = n0 + wc * 64 + chunk * 8;
; #pragma unroll
;     for (int itr = 0; itr < 8; ++itr) {
;       const int rl = (lane >> 3) + 8 * itr;
;       const u32x4 v = *(const u32x4*)(st + rl * 72 + chunk * 8);
;       if (c0 + 8 <= ncols) *(u32x4*)(OUT + (size_t)(m0 + wr * 128 + mh * 64 + rl) * ld + c0) = v;
;     }
;   }
; }
	v_mfma_f32_16x16x32_bf16 v[60:63], v[128:131], v[152:155], v[60:63]
	v_mfma_f32_16x16x32_bf16 v[56:59], v[128:131], v[160:163], v[56:59]
	v_mfma_f32_16x16x32_bf16 v[52:55], v[128:131], v[172:175], v[52:55]
	v_mfma_f32_16x16x32_bf16 v[48:51], v[128:131], v[192:195], v[48:51]
	v_mov_b32_e32 v129, v178
	v_mfma_f32_16x16x32_bf16 v[124:127], v[92:95], v[152:155], v[148:151]
	v_lshrrev_b32_e32 v128, 6, v129
	v_mul_lo_u32 v131, v128, s75
	v_lshrrev_b32_e32 v128, 2, v129
	v_mfma_f32_16x16x32_bf16 v[44:47], v[132:135], v[152:155], v[44:47]
	v_and_b32_e32 v130, 15, v129
	v_lshl_or_b32 v130, v130, 1, v131
	v_mfma_f32_16x16x32_bf16 v[40:43], v[132:135], v[160:163], v[40:43]
	v_mfma_f32_16x16x32_bf16 v[36:39], v[132:135], v[172:175], v[36:39]
	v_mfma_f32_16x16x32_bf16 v[32:35], v[132:135], v[192:195], v[32:35]
	v_lshlrev_b32_e32 v133, 3, v129
	v_and_b32_e32 v132, 12, v128
	v_and_b32_e32 v128, 64, v129
	v_and_b32_e32 v133, 56, v133
	v_or3_b32 v128, v128, s6, v133
	v_lshl_or_b32 v131, v133, 1, v131
	v_bfe_u32 v133, v129, 3, 3
	v_and_b32_e32 v129, 0xffffff80, v129
	v_add_u32_e32 v134, s4, v129
	v_bfe_u32 v135, v124, 16, 1
	s_movk_i32 s4, 0x90
	v_add3_u32 v135, v124, v135, s71
	v_mad_u32_u24 v124, v132, s4, v130
	v_bfe_u32 v130, v125, 16, 1
	v_add3_u32 v125, v125, v130, s71
	v_mfma_f32_16x16x32_bf16 v[120:123], v[92:95], v[160:163], v[144:147]
	ds_write_b16_d16_hi v124, v125 offset:144
	v_bfe_u32 v125, v126, 16, 1
	v_add3_u32 v125, v126, v125, s71
	ds_write_b16_d16_hi v124, v125 offset:288
	v_bfe_u32 v125, v127, 16, 1
	v_add3_u32 v125, v127, v125, s71
	ds_write_b16_d16_hi v124, v125 offset:432
	s_nop 0
	v_bfe_u32 v125, v120, 16, 1
	v_add3_u32 v120, v120, v125, s71
	ds_write_b16_d16_hi v124, v120 offset:32
	v_bfe_u32 v120, v121, 16, 1
	v_add3_u32 v120, v121, v120, s71
	ds_write_b16_d16_hi v124, v120 offset:176
	v_bfe_u32 v120, v122, 16, 1
	v_add3_u32 v120, v122, v120, s71
	ds_write_b16_d16_hi v124, v120 offset:320
	v_bfe_u32 v120, v123, 16, 1
	v_add3_u32 v120, v123, v120, s71
	ds_write_b16_d16_hi v124, v120 offset:464
	v_bfe_u32 v120, v116, 16, 1
	v_add3_u32 v116, v116, v120, s71
	ds_write_b16_d16_hi v124, v116 offset:64
	v_bfe_u32 v116, v117, 16, 1
	v_add3_u32 v116, v117, v116, s71
	v_mfma_f32_16x16x32_bf16 v[112:115], v[92:95], v[192:195], v[112:115]
	ds_write_b16_d16_hi v124, v116 offset:208
	v_bfe_u32 v116, v118, 16, 1
	v_add3_u32 v116, v118, v116, s71
	ds_write_b16_d16_hi v124, v116 offset:352
	v_bfe_u32 v116, v119, 16, 1
	v_add3_u32 v116, v119, v116, s71
	ds_write_b16_d16_hi v124, v116 offset:496
	s_nop 0
	v_bfe_u32 v116, v112, 16, 1
	v_add3_u32 v112, v112, v116, s71
	ds_write_b16_d16_hi v124, v112 offset:96
	v_bfe_u32 v112, v113, 16, 1
	v_add3_u32 v112, v113, v112, s71
	ds_write_b16_d16_hi v124, v112 offset:240
	v_bfe_u32 v112, v114, 16, 1
	v_add3_u32 v112, v114, v112, s71
	ds_write_b16_d16_hi v124, v112 offset:384
	v_bfe_u32 v112, v115, 16, 1
	v_add3_u32 v112, v115, v112, s71
	ds_write_b16_d16_hi v124, v112 offset:528
	v_bfe_u32 v112, v108, 16, 1
	v_add3_u32 v108, v108, v112, s71
	ds_write_b16_d16_hi v124, v108 offset:2304
	v_bfe_u32 v108, v109, 16, 1
	v_add3_u32 v108, v109, v108, s71
	ds_write_b16_d16_hi v124, v108 offset:2448
	v_bfe_u32 v108, v110, 16, 1
	v_add3_u32 v108, v110, v108, s71
	ds_write_b16_d16_hi v124, v108 offset:2592
	v_bfe_u32 v108, v111, 16, 1
	v_add3_u32 v108, v111, v108, s71
	ds_write_b16_d16_hi v124, v108 offset:2736
	v_bfe_u32 v108, v104, 16, 1
	v_add3_u32 v104, v104, v108, s71
	ds_write_b16_d16_hi v124, v104 offset:2336
	v_bfe_u32 v104, v105, 16, 1
	v_add3_u32 v104, v105, v104, s71
	ds_write_b16_d16_hi v124, v104 offset:2480
	v_bfe_u32 v104, v106, 16, 1
	v_add3_u32 v104, v106, v104, s71
	ds_write_b16_d16_hi v124, v104 offset:2624
	v_bfe_u32 v104, v107, 16, 1
	v_add3_u32 v104, v107, v104, s71
	ds_write_b16_d16_hi v124, v104 offset:2768
	v_bfe_u32 v104, v100, 16, 1
	v_add3_u32 v100, v100, v104, s71
	ds_write_b16_d16_hi v124, v100 offset:2368
	v_bfe_u32 v100, v101, 16, 1
	v_add3_u32 v100, v101, v100, s71
	v_mfma_f32_16x16x32_bf16 v[96:99], v[96:99], v[192:195], v[164:167]
	ds_write_b16_d16_hi v124, v100 offset:2512
	v_bfe_u32 v100, v102, 16, 1
	v_add3_u32 v100, v102, v100, s71
	ds_write_b16_d16_hi v124, v100 offset:2656
	v_bfe_u32 v100, v103, 16, 1
	v_add3_u32 v100, v103, v100, s71
	ds_write_b16_d16_hi v124, v100 offset:2800
	s_nop 0
	v_bfe_u32 v100, v96, 16, 1
	v_add3_u32 v96, v96, v100, s71
	ds_write_b16_d16_hi v124, v96 offset:2400
	v_bfe_u32 v96, v97, 16, 1
	v_add3_u32 v96, v97, v96, s71
	v_mfma_f32_16x16x32_bf16 v[92:95], v[196:199], v[152:155], v[168:171]
	ds_write_b16_d16_hi v124, v96 offset:2544
	v_bfe_u32 v96, v98, 16, 1
	v_add3_u32 v96, v98, v96, s71
	ds_write_b16_d16_hi v124, v96 offset:2688
	v_bfe_u32 v96, v99, 16, 1
	v_add3_u32 v96, v99, v96, s71
	ds_write_b16_d16_hi v124, v96 offset:2832
	s_nop 0
	v_bfe_u32 v96, v92, 16, 1
	v_add3_u32 v92, v92, v96, s71
	ds_write_b16_d16_hi v124, v92 offset:4608
	v_bfe_u32 v92, v93, 16, 1
	v_add3_u32 v92, v93, v92, s71
	v_mfma_f32_16x16x32_bf16 v[88:91], v[196:199], v[160:163], v[88:91]
	ds_write_b16_d16_hi v124, v92 offset:4752
	v_bfe_u32 v92, v94, 16, 1
	v_add3_u32 v92, v94, v92, s71
	ds_write_b16_d16_hi v124, v92 offset:4896
	v_bfe_u32 v92, v95, 16, 1
	v_add3_u32 v92, v95, v92, s71
	ds_write_b16_d16_hi v124, v92 offset:5040
	s_nop 0
	v_bfe_u32 v92, v88, 16, 1
	v_add3_u32 v88, v88, v92, s71
	ds_write_b16_d16_hi v124, v88 offset:4640
	v_bfe_u32 v88, v89, 16, 1
	v_add3_u32 v88, v89, v88, s71
; DEV int TID() { int t = threadIdx.x; asm volatile("" : "+v"(t)); return t; }
; DEV void store_tile_bf16(const f32x4 (&acc)[8][4], u16* __restrict__ OUT, size_t ld, int m0, int n0, int ncols,
;                          unsigned char* smem) {
;   const int tid = TID(), lane = tid & 63, wid = tid >> 6;
;   const int wr = wid >> 1, wc = wid & 1, fr = lane & 15, fq = lane >> 4;
;   u16* st = (u16*)(smem + wid * 9216);
; #pragma unroll
;   for (int mh = 0; mh < 2; ++mh) {
; #pragma unroll
;     for (int mi = 0; mi < 4; ++mi)
; #pragma unroll
;       for (int ni = 0; ni < 4; ++ni)
; #pragma unroll
;         for (int j = 0; j < 4; ++j) st[(mi * 16 + fq * 4 + j) * 72 + ni * 16 + fr] = f2bf(acc[mh * 4 + mi][ni][j]);
;     const int chunk = lane & 7;
;     const int c0 = n0 + wc * 64 + chunk * 8;
; #pragma unroll
;     for (int itr = 0; itr < 8; ++itr) {
;       const int rl = (lane >> 3) + 8 * itr;
;       const u32x4 v = *(const u32x4*)(st + rl * 72 + chunk * 8);
;       if (c0 + 8 <= ncols) *(u32x4*)(OUT + (size_t)(m0 + wr * 128 + mh * 64 + rl) * ld + c0) = v;
;     }
;   }
; }
	v_mfma_f32_16x16x32_bf16 v[84:87], v[196:199], v[172:175], v[84:87]
	ds_write_b16_d16_hi v124, v88 offset:4784
	v_bfe_u32 v88, v90, 16, 1
	v_add3_u32 v88, v90, v88, s71
	ds_write_b16_d16_hi v124, v88 offset:4928
	v_bfe_u32 v88, v91, 16, 1
	v_add3_u32 v88, v91, v88, s71
	ds_write_b16_d16_hi v124, v88 offset:5072
	s_nop 0
	v_bfe_u32 v88, v84, 16, 1
	v_add3_u32 v84, v84, v88, s71
	ds_write_b16_d16_hi v124, v84 offset:4672
	v_bfe_u32 v84, v85, 16, 1
	v_add3_u32 v84, v85, v84, s71
	v_mfma_f32_16x16x32_bf16 v[80:83], v[196:199], v[192:195], v[80:83]
	ds_write_b16_d16_hi v124, v84 offset:4816
	v_bfe_u32 v84, v86, 16, 1
	v_add3_u32 v84, v86, v84, s71
	ds_write_b16_d16_hi v124, v84 offset:4960
	v_bfe_u32 v84, v87, 16, 1
	v_add3_u32 v84, v87, v84, s71
	ds_write_b16_d16_hi v124, v84 offset:5104
	s_nop 0
	v_bfe_u32 v84, v80, 16, 1
	v_add3_u32 v80, v80, v84, s71
	ds_write_b16_d16_hi v124, v80 offset:4704
	v_bfe_u32 v80, v81, 16, 1
	v_add3_u32 v80, v81, v80, s71
	v_mfma_f32_16x16x32_bf16 v[76:79], v[200:203], v[152:155], v[76:79]
	ds_write_b16_d16_hi v124, v80 offset:4848
	v_bfe_u32 v80, v82, 16, 1
	v_add3_u32 v80, v82, v80, s71
	ds_write_b16_d16_hi v124, v80 offset:4992
	v_bfe_u32 v80, v83, 16, 1
	v_add3_u32 v80, v83, v80, s71
	ds_write_b16_d16_hi v124, v80 offset:5136
	s_nop 0
	v_bfe_u32 v80, v76, 16, 1
	v_add3_u32 v76, v76, v80, s71
	ds_write_b16_d16_hi v124, v76 offset:6912
	v_bfe_u32 v76, v77, 16, 1
	v_add3_u32 v76, v77, v76, s71
	v_mfma_f32_16x16x32_bf16 v[72:75], v[200:203], v[160:163], v[72:75]
	ds_write_b16_d16_hi v124, v76 offset:7056
	v_bfe_u32 v76, v78, 16, 1
	v_add3_u32 v76, v78, v76, s71
	ds_write_b16_d16_hi v124, v76 offset:7200
	v_bfe_u32 v76, v79, 16, 1
	v_add3_u32 v76, v79, v76, s71
	ds_write_b16_d16_hi v124, v76 offset:7344
	s_nop 0
	v_bfe_u32 v76, v72, 16, 1
	v_add3_u32 v72, v72, v76, s71
	ds_write_b16_d16_hi v124, v72 offset:6944
	v_bfe_u32 v72, v73, 16, 1
	v_add3_u32 v72, v73, v72, s71
	v_mfma_f32_16x16x32_bf16 v[68:71], v[200:203], v[172:175], v[68:71]
	ds_write_b16_d16_hi v124, v72 offset:7088
	v_bfe_u32 v72, v74, 16, 1
	v_add3_u32 v72, v74, v72, s71
	ds_write_b16_d16_hi v124, v72 offset:7232
	v_bfe_u32 v72, v75, 16, 1
	v_add3_u32 v72, v75, v72, s71
	ds_write_b16_d16_hi v124, v72 offset:7376
	s_nop 0
	v_bfe_u32 v72, v68, 16, 1
	v_add3_u32 v68, v68, v72, s71
	ds_write_b16_d16_hi v124, v68 offset:6976
	v_bfe_u32 v68, v69, 16, 1
	v_add3_u32 v68, v69, v68, s71
	v_mfma_f32_16x16x32_bf16 v[64:67], v[200:203], v[192:195], v[64:67]
	ds_write_b16_d16_hi v124, v68 offset:7120
	v_bfe_u32 v68, v70, 16, 1
	v_add3_u32 v68, v70, v68, s71
	ds_write_b16_d16_hi v124, v68 offset:7264
	v_bfe_u32 v68, v71, 16, 1
	v_add3_u32 v68, v71, v68, s71
	ds_write_b16_d16_hi v124, v68 offset:7408
	s_nop 0
	v_bfe_u32 v68, v64, 16, 1
	v_add3_u32 v64, v64, v68, s71
	ds_write_b16_d16_hi v124, v64 offset:7008
	v_bfe_u32 v64, v65, 16, 1
	v_add3_u32 v64, v65, v64, s71
	ds_write_b16_d16_hi v124, v64 offset:7152
	v_bfe_u32 v64, v66, 16, 1
	v_mfma_f32_16x16x32_bf16 v[28:31], v[136:139], v[152:155], v[28:31]
	v_add3_u32 v64, v66, v64, s71
	ds_write_b16_d16_hi v124, v64 offset:7296
	v_bfe_u32 v64, v67, 16, 1
	v_mfma_f32_16x16x32_bf16 v[24:27], v[136:139], v[160:163], v[24:27]
	v_ashrrev_i32_e32 v129, 31, v128
	v_add3_u32 v64, v67, v64, s71
	v_cmp_gt_i32_e32 vcc, s5, v128
	v_mfma_f32_16x16x32_bf16 v[20:23], v[136:139], v[172:175], v[20:23]
	v_lshl_add_u64 v[128:129], v[128:129], 1, s[68:69]
	ds_write_b16_d16_hi v124, v64 offset:7440
	v_mad_u32_u24 v65, v133, s4, v131
	v_mfma_f32_16x16x32_bf16 v[16:19], v[136:139], v[192:195], v[16:19]
	v_or_b32_e32 v64, v134, v133
	ds_write_b16_d16_hi v124, v135
	v_mfma_f32_16x16x32_bf16 v[12:15], v[140:143], v[152:155], v[12:15]
	v_mfma_f32_16x16x32_bf16 v[8:11], v[140:143], v[160:163], v[8:11]
	v_mfma_f32_16x16x32_bf16 v[4:7], v[140:143], v[172:175], v[4:7]
	v_mfma_f32_16x16x32_bf16 v[0:3], v[140:143], v[192:195], v[0:3]
	s_and_saveexec_b64 s[4:5], vcc
	s_cbranch_execz .LBB0_165
	ds_read_b128 v[66:69], v65
	v_mad_i64_i32 v[70:71], s[6:7], v64, s75, v[128:129]
	s_waitcnt lgkmcnt(0)
	global_store_dwordx4 v[70:71], v[66:69], off
	ds_read_b128 v[66:69], v65 offset:1152
	v_or_b32_e32 v70, 8, v64
	v_mad_i64_i32 v[70:71], s[6:7], v70, s75, v[128:129]
	s_waitcnt lgkmcnt(0)
	global_store_dwordx4 v[70:71], v[66:69], off
	ds_read_b128 v[66:69], v65 offset:2304
	v_or_b32_e32 v70, 16, v64
	v_mad_i64_i32 v[70:71], s[6:7], v70, s75, v[128:129]
	s_waitcnt lgkmcnt(0)
	global_store_dwordx4 v[70:71], v[66:69], off
	ds_read_b128 v[66:69], v65 offset:3456
	v_or_b32_e32 v70, 24, v64
	v_mad_i64_i32 v[70:71], s[6:7], v70, s75, v[128:129]
	s_waitcnt lgkmcnt(0)
	global_store_dwordx4 v[70:71], v[66:69], off
	ds_read_b128 v[66:69], v65 offset:4608
	v_or_b32_e32 v70, 32, v64
	v_mad_i64_i32 v[70:71], s[6:7], v70, s75, v[128:129]
	s_waitcnt lgkmcnt(0)
	global_store_dwordx4 v[70:71], v[66:69], off
	ds_read_b128 v[66:69], v65 offset:5760
	v_or_b32_e32 v70, 40, v64
	v_mad_i64_i32 v[70:71], s[6:7], v70, s75, v[128:129]
	s_waitcnt lgkmcnt(0)
	global_store_dwordx4 v[70:71], v[66:69], off
	ds_read_b128 v[66:69], v65 offset:6912
	v_or_b32_e32 v70, 48, v64
	v_mad_i64_i32 v[70:71], s[6:7], v70, s75, v[128:129]
	s_waitcnt lgkmcnt(0)
	global_store_dwordx4 v[70:71], v[66:69], off
	ds_read_b128 v[66:69], v65 offset:8064
	v_or_b32_e32 v70, 56, v64
	v_mad_i64_i32 v[70:71], s[6:7], v70, s75, v[128:129]
	s_waitcnt lgkmcnt(0)
	global_store_dwordx4 v[70:71], v[66:69], off

; DEV f32x4 mfma16(bf16x8 a, bf16x8 b, f32x4 c) { return __builtin_amdgcn_mfma_f32_16x16x32_bf16(a, b, c, 0, 0, 0); }
; DEV void gemm_tile(const u16* __restrict__ A, size_t lda, const u16* __restrict__ Bt, size_t ldb, int K,
;                    u16* sA, u16* sB, f32x4 (&acc)[8][4]) {
;     ...
;   for (int kt = 0; kt < nk; ++kt) {
;     const int st = kt & 1;
;     if (kt + 1 < nk) S_STORE(st ^ 1)
;     if (kt + 2 < nk) G_LOAD((kt + 2) << 5)
;     {
;       const u16* pa = sAr + st * 12288;
;       const u16* pb = sBr + st * 12288;
;       bf16x8 b[4];
; #pragma unroll
;       for (int ni = 0; ni < 4; ++ni) b[ni] = *(const bf16x8*)(pb + ni * 16 * 32);
; #pragma unroll
;       for (int mh = 0; mh < 2; ++mh) {
;         bf16x8 a[4];
; #pragma unroll
;         for (int mi = 0; mi < 4; ++mi) a[mi] = *(const bf16x8*)(pa + (mh * 64 + mi * 16) * 32);
; #pragma unroll
;         for (int mi = 0; mi < 4; ++mi)
; #pragma unroll
;           for (int ni = 0; ni < 4; ++ni) acc[mh * 4 + mi][ni] = mfma16(a[mi], b[ni], acc[mh * 4 + mi][ni]);
;       }
;     }
;     __syncthreads();
.LBB0_198:
	v_add_u32_e32 v229, s8, v166
	v_add_u32_e32 v228, s8, v156
	ds_read_b128 v[116:119], v229 offset:16384
	ds_read_b128 v[168:171], v228
	ds_read_b128 v[128:131], v229 offset:17408
	ds_read_b128 v[140:143], v229 offset:18432
	ds_read_b128 v[120:123], v229 offset:19456
	ds_read_b128 v[152:155], v228 offset:1024
	ds_read_b128 v[172:175], v228 offset:2048
	ds_read_b128 v[132:135], v228 offset:3072
	s_waitcnt lgkmcnt(6)
	v_mfma_f32_16x16x32_bf16 v[148:151], v[168:171], v[116:119], v[148:151]
	s_waitcnt lgkmcnt(5)
	v_mfma_f32_16x16x32_bf16 v[144:147], v[168:171], v[128:131], v[144:147]
	s_waitcnt lgkmcnt(4)
	v_mfma_f32_16x16x32_bf16 v[124:127], v[168:171], v[140:143], v[124:127]
	s_waitcnt lgkmcnt(3)
	v_mfma_f32_16x16x32_bf16 v[112:115], v[168:171], v[120:123], v[112:115]
	ds_read_b128 v[232:235], v228 offset:4096
	ds_read_b128 v[236:239], v228 offset:5120
	s_waitcnt lgkmcnt(4)
	v_mfma_f32_16x16x32_bf16 v[108:111], v[152:155], v[116:119], v[108:111]
	s_add_i32 m0, s9, 0x0
	v_mfma_f32_16x16x32_bf16 v[104:107], v[152:155], v[128:131], v[104:107]
	global_load_lds_dwordx4 v[136:137], off
	v_lshl_add_u64 v[136:137], v[136:137], 0, 64
	global_load_dwordx4 v[244:247], v[136:137], off
	v_lshl_add_u64 v[136:137], v[136:137], 0, 64
	v_mfma_f32_16x16x32_bf16 v[100:103], v[152:155], v[140:143], v[100:103]
	s_add_i32 m0, s9, 0x1000
	v_mfma_f32_16x16x32_bf16 v[96:99], v[152:155], v[120:123], v[96:99]
	global_load_lds_dwordx4 v[138:139], off
	v_lshl_add_u64 v[138:139], v[138:139], 0, 64
	global_load_dwordx4 v[252:255], v[138:139], off
	v_lshl_add_u64 v[138:139], v[138:139], 0, 64
	s_waitcnt lgkmcnt(3)
	v_mfma_f32_16x16x32_bf16 v[92:95], v[172:175], v[116:119], v[92:95]
	s_add_i32 m0, s9, 0x2000
	v_mfma_f32_16x16x32_bf16 v[88:91], v[172:175], v[128:131], v[88:91]
	global_load_lds_dwordx4 v[176:177], off
	v_lshl_add_u64 v[176:177], v[176:177], 0, 64
	global_load_dwordx4 v[208:211], v[176:177], off
	v_lshl_add_u64 v[176:177], v[176:177], 0, 64
	v_mfma_f32_16x16x32_bf16 v[84:87], v[172:175], v[140:143], v[84:87]
	s_add_i32 m0, s9, 0x3000
	v_mfma_f32_16x16x32_bf16 v[80:83], v[172:175], v[120:123], v[80:83]
	ds_read_b128 v[240:243], v228 offset:6144
	ds_read_b128 v[168:171], v228 offset:7168
	s_waitcnt lgkmcnt(4)
	v_mfma_f32_16x16x32_bf16 v[76:79], v[132:135], v[116:119], v[76:79]
	global_load_lds_dwordx4 v[186:187], off
	v_lshl_add_u64 v[186:187], v[186:187], 0, 64
	global_load_dwordx4 v[212:215], v[186:187], off
	v_lshl_add_u64 v[186:187], v[186:187], 0, 64
	v_mfma_f32_16x16x32_bf16 v[72:75], v[132:135], v[128:131], v[72:75]
	s_add_i32 m0, s9, 0x4000
	v_mfma_f32_16x16x32_bf16 v[68:71], v[132:135], v[140:143], v[68:71]
	global_load_lds_dwordx4 v[188:189], off
	v_lshl_add_u64 v[188:189], v[188:189], 0, 64
	global_load_dwordx4 v[216:219], v[188:189], off
	v_lshl_add_u64 v[188:189], v[188:189], 0, 64
	v_mfma_f32_16x16x32_bf16 v[64:67], v[132:135], v[120:123], v[64:67]
	s_add_i32 m0, s9, 0x5000
	s_waitcnt lgkmcnt(3)
	v_mfma_f32_16x16x32_bf16 v[60:63], v[232:235], v[116:119], v[60:63]
	global_load_lds_dwordx4 v[192:193], off
	v_lshl_add_u64 v[192:193], v[192:193], 0, 64
	global_load_dwordx4 v[220:223], v[192:193], off
	v_lshl_add_u64 v[192:193], v[192:193], 0, 64
	v_mfma_f32_16x16x32_bf16 v[56:59], v[232:235], v[128:131], v[56:59]
	s_add_i32 s9, s8, s5
	s_add_i32 s8, s8, 0x6000
	v_mfma_f32_16x16x32_bf16 v[52:55], v[232:235], v[140:143], v[52:55]
	s_cmp_eq_u32 s8, 0x12000
	s_cselect_b32 s8, 0, s8
	v_mfma_f32_16x16x32_bf16 v[48:51], v[232:235], v[120:123], v[48:51]
	s_add_u32 s6, s6, 64
	s_addc_u32 s7, s7, 0
	s_cmpk_lg_i32 s6, 0xf80
	s_waitcnt lgkmcnt(2)
	v_mfma_f32_16x16x32_bf16 v[44:47], v[236:239], v[116:119], v[44:47]
	v_mfma_f32_16x16x32_bf16 v[40:43], v[236:239], v[128:131], v[40:43]
	v_mfma_f32_16x16x32_bf16 v[36:39], v[236:239], v[140:143], v[36:39]
	v_mfma_f32_16x16x32_bf16 v[32:35], v[236:239], v[120:123], v[32:35]
	s_waitcnt lgkmcnt(1)
	v_mfma_f32_16x16x32_bf16 v[28:31], v[240:243], v[116:119], v[28:31]
	v_mfma_f32_16x16x32_bf16 v[24:27], v[240:243], v[128:131], v[24:27]
	v_mfma_f32_16x16x32_bf16 v[20:23], v[240:243], v[140:143], v[20:23]
	v_mfma_f32_16x16x32_bf16 v[16:19], v[240:243], v[120:123], v[16:19]
	s_waitcnt lgkmcnt(0)
	s_waitcnt vmcnt(12)
	s_barrier
	v_mfma_f32_16x16x32_bf16 v[12:15], v[168:171], v[116:119], v[12:15]
	v_mfma_f32_16x16x32_bf16 v[8:11], v[168:171], v[128:131], v[8:11]
	v_mfma_f32_16x16x32_bf16 v[4:7], v[168:171], v[140:143], v[4:7]
	v_mfma_f32_16x16x32_bf16 v[0:3], v[168:171], v[120:123], v[0:3]
	v_add_u32_e32 v229, s8, v166
	v_add_u32_e32 v228, s8, v156
	ds_read_b128 v[116:119], v229 offset:16384
	ds_read_b128 v[168:171], v228
	ds_read_b128 v[128:131], v229 offset:17408
	ds_read_b128 v[140:143], v229 offset:18432
	ds_read_b128 v[120:123], v229 offset:19456
	ds_read_b128 v[152:155], v228 offset:1024
	ds_read_b128 v[172:175], v228 offset:2048
	ds_read_b128 v[132:135], v228 offset:3072
	s_waitcnt lgkmcnt(6)
	v_mfma_f32_16x16x32_bf16 v[148:151], v[168:171], v[116:119], v[148:151]
	s_waitcnt lgkmcnt(5)
	v_mfma_f32_16x16x32_bf16 v[144:147], v[168:171], v[128:131], v[144:147]
	s_waitcnt lgkmcnt(4)
	v_mfma_f32_16x16x32_bf16 v[124:127], v[168:171], v[140:143], v[124:127]
	s_waitcnt lgkmcnt(3)
	v_mfma_f32_16x16x32_bf16 v[112:115], v[168:171], v[120:123], v[112:115]
	ds_read_b128 v[232:235], v228 offset:4096
	ds_read_b128 v[236:239], v228 offset:5120
	s_waitcnt lgkmcnt(4)
	v_mfma_f32_16x16x32_bf16 v[108:111], v[152:155], v[116:119], v[108:111]
	v_mfma_f32_16x16x32_bf16 v[104:107], v[152:155], v[128:131], v[104:107]
	v_mfma_f32_16x16x32_bf16 v[100:103], v[152:155], v[140:143], v[100:103]
	v_mfma_f32_16x16x32_bf16 v[96:99], v[152:155], v[120:123], v[96:99]
	s_waitcnt lgkmcnt(3)
; DEV f32x4 mfma16(bf16x8 a, bf16x8 b, f32x4 c) { return __builtin_amdgcn_mfma_f32_16x16x32_bf16(a, b, c, 0, 0, 0); }
; DEV void gemm_tile(const u16* __restrict__ A, size_t lda, const u16* __restrict__ Bt, size_t ldb, int K,
;                    u16* sA, u16* sB, f32x4 (&acc)[8][4]) {
;     ...
;   for (int kt = 0; kt < nk; ++kt) {
;     const int st = kt & 1;
;     if (kt + 1 < nk) S_STORE(st ^ 1)
;     if (kt + 2 < nk) G_LOAD((kt + 2) << 5)
;     {
;       const u16* pa = sAr + st * 12288;
;       const u16* pb = sBr + st * 12288;
;       bf16x8 b[4];
; #pragma unroll
;       for (int ni = 0; ni < 4; ++ni) b[ni] = *(const bf16x8*)(pb + ni * 16 * 32);
; #pragma unroll
;       for (int mh = 0; mh < 2; ++mh) {
;         bf16x8 a[4];
; #pragma unroll
;         for (int mi = 0; mi < 4; ++mi) a[mi] = *(const bf16x8*)(pa + (mh * 64 + mi * 16) * 32);
; #pragma unroll
;         for (int mi = 0; mi < 4; ++mi)
; #pragma unroll
;           for (int ni = 0; ni < 4; ++ni) acc[mh * 4 + mi][ni] = mfma16(a[mi], b[ni], acc[mh * 4 + mi][ni]);
;       }
;     }
;     __syncthreads();
	v_mfma_f32_16x16x32_bf16 v[92:95], v[172:175], v[116:119], v[92:95]
	v_mfma_f32_16x16x32_bf16 v[88:91], v[172:175], v[128:131], v[88:91]
	v_mfma_f32_16x16x32_bf16 v[84:87], v[172:175], v[140:143], v[84:87]
	v_mfma_f32_16x16x32_bf16 v[80:83], v[172:175], v[120:123], v[80:83]
	ds_read_b128 v[240:243], v228 offset:6144
	ds_read_b128 v[168:171], v228 offset:7168
	s_waitcnt lgkmcnt(4)
	v_mfma_f32_16x16x32_bf16 v[76:79], v[132:135], v[116:119], v[76:79]
	s_waitcnt vmcnt(0)
	v_add_u32_e32 v231, s9, v230
	v_mfma_f32_16x16x32_bf16 v[72:75], v[132:135], v[128:131], v[72:75]
	ds_write_b128 v231, v[244:247]
	v_mfma_f32_16x16x32_bf16 v[68:71], v[132:135], v[140:143], v[68:71]
	ds_write_b128 v231, v[252:255] offset:4096
	v_mfma_f32_16x16x32_bf16 v[64:67], v[132:135], v[120:123], v[64:67]
	ds_write_b128 v231, v[208:211] offset:8192
	s_waitcnt lgkmcnt(6)
	v_mfma_f32_16x16x32_bf16 v[60:63], v[232:235], v[116:119], v[60:63]
	ds_write_b128 v231, v[212:215] offset:12288
	v_mfma_f32_16x16x32_bf16 v[56:59], v[232:235], v[128:131], v[56:59]
	ds_write_b128 v231, v[216:219] offset:16384
	v_mfma_f32_16x16x32_bf16 v[52:55], v[232:235], v[140:143], v[52:55]
	ds_write_b128 v231, v[220:223] offset:20480
	v_mfma_f32_16x16x32_bf16 v[48:51], v[232:235], v[120:123], v[48:51]
	s_add_i32 s9, s8, s5
	s_add_i32 s8, s8, 0x6000
	s_waitcnt lgkmcnt(8)
	v_mfma_f32_16x16x32_bf16 v[44:47], v[236:239], v[116:119], v[44:47]
	s_cmp_eq_u32 s8, 0x12000
	s_cselect_b32 s8, 0, s8
	v_mfma_f32_16x16x32_bf16 v[40:43], v[236:239], v[128:131], v[40:43]
	s_add_u32 s6, s6, 64
	s_addc_u32 s7, s7, 0
	s_cmpk_lg_i32 s6, 0xf80
	v_mfma_f32_16x16x32_bf16 v[36:39], v[236:239], v[140:143], v[36:39]
	v_mfma_f32_16x16x32_bf16 v[32:35], v[236:239], v[120:123], v[32:35]
	s_waitcnt lgkmcnt(7)
	v_mfma_f32_16x16x32_bf16 v[28:31], v[240:243], v[116:119], v[28:31]
	v_mfma_f32_16x16x32_bf16 v[24:27], v[240:243], v[128:131], v[24:27]
	v_mfma_f32_16x16x32_bf16 v[20:23], v[240:243], v[140:143], v[20:23]
	v_mfma_f32_16x16x32_bf16 v[16:19], v[240:243], v[120:123], v[16:19]
	s_waitcnt lgkmcnt(6)
	s_waitcnt lgkmcnt(0)
	s_barrier
	v_mfma_f32_16x16x32_bf16 v[12:15], v[168:171], v[116:119], v[12:15]
	v_mfma_f32_16x16x32_bf16 v[8:11], v[168:171], v[128:131], v[8:11]
	v_mfma_f32_16x16x32_bf16 v[4:7], v[168:171], v[140:143], v[4:7]
	v_mfma_f32_16x16x32_bf16 v[0:3], v[168:171], v[120:123], v[0:3]
	s_cbranch_scc1 .LBB0_198
	ds_read_b128 v[116:119], v166 offset:16384
	ds_read_b128 v[120:123], v166 offset:17408
	ds_read_b128 v[128:131], v166 offset:18432
	ds_read_b128 v[132:135], v166 offset:19456
	ds_read_b128 v[136:139], v156
	ds_read_b128 v[140:143], v156 offset:1024
	ds_read_b128 v[152:155], v156 offset:2048
	ds_read_b128 v[162:165], v156 offset:3072
	s_movk_i32 s5, 0x2200
	s_waitcnt lgkmcnt(3)
	v_mfma_f32_16x16x32_bf16 v[148:151], v[136:139], v[116:119], v[148:151]
	s_movk_i32 s8, 0x110
	v_mfma_f32_16x16x32_bf16 v[144:147], v[136:139], v[120:123], v[144:147]
	v_mfma_f32_16x16x32_bf16 v[124:127], v[136:139], v[128:131], v[124:127]
	v_mfma_f32_16x16x32_bf16 v[112:115], v[136:139], v[132:135], v[112:115]
	s_waitcnt lgkmcnt(2)
	v_mfma_f32_16x16x32_bf16 v[108:111], v[140:143], v[116:119], v[108:111]
	v_mfma_f32_16x16x32_bf16 v[104:107], v[140:143], v[120:123], v[104:107]
	v_mfma_f32_16x16x32_bf16 v[100:103], v[140:143], v[128:131], v[100:103]
	v_mfma_f32_16x16x32_bf16 v[96:99], v[140:143], v[132:135], v[96:99]
	s_waitcnt lgkmcnt(1)
	v_mfma_f32_16x16x32_bf16 v[92:95], v[152:155], v[116:119], v[92:95]
	v_mfma_f32_16x16x32_bf16 v[88:91], v[152:155], v[120:123], v[88:91]
	v_mfma_f32_16x16x32_bf16 v[84:87], v[152:155], v[128:131], v[84:87]
	v_mfma_f32_16x16x32_bf16 v[80:83], v[152:155], v[132:135], v[80:83]
	s_waitcnt lgkmcnt(0)
	v_mfma_f32_16x16x32_bf16 v[76:79], v[162:165], v[116:119], v[76:79]
	v_mfma_f32_16x16x32_bf16 v[72:75], v[162:165], v[120:123], v[72:75]
	v_mfma_f32_16x16x32_bf16 v[68:71], v[162:165], v[128:131], v[68:71]
	v_mfma_f32_16x16x32_bf16 v[64:67], v[162:165], v[132:135], v[64:67]
	ds_read_b128 v[136:139], v156 offset:4096
	ds_read_b128 v[140:143], v156 offset:5120
	ds_read_b128 v[152:155], v156 offset:6144
	ds_read_b128 v[162:165], v156 offset:7168
	s_waitcnt lgkmcnt(0)
	s_waitcnt vmcnt(0)
	s_barrier
	v_mfma_f32_16x16x32_bf16 v[60:63], v[136:139], v[116:119], v[60:63]
	v_mfma_f32_16x16x32_bf16 v[56:59], v[136:139], v[120:123], v[56:59]
	v_mfma_f32_16x16x32_bf16 v[52:55], v[136:139], v[128:131], v[52:55]
	v_mfma_f32_16x16x32_bf16 v[48:51], v[136:139], v[132:135], v[48:51]
	v_mfma_f32_16x16x32_bf16 v[44:47], v[140:143], v[116:119], v[44:47]
	v_mfma_f32_16x16x32_bf16 v[40:43], v[140:143], v[120:123], v[40:43]
	v_mfma_f32_16x16x32_bf16 v[36:39], v[140:143], v[128:131], v[36:39]
	v_mfma_f32_16x16x32_bf16 v[32:35], v[140:143], v[132:135], v[32:35]
	v_mfma_f32_16x16x32_bf16 v[28:31], v[152:155], v[116:119], v[28:31]
	v_mfma_f32_16x16x32_bf16 v[24:27], v[152:155], v[120:123], v[24:27]
	v_mfma_f32_16x16x32_bf16 v[20:23], v[152:155], v[128:131], v[20:23]
	v_mfma_f32_16x16x32_bf16 v[16:19], v[152:155], v[132:135], v[16:19]
	v_mfma_f32_16x16x32_bf16 v[12:15], v[162:165], v[116:119], v[12:15]
	v_mfma_f32_16x16x32_bf16 v[8:11], v[162:165], v[120:123], v[8:11]
	v_mfma_f32_16x16x32_bf16 v[4:7], v[162:165], v[128:131], v[4:7]
	v_mfma_f32_16x16x32_bf16 v[0:3], v[162:165], v[132:135], v[0:3]
	ds_read_b128 v[116:119], v166 offset:40960
	ds_read_b128 v[120:123], v166 offset:41984
	ds_read_b128 v[128:131], v166 offset:43008
	ds_read_b128 v[132:135], v166 offset:44032
	ds_read_b128 v[136:139], v156 offset:24576
	ds_read_b128 v[140:143], v156 offset:25600
	ds_read_b128 v[152:155], v156 offset:26624
	ds_read_b128 v[162:165], v156 offset:27648
	s_waitcnt lgkmcnt(3)
; DEV int TID() { int t = threadIdx.x; asm volatile("" : "+v"(t)); return t; }
; DEV f32x4 mfma16(bf16x8 a, bf16x8 b, f32x4 c) { return __builtin_amdgcn_mfma_f32_16x16x32_bf16(a, b, c, 0, 0, 0); }
; DEV void gemm_tile(const u16* __restrict__ A, size_t lda, const u16* __restrict__ Bt, size_t ldb, int K,
;                    u16* sA, u16* sB, f32x4 (&acc)[8][4]) {
;     ...
;         for (int mi = 0; mi < 4; ++mi) a[mi] = *(const bf16x8*)(pa + (mh * 64 + mi * 16) * 32);
; #pragma unroll
;         for (int mi = 0; mi < 4; ++mi)
; #pragma unroll
;           for (int ni = 0; ni < 4; ++ni) acc[mh * 4 + mi][ni] = mfma16(a[mi], b[ni], acc[mh * 4 + mi][ni]);
; DEV void store_tile_f32_add(const f32x4 (&acc)[8][4], const float* xres, float* out, int m0, int n0, unsigned char* smem) {
;   const int tid = TID(), lane = tid & 63, wid = tid >> 6;
;   const int wr = wid >> 1, wc = wid & 1, fr = lane & 15, fq = lane >> 4;
;   float* st = (float*)(smem + wid * 8704);
;   const int chunk = lane & 15;
; #pragma unroll
;   for (int mq = 0; mq < 4; ++mq) {
; #pragma unroll
;     for (int mh = 0; mh < 2; ++mh)
; #pragma unroll
;       for (int ni = 0; ni < 4; ++ni)
; #pragma unroll
;         for (int j = 0; j < 4; ++j) st[(mh * 16 + fq * 4 + j) * 68 + ni * 16 + fr] = acc[mq * 2 + mh][ni][j];
; #pragma unroll
;     for (int itr = 0; itr < 8; ++itr) {
;       const int rl = (lane >> 4) + 4 * itr;
;       const f32x4 v = *(const f32x4*)(st + rl * 68 + chunk * 4);
;       const size_t idx = (size_t)(m0 + wr * 128 + mq * 32 + rl) * 2048 + n0 + wc * 64 + chunk * 4;
;       const f32x4 x = *(const f32x4*)(xres + idx);
;       *(f32x4*)(out + idx) = x + v;
;     }
;   }
; }
	v_mfma_f32_16x16x32_bf16 v[148:151], v[136:139], v[116:119], v[148:151]
	v_mfma_f32_16x16x32_bf16 v[144:147], v[136:139], v[120:123], v[144:147]
	v_mfma_f32_16x16x32_bf16 v[124:127], v[136:139], v[128:131], v[124:127]
	v_mfma_f32_16x16x32_bf16 v[112:115], v[136:139], v[132:135], v[112:115]
	s_waitcnt lgkmcnt(2)
	v_mfma_f32_16x16x32_bf16 v[108:111], v[140:143], v[116:119], v[108:111]
	v_mfma_f32_16x16x32_bf16 v[104:107], v[140:143], v[120:123], v[104:107]
	v_mfma_f32_16x16x32_bf16 v[136:139], v[140:143], v[128:131], v[100:103]
	v_mfma_f32_16x16x32_bf16 v[96:99], v[140:143], v[132:135], v[96:99]
	s_waitcnt lgkmcnt(1)
	v_mfma_f32_16x16x32_bf16 v[92:95], v[152:155], v[116:119], v[92:95]
	v_mfma_f32_16x16x32_bf16 v[88:91], v[152:155], v[120:123], v[88:91]
	v_mfma_f32_16x16x32_bf16 v[84:87], v[152:155], v[128:131], v[84:87]
	v_mfma_f32_16x16x32_bf16 v[80:83], v[152:155], v[132:135], v[80:83]
	s_waitcnt lgkmcnt(0)
	v_mfma_f32_16x16x32_bf16 v[76:79], v[162:165], v[116:119], v[76:79]
	v_mfma_f32_16x16x32_bf16 v[72:75], v[162:165], v[120:123], v[72:75]
	v_mfma_f32_16x16x32_bf16 v[68:71], v[162:165], v[128:131], v[68:71]
	v_mfma_f32_16x16x32_bf16 v[64:67], v[162:165], v[132:135], v[64:67]
	ds_read_b128 v[100:103], v156 offset:28672
	ds_read_b128 v[140:143], v156 offset:29696
	ds_read_b128 v[152:155], v156 offset:30720
	ds_read_b128 v[162:165], v156 offset:31744
	s_waitcnt lgkmcnt(0)
	s_barrier
	v_mfma_f32_16x16x32_bf16 v[60:63], v[100:103], v[116:119], v[60:63]
	v_mfma_f32_16x16x32_bf16 v[56:59], v[100:103], v[120:123], v[56:59]
	v_mfma_f32_16x16x32_bf16 v[52:55], v[100:103], v[128:131], v[52:55]
	v_mfma_f32_16x16x32_bf16 v[48:51], v[100:103], v[132:135], v[48:51]
	v_mov_b32_e32 v102, v178
	s_nop 0
	v_lshrrev_b32_e32 v101, 6, v102
	v_and_b32_e32 v103, 15, v102
	v_mfma_f32_16x16x32_bf16 v[44:47], v[140:143], v[116:119], v[44:47]
	v_mul_lo_u32 v101, v101, s5
	v_bfe_u32 v100, v102, 4, 2
	v_mfma_f32_16x16x32_bf16 v[28:31], v[152:155], v[116:119], v[28:31]
	v_mfma_f32_16x16x32_bf16 v[12:15], v[162:165], v[116:119], v[12:15]
	v_lshlrev_b32_e32 v116, 2, v103
	v_or_b32_e32 v117, v101, v116
	v_and_b32_e32 v101, 0xffffff80, v102
	v_add_u32_e32 v101, s4, v101
	s_movk_i32 s4, 0x440
	v_mad_u32_u24 v118, v103, 12, v117
	v_and_or_b32 v116, v102, 64, v116
	v_mad_u32_u24 v103, v100, s4, v117
	v_readlane_b32 s4, v251, 7
	ds_write_b32 v103, v148
	ds_write_b32 v103, v149 offset:272
	ds_write_b32 v103, v150 offset:544
	ds_write_b32 v103, v151 offset:816
	ds_write_b32 v103, v144 offset:64
	ds_write_b32 v103, v145 offset:336
	ds_write_b32 v103, v146 offset:608
	ds_write_b32 v103, v147 offset:880
	ds_write_b32 v103, v124 offset:128
	ds_write_b32 v103, v125 offset:400
	ds_write_b32 v103, v126 offset:672
	ds_write_b32 v103, v127 offset:944
	ds_write_b32 v103, v112 offset:192
	ds_write_b32 v103, v113 offset:464
	ds_write_b32 v103, v114 offset:736
	ds_write_b32 v103, v115 offset:1008
	ds_write_b32 v103, v108 offset:4352
	ds_write_b32 v103, v109 offset:4624
	ds_write_b32 v103, v110 offset:4896
	ds_write_b32 v103, v111 offset:5168
	ds_write_b32 v103, v104 offset:4416
	ds_write_b32 v103, v105 offset:4688
	ds_write_b32 v103, v106 offset:4960
	ds_write_b32 v103, v107 offset:5232
	ds_write_b32 v103, v136 offset:4480
	ds_write_b32 v103, v137 offset:4752
	ds_write_b32 v103, v138 offset:5024
	ds_write_b32 v103, v139 offset:5296
	ds_write_b32 v103, v96 offset:4544
	ds_write_b32 v103, v97 offset:4816
	ds_write_b32 v103, v98 offset:5088
	ds_write_b32 v103, v99 offset:5360
	v_or_b32_e32 v98, v101, v100
	v_lshlrev_b32_e32 v156, 2, v116
	v_readlane_b32 s6, v251, 9
	v_readlane_b32 s7, v251, 10
	v_ashrrev_i32_e32 v99, 31, v98
	v_lshlrev_b64 v[98:99], 13, v[98:99]
	v_lshl_add_u64 v[96:97], s[6:7], 0, v[156:157]
	v_lshl_add_u64 v[96:97], s[2:3], 2, v[96:97]
	v_lshl_add_u64 v[98:99], v[96:97], 0, v[98:99]
	global_load_dwordx4 v[108:111], v[98:99], off
	v_mad_u32_u24 v102, v100, s8, v118
	ds_read_b128 v[104:107], v102
	v_mfma_f32_16x16x32_bf16 v[32:35], v[140:143], v[132:135], v[32:35]
	v_readlane_b32 s5, v251, 8
	s_waitcnt vmcnt(0) lgkmcnt(0)
	v_pk_add_f32 v[106:107], v[106:107], v[110:111]
	v_pk_add_f32 v[104:105], v[104:105], v[108:109]
	global_store_dwordx4 v[98:99], v[104:107], off
	v_or_b32_e32 v99, 4, v100
	v_or_b32_e32 v108, v99, v101
	v_ashrrev_i32_e32 v109, 31, v108
	v_lshlrev_b64 v[108:109], 13, v[108:109]
	v_lshl_add_u64 v[112:113], v[96:97], 0, v[108:109]
	global_load_dwordx4 v[108:111], v[112:113], off
	v_mad_u32_u24 v98, v99, s8, v118
	ds_read_b128 v[104:107], v98
	v_mfma_f32_16x16x32_bf16 v[40:43], v[140:143], v[120:123], v[40:43]
	s_waitcnt vmcnt(0) lgkmcnt(0)
	v_pk_add_f32 v[106:107], v[106:107], v[110:111]
	v_pk_add_f32 v[104:105], v[104:105], v[108:109]
	global_store_dwordx4 v[112:113], v[104:107], off
	ds_read_b128 v[106:109], v98 offset:1088
	v_mfma_f32_16x16x32_bf16 v[36:39], v[140:143], v[128:131], v[36:39]
	v_or_b32_e32 v104, 8, v100
	v_or_b32_e32 v110, v104, v101
	v_ashrrev_i32_e32 v111, 31, v110
	v_lshlrev_b64 v[110:111], 13, v[110:111]
	v_lshl_add_u64 v[114:115], v[96:97], 0, v[110:111]
	global_load_dwordx4 v[110:113], v[114:115], off
	v_or_b32_e32 v105, 12, v100
	v_mfma_f32_16x16x32_bf16 v[8:11], v[162:165], v[120:123], v[8:11]
	s_waitcnt vmcnt(0) lgkmcnt(0)
	v_pk_add_f32 v[106:107], v[106:107], v[110:111]
	v_or_b32_e32 v110, v105, v101
	v_ashrrev_i32_e32 v111, 31, v110
	v_pk_add_f32 v[108:109], v[108:109], v[112:113]
	v_lshlrev_b64 v[110:111], 13, v[110:111]
	global_store_dwordx4 v[114:115], v[106:109], off
	v_lshl_add_u64 v[114:115], v[96:97], 0, v[110:111]
	global_load_dwordx4 v[110:113], v[114:115], off
	ds_read_b128 v[106:109], v98 offset:2176
	v_mfma_f32_16x16x32_bf16 v[24:27], v[152:155], v[120:123], v[24:27]
	s_waitcnt vmcnt(0) lgkmcnt(0)
; DEV int TID() { int t = threadIdx.x; asm volatile("" : "+v"(t)); return t; }
; DEV void store_tile_f32_add(const f32x4 (&acc)[8][4], const float* xres, float* out, int m0, int n0, unsigned char* smem) {
;   const int tid = TID(), lane = tid & 63, wid = tid >> 6;
;   const int wr = wid >> 1, wc = wid & 1, fr = lane & 15, fq = lane >> 4;
;   float* st = (float*)(smem + wid * 8704);
;   const int chunk = lane & 15;
; #pragma unroll
;   for (int mq = 0; mq < 4; ++mq) {
; #pragma unroll
;     for (int mh = 0; mh < 2; ++mh)
; #pragma unroll
;       for (int ni = 0; ni < 4; ++ni)
; #pragma unroll
;         for (int j = 0; j < 4; ++j) st[(mh * 16 + fq * 4 + j) * 68 + ni * 16 + fr] = acc[mq * 2 + mh][ni][j];
; #pragma unroll
;     for (int itr = 0; itr < 8; ++itr) {
;       const int rl = (lane >> 4) + 4 * itr;
;       const f32x4 v = *(const f32x4*)(st + rl * 68 + chunk * 4);
;       const size_t idx = (size_t)(m0 + wr * 128 + mq * 32 + rl) * 2048 + n0 + wc * 64 + chunk * 4;
;       const f32x4 x = *(const f32x4*)(xres + idx);
;       *(f32x4*)(out + idx) = x + v;
;     }
;   }
; }
	v_pk_add_f32 v[108:109], v[108:109], v[112:113]
	v_pk_add_f32 v[106:107], v[106:107], v[110:111]
	global_store_dwordx4 v[114:115], v[106:109], off
	ds_read_b128 v[108:111], v98 offset:3264
	v_mfma_f32_16x16x32_bf16 v[20:23], v[152:155], v[128:131], v[20:23]
	v_or_b32_e32 v106, 16, v100
	v_or_b32_e32 v112, v106, v101
	v_ashrrev_i32_e32 v113, 31, v112
	v_lshlrev_b64 v[112:113], 13, v[112:113]
	v_lshl_add_u64 v[116:117], v[96:97], 0, v[112:113]
	global_load_dwordx4 v[112:115], v[116:117], off
	v_or_b32_e32 v107, 20, v100
	v_mfma_f32_16x16x32_bf16 v[16:19], v[152:155], v[132:135], v[16:19]
	s_waitcnt vmcnt(0) lgkmcnt(0)
	v_pk_add_f32 v[108:109], v[108:109], v[112:113]
	v_or_b32_e32 v112, v107, v101
	v_ashrrev_i32_e32 v113, 31, v112
	v_pk_add_f32 v[110:111], v[110:111], v[114:115]
	v_lshlrev_b64 v[112:113], 13, v[112:113]
	global_store_dwordx4 v[116:117], v[108:111], off
	v_lshl_add_u64 v[116:117], v[96:97], 0, v[112:113]
	global_load_dwordx4 v[112:115], v[116:117], off
	ds_read_b128 v[108:111], v98 offset:4352
	v_mfma_f32_16x16x32_bf16 v[4:7], v[162:165], v[128:131], v[4:7]
	s_waitcnt vmcnt(0) lgkmcnt(0)
	v_pk_add_f32 v[110:111], v[110:111], v[114:115]
	v_pk_add_f32 v[108:109], v[108:109], v[112:113]
	global_store_dwordx4 v[116:117], v[108:111], off
	ds_read_b128 v[110:113], v98 offset:5440
	v_mfma_f32_16x16x32_bf16 v[0:3], v[162:165], v[132:135], v[0:3]
	v_or_b32_e32 v108, 24, v100
	v_or_b32_e32 v114, v108, v101
	v_ashrrev_i32_e32 v115, 31, v114
	v_lshlrev_b64 v[114:115], 13, v[114:115]
	v_lshl_add_u64 v[118:119], v[96:97], 0, v[114:115]
	global_load_dwordx4 v[114:117], v[118:119], off
	v_or_b32_e32 v109, 28, v100
	s_waitcnt vmcnt(0) lgkmcnt(0)
	v_pk_add_f32 v[110:111], v[110:111], v[114:115]
	v_or_b32_e32 v114, v109, v101
	v_ashrrev_i32_e32 v115, 31, v114
	v_pk_add_f32 v[112:113], v[112:113], v[116:117]
	v_lshlrev_b64 v[114:115], 13, v[114:115]
	global_store_dwordx4 v[118:119], v[110:113], off
	v_lshl_add_u64 v[118:119], v[96:97], 0, v[114:115]
	global_load_dwordx4 v[114:117], v[118:119], off
	ds_read_b128 v[110:113], v98 offset:6528
	s_waitcnt vmcnt(0) lgkmcnt(0)
	v_pk_add_f32 v[112:113], v[112:113], v[116:117]
	v_pk_add_f32 v[110:111], v[110:111], v[114:115]
	global_store_dwordx4 v[118:119], v[110:113], off
	ds_write_b32 v103, v92
	ds_write_b32 v103, v93 offset:272
	ds_write_b32 v103, v94 offset:544
	ds_write_b32 v103, v95 offset:816
	ds_write_b32 v103, v88 offset:64
	ds_write_b32 v103, v89 offset:336
	ds_write_b32 v103, v90 offset:608
	ds_write_b32 v103, v91 offset:880
	ds_write_b32 v103, v84 offset:128
	ds_write_b32 v103, v85 offset:400
	ds_write_b32 v103, v86 offset:672
	ds_write_b32 v103, v87 offset:944
	ds_write_b32 v103, v80 offset:192
	ds_write_b32 v103, v81 offset:464
	ds_write_b32 v103, v82 offset:736
	ds_write_b32 v103, v83 offset:1008
	ds_write_b32 v103, v76 offset:4352
	ds_write_b32 v103, v77 offset:4624
	ds_write_b32 v103, v78 offset:4896
	ds_write_b32 v103, v79 offset:5168
	ds_write_b32 v103, v72 offset:4416
	ds_write_b32 v103, v73 offset:4688
	ds_write_b32 v103, v74 offset:4960
	ds_write_b32 v103, v75 offset:5232
	ds_write_b32 v103, v68 offset:4480
	ds_write_b32 v103, v69 offset:4752
	ds_write_b32 v103, v70 offset:5024
	ds_write_b32 v103, v71 offset:5296
	ds_write_b32 v103, v64 offset:4544
	ds_write_b32 v103, v65 offset:4816
	ds_write_b32 v103, v66 offset:5088
	ds_write_b32 v103, v67 offset:5360
	v_or_b32_e32 v64, 32, v101
	v_or_b32_e32 v70, v64, v100
	v_ashrrev_i32_e32 v71, 31, v70
	v_lshlrev_b64 v[70:71], 13, v[70:71]
	v_lshl_add_u64 v[74:75], v[96:97], 0, v[70:71]
	global_load_dwordx4 v[70:73], v[74:75], off
	ds_read_b128 v[66:69], v102
	s_waitcnt vmcnt(0) lgkmcnt(0)
	v_pk_add_f32 v[66:67], v[66:67], v[70:71]
	v_or_b32_e32 v70, v64, v99
	v_ashrrev_i32_e32 v71, 31, v70
	v_pk_add_f32 v[68:69], v[68:69], v[72:73]
	v_lshlrev_b64 v[70:71], 13, v[70:71]
	global_store_dwordx4 v[74:75], v[66:69], off
	v_lshl_add_u64 v[74:75], v[96:97], 0, v[70:71]
	global_load_dwordx4 v[70:73], v[74:75], off
	ds_read_b128 v[66:69], v98
	s_waitcnt vmcnt(0) lgkmcnt(0)
	v_pk_add_f32 v[66:67], v[66:67], v[70:71]
	v_or_b32_e32 v70, v64, v104
	v_ashrrev_i32_e32 v71, 31, v70
	v_pk_add_f32 v[68:69], v[68:69], v[72:73]
	v_lshlrev_b64 v[70:71], 13, v[70:71]
	global_store_dwordx4 v[74:75], v[66:69], off
	v_lshl_add_u64 v[74:75], v[96:97], 0, v[70:71]
	global_load_dwordx4 v[70:73], v[74:75], off
	ds_read_b128 v[66:69], v98 offset:1088
	s_waitcnt vmcnt(0) lgkmcnt(0)
	v_pk_add_f32 v[66:67], v[66:67], v[70:71]
	v_or_b32_e32 v70, v64, v105
	v_ashrrev_i32_e32 v71, 31, v70
	v_pk_add_f32 v[68:69], v[68:69], v[72:73]
	v_lshlrev_b64 v[70:71], 13, v[70:71]
	global_store_dwordx4 v[74:75], v[66:69], off
	v_lshl_add_u64 v[74:75], v[96:97], 0, v[70:71]
	global_load_dwordx4 v[70:73], v[74:75], off
	ds_read_b128 v[66:69], v98 offset:2176
	s_waitcnt vmcnt(0) lgkmcnt(0)
	v_pk_add_f32 v[66:67], v[66:67], v[70:71]
	v_or_b32_e32 v70, v64, v106
	v_ashrrev_i32_e32 v71, 31, v70
	v_pk_add_f32 v[68:69], v[68:69], v[72:73]
	v_lshlrev_b64 v[70:71], 13, v[70:71]
	global_store_dwordx4 v[74:75], v[66:69], off
	v_lshl_add_u64 v[74:75], v[96:97], 0, v[70:71]
	global_load_dwordx4 v[70:73], v[74:75], off
	ds_read_b128 v[66:69], v98 offset:3264
	s_waitcnt vmcnt(0) lgkmcnt(0)
	v_pk_add_f32 v[66:67], v[66:67], v[70:71]
	v_or_b32_e32 v70, v64, v107
	v_ashrrev_i32_e32 v71, 31, v70
	v_pk_add_f32 v[68:69], v[68:69], v[72:73]
	v_lshlrev_b64 v[70:71], 13, v[70:71]
	global_store_dwordx4 v[74:75], v[66:69], off
	v_lshl_add_u64 v[74:75], v[96:97], 0, v[70:71]
	global_load_dwordx4 v[70:73], v[74:75], off
	ds_read_b128 v[66:69], v98 offset:4352
	s_waitcnt vmcnt(0) lgkmcnt(0)
; DEV int TID() { int t = threadIdx.x; asm volatile("" : "+v"(t)); return t; }
; DEV void store_tile_f32_add(const f32x4 (&acc)[8][4], const float* xres, float* out, int m0, int n0, unsigned char* smem) {
;   const int tid = TID(), lane = tid & 63, wid = tid >> 6;
;   const int wr = wid >> 1, wc = wid & 1, fr = lane & 15, fq = lane >> 4;
;   float* st = (float*)(smem + wid * 8704);
;   const int chunk = lane & 15;
; #pragma unroll
;   for (int mq = 0; mq < 4; ++mq) {
; #pragma unroll
;     for (int mh = 0; mh < 2; ++mh)
; #pragma unroll
;       for (int ni = 0; ni < 4; ++ni)
; #pragma unroll
;         for (int j = 0; j < 4; ++j) st[(mh * 16 + fq * 4 + j) * 68 + ni * 16 + fr] = acc[mq * 2 + mh][ni][j];
; #pragma unroll
;     for (int itr = 0; itr < 8; ++itr) {
;       const int rl = (lane >> 4) + 4 * itr;
;       const f32x4 v = *(const f32x4*)(st + rl * 68 + chunk * 4);
;       const size_t idx = (size_t)(m0 + wr * 128 + mq * 32 + rl) * 2048 + n0 + wc * 64 + chunk * 4;
;       const f32x4 x = *(const f32x4*)(xres + idx);
;       *(f32x4*)(out + idx) = x + v;
;     }
;   }
; }
	v_pk_add_f32 v[66:67], v[66:67], v[70:71]
	v_or_b32_e32 v70, v64, v108
	v_ashrrev_i32_e32 v71, 31, v70
	v_pk_add_f32 v[68:69], v[68:69], v[72:73]
	v_lshlrev_b64 v[70:71], 13, v[70:71]
	global_store_dwordx4 v[74:75], v[66:69], off
	v_lshl_add_u64 v[74:75], v[96:97], 0, v[70:71]
	global_load_dwordx4 v[70:73], v[74:75], off
	ds_read_b128 v[66:69], v98 offset:5440
	v_or_b32_e32 v64, v64, v109
	v_ashrrev_i32_e32 v65, 31, v64
	v_lshlrev_b64 v[64:65], 13, v[64:65]
	v_lshl_add_u64 v[64:65], v[96:97], 0, v[64:65]
	s_waitcnt vmcnt(0) lgkmcnt(0)
	v_pk_add_f32 v[68:69], v[68:69], v[72:73]
	v_pk_add_f32 v[66:67], v[66:67], v[70:71]
	global_load_dwordx4 v[70:73], v[64:65], off
	s_nop 0
	global_store_dwordx4 v[74:75], v[66:69], off
	ds_read_b128 v[66:69], v98 offset:6528
	s_waitcnt vmcnt(1) lgkmcnt(0)
	v_pk_add_f32 v[68:69], v[68:69], v[72:73]
	v_pk_add_f32 v[66:67], v[66:67], v[70:71]
	global_store_dwordx4 v[64:65], v[66:69], off
	ds_write_b32 v103, v60
	ds_write_b32 v103, v61 offset:272
	ds_write_b32 v103, v62 offset:544
	ds_write_b32 v103, v63 offset:816
	ds_write_b32 v103, v56 offset:64
	ds_write_b32 v103, v57 offset:336
	ds_write_b32 v103, v58 offset:608
	ds_write_b32 v103, v59 offset:880
	ds_write_b32 v103, v52 offset:128
	ds_write_b32 v103, v53 offset:400
	ds_write_b32 v103, v54 offset:672
	ds_write_b32 v103, v55 offset:944
	ds_write_b32 v103, v48 offset:192
	ds_write_b32 v103, v49 offset:464
	ds_write_b32 v103, v50 offset:736
	ds_write_b32 v103, v51 offset:1008
	ds_write_b32 v103, v44 offset:4352
	ds_write_b32 v103, v45 offset:4624
	ds_write_b32 v103, v46 offset:4896
	ds_write_b32 v103, v47 offset:5168
	ds_write_b32 v103, v40 offset:4416
	ds_write_b32 v103, v41 offset:4688
	ds_write_b32 v103, v42 offset:4960
	ds_write_b32 v103, v43 offset:5232
	ds_write_b32 v103, v36 offset:4480
	ds_write_b32 v103, v37 offset:4752
	ds_write_b32 v103, v38 offset:5024
	ds_write_b32 v103, v39 offset:5296
	ds_write_b32 v103, v32 offset:4544
	ds_write_b32 v103, v33 offset:4816
	ds_write_b32 v103, v34 offset:5088
	ds_write_b32 v103, v35 offset:5360
	v_or_b32_e32 v32, 64, v101
	v_or_b32_e32 v38, v32, v100
	v_ashrrev_i32_e32 v39, 31, v38
	v_lshlrev_b64 v[38:39], 13, v[38:39]
	v_lshl_add_u64 v[42:43], v[96:97], 0, v[38:39]
	global_load_dwordx4 v[38:41], v[42:43], off
	ds_read_b128 v[34:37], v102
	s_waitcnt vmcnt(0) lgkmcnt(0)
	v_pk_add_f32 v[34:35], v[34:35], v[38:39]
	v_or_b32_e32 v38, v32, v99
	v_ashrrev_i32_e32 v39, 31, v38
	v_pk_add_f32 v[36:37], v[36:37], v[40:41]
	v_lshlrev_b64 v[38:39], 13, v[38:39]
	global_store_dwordx4 v[42:43], v[34:37], off
	v_lshl_add_u64 v[42:43], v[96:97], 0, v[38:39]
	global_load_dwordx4 v[38:41], v[42:43], off
	ds_read_b128 v[34:37], v98
	s_waitcnt vmcnt(0) lgkmcnt(0)
	v_pk_add_f32 v[34:35], v[34:35], v[38:39]
	v_or_b32_e32 v38, v32, v104
	v_ashrrev_i32_e32 v39, 31, v38
	v_pk_add_f32 v[36:37], v[36:37], v[40:41]
	v_lshlrev_b64 v[38:39], 13, v[38:39]
	global_store_dwordx4 v[42:43], v[34:37], off
	v_lshl_add_u64 v[42:43], v[96:97], 0, v[38:39]
	global_load_dwordx4 v[38:41], v[42:43], off
	ds_read_b128 v[34:37], v98 offset:1088
	s_waitcnt vmcnt(0) lgkmcnt(0)
	v_pk_add_f32 v[34:35], v[34:35], v[38:39]
	v_or_b32_e32 v38, v32, v105
	v_ashrrev_i32_e32 v39, 31, v38
	v_pk_add_f32 v[36:37], v[36:37], v[40:41]
	v_lshlrev_b64 v[38:39], 13, v[38:39]
	global_store_dwordx4 v[42:43], v[34:37], off
	v_lshl_add_u64 v[42:43], v[96:97], 0, v[38:39]
	global_load_dwordx4 v[38:41], v[42:43], off
	ds_read_b128 v[34:37], v98 offset:2176
	s_waitcnt vmcnt(0) lgkmcnt(0)
	v_pk_add_f32 v[34:35], v[34:35], v[38:39]
	v_or_b32_e32 v38, v32, v106
	v_ashrrev_i32_e32 v39, 31, v38
	v_pk_add_f32 v[36:37], v[36:37], v[40:41]
	v_lshlrev_b64 v[38:39], 13, v[38:39]
	global_store_dwordx4 v[42:43], v[34:37], off
	v_lshl_add_u64 v[42:43], v[96:97], 0, v[38:39]
	global_load_dwordx4 v[38:41], v[42:43], off
	ds_read_b128 v[34:37], v98 offset:3264
	s_waitcnt vmcnt(0) lgkmcnt(0)
	v_pk_add_f32 v[34:35], v[34:35], v[38:39]
	v_or_b32_e32 v38, v32, v107
	v_ashrrev_i32_e32 v39, 31, v38
	v_pk_add_f32 v[36:37], v[36:37], v[40:41]
	v_lshlrev_b64 v[38:39], 13, v[38:39]
	global_store_dwordx4 v[42:43], v[34:37], off
	v_lshl_add_u64 v[42:43], v[96:97], 0, v[38:39]
	global_load_dwordx4 v[38:41], v[42:43], off
	ds_read_b128 v[34:37], v98 offset:4352
	s_waitcnt vmcnt(0) lgkmcnt(0)
	v_pk_add_f32 v[34:35], v[34:35], v[38:39]
	v_or_b32_e32 v38, v32, v108
	v_ashrrev_i32_e32 v39, 31, v38
	v_pk_add_f32 v[36:37], v[36:37], v[40:41]
	v_lshlrev_b64 v[38:39], 13, v[38:39]
	global_store_dwordx4 v[42:43], v[34:37], off
	v_lshl_add_u64 v[42:43], v[96:97], 0, v[38:39]
	global_load_dwordx4 v[38:41], v[42:43], off
	ds_read_b128 v[34:37], v98 offset:5440
	v_or_b32_e32 v32, v32, v109
	v_ashrrev_i32_e32 v33, 31, v32
	v_lshlrev_b64 v[32:33], 13, v[32:33]
	v_lshl_add_u64 v[32:33], v[96:97], 0, v[32:33]
	s_waitcnt vmcnt(0) lgkmcnt(0)
; DEV int TID() { int t = threadIdx.x; asm volatile("" : "+v"(t)); return t; }
; DEV void store_tile_f32_add(const f32x4 (&acc)[8][4], const float* xres, float* out, int m0, int n0, unsigned char* smem) {
;   const int tid = TID(), lane = tid & 63, wid = tid >> 6;
;   const int wr = wid >> 1, wc = wid & 1, fr = lane & 15, fq = lane >> 4;
;   float* st = (float*)(smem + wid * 8704);
;   const int chunk = lane & 15;
; #pragma unroll
;   for (int mq = 0; mq < 4; ++mq) {
; #pragma unroll
;     for (int mh = 0; mh < 2; ++mh)
; #pragma unroll
;       for (int ni = 0; ni < 4; ++ni)
; #pragma unroll
;         for (int j = 0; j < 4; ++j) st[(mh * 16 + fq * 4 + j) * 68 + ni * 16 + fr] = acc[mq * 2 + mh][ni][j];
; #pragma unroll
;     for (int itr = 0; itr < 8; ++itr) {
;       const int rl = (lane >> 4) + 4 * itr;
;       const f32x4 v = *(const f32x4*)(st + rl * 68 + chunk * 4);
;       const size_t idx = (size_t)(m0 + wr * 128 + mq * 32 + rl) * 2048 + n0 + wc * 64 + chunk * 4;
;       const f32x4 x = *(const f32x4*)(xres + idx);
;       *(f32x4*)(out + idx) = x + v;
;     }
;   }
; }
; PHASE void gemm_down_phase(const u16* ACT, const u16* WTDN, int jc, float* out, unsigned char* smem) {
;     ...
;   for (int it = 0; it < nit; ++it) {
;     int mt, nt;
;     if (!tile_map(it, 16, mt, nt)) continue;
;     const int m0 = mt * 256, n0 = nt * 128;
;     f32x4 acc[8][4];
;     gemm_tile(ACT + (size_t)m0 * 2048, 2048, WTDN + (size_t)n0 * 6144 + (size_t)jc * 2048, 6144, 2048, sA, sB, acc);
;     store_tile_f32_add(acc, out, out, m0, n0, smem);
	v_pk_add_f32 v[36:37], v[36:37], v[40:41]
	v_pk_add_f32 v[34:35], v[34:35], v[38:39]
	global_load_dwordx4 v[38:41], v[32:33], off
	s_nop 0
	global_store_dwordx4 v[42:43], v[34:37], off
	ds_read_b128 v[34:37], v98 offset:6528
	s_waitcnt vmcnt(1) lgkmcnt(0)
	v_pk_add_f32 v[36:37], v[36:37], v[40:41]
	v_pk_add_f32 v[34:35], v[34:35], v[38:39]
	global_store_dwordx4 v[32:33], v[34:37], off
	ds_write_b32 v103, v28
	ds_write_b32 v103, v29 offset:272
	ds_write_b32 v103, v30 offset:544
	ds_write_b32 v103, v31 offset:816
	ds_write_b32 v103, v24 offset:64
	ds_write_b32 v103, v25 offset:336
	ds_write_b32 v103, v26 offset:608
	ds_write_b32 v103, v27 offset:880
	ds_write_b32 v103, v20 offset:128
	ds_write_b32 v103, v21 offset:400
	ds_write_b32 v103, v22 offset:672
	ds_write_b32 v103, v23 offset:944
	ds_write_b32 v103, v16 offset:192
	ds_write_b32 v103, v17 offset:464
	ds_write_b32 v103, v18 offset:736
	ds_write_b32 v103, v19 offset:1008
	ds_write_b32 v103, v12 offset:4352
	ds_write_b32 v103, v13 offset:4624
	ds_write_b32 v103, v14 offset:4896
	ds_write_b32 v103, v15 offset:5168
	ds_write_b32 v103, v8 offset:4416
	ds_write_b32 v103, v9 offset:4688
	ds_write_b32 v103, v10 offset:4960
	ds_write_b32 v103, v11 offset:5232
	ds_write_b32 v103, v4 offset:4480
	ds_write_b32 v103, v5 offset:4752
	ds_write_b32 v103, v6 offset:5024
	ds_write_b32 v103, v7 offset:5296
	ds_write_b32 v103, v0 offset:4544
	ds_write_b32 v103, v1 offset:4816
	ds_write_b32 v103, v2 offset:5088
	ds_write_b32 v103, v3 offset:5360
	v_or_b32_e32 v10, 0x60, v101
	v_or_b32_e32 v4, v10, v100
	v_ashrrev_i32_e32 v5, 31, v4
	v_lshlrev_b64 v[4:5], 13, v[4:5]
	v_lshl_add_u64 v[8:9], v[96:97], 0, v[4:5]
	global_load_dwordx4 v[4:7], v[8:9], off
	ds_read_b128 v[0:3], v102
	s_waitcnt vmcnt(0) lgkmcnt(0)
	v_pk_add_f32 v[0:1], v[0:1], v[4:5]
	v_or_b32_e32 v4, v10, v99
	v_ashrrev_i32_e32 v5, 31, v4
	v_pk_add_f32 v[2:3], v[2:3], v[6:7]
	v_lshlrev_b64 v[4:5], 13, v[4:5]
	global_store_dwordx4 v[8:9], v[0:3], off
	v_lshl_add_u64 v[8:9], v[96:97], 0, v[4:5]
	global_load_dwordx4 v[4:7], v[8:9], off
	ds_read_b128 v[0:3], v98
	s_waitcnt vmcnt(0) lgkmcnt(0)
	v_pk_add_f32 v[0:1], v[0:1], v[4:5]
	v_or_b32_e32 v4, v10, v104
	v_ashrrev_i32_e32 v5, 31, v4
	v_pk_add_f32 v[2:3], v[2:3], v[6:7]
	v_lshlrev_b64 v[4:5], 13, v[4:5]
	global_store_dwordx4 v[8:9], v[0:3], off
	v_lshl_add_u64 v[8:9], v[96:97], 0, v[4:5]
	global_load_dwordx4 v[4:7], v[8:9], off
	ds_read_b128 v[0:3], v98 offset:1088
	s_waitcnt vmcnt(0) lgkmcnt(0)
	v_pk_add_f32 v[0:1], v[0:1], v[4:5]
	v_or_b32_e32 v4, v10, v105
	v_ashrrev_i32_e32 v5, 31, v4
	v_pk_add_f32 v[2:3], v[2:3], v[6:7]
	v_lshlrev_b64 v[4:5], 13, v[4:5]
	global_store_dwordx4 v[8:9], v[0:3], off
	v_lshl_add_u64 v[8:9], v[96:97], 0, v[4:5]
	global_load_dwordx4 v[4:7], v[8:9], off
	ds_read_b128 v[0:3], v98 offset:2176
	s_waitcnt vmcnt(0) lgkmcnt(0)
	v_pk_add_f32 v[0:1], v[0:1], v[4:5]
	v_or_b32_e32 v4, v10, v106
	v_ashrrev_i32_e32 v5, 31, v4
	v_pk_add_f32 v[2:3], v[2:3], v[6:7]
	v_lshlrev_b64 v[4:5], 13, v[4:5]
	global_store_dwordx4 v[8:9], v[0:3], off
	v_lshl_add_u64 v[8:9], v[96:97], 0, v[4:5]
	global_load_dwordx4 v[4:7], v[8:9], off
	ds_read_b128 v[0:3], v98 offset:3264
	s_waitcnt vmcnt(0) lgkmcnt(0)
	v_pk_add_f32 v[0:1], v[0:1], v[4:5]
	v_or_b32_e32 v4, v10, v107
	v_ashrrev_i32_e32 v5, 31, v4
	v_pk_add_f32 v[2:3], v[2:3], v[6:7]
	v_lshlrev_b64 v[4:5], 13, v[4:5]
	global_store_dwordx4 v[8:9], v[0:3], off
	v_lshl_add_u64 v[8:9], v[96:97], 0, v[4:5]
	global_load_dwordx4 v[4:7], v[8:9], off
	ds_read_b128 v[0:3], v98 offset:4352
	s_waitcnt vmcnt(0) lgkmcnt(0)
	v_pk_add_f32 v[0:1], v[0:1], v[4:5]
	v_or_b32_e32 v4, v10, v108
	v_ashrrev_i32_e32 v5, 31, v4
	v_pk_add_f32 v[2:3], v[2:3], v[6:7]
	v_lshlrev_b64 v[4:5], 13, v[4:5]
	global_store_dwordx4 v[8:9], v[0:3], off
	v_lshl_add_u64 v[8:9], v[96:97], 0, v[4:5]
	global_load_dwordx4 v[4:7], v[8:9], off
	ds_read_b128 v[0:3], v98 offset:5440
	s_waitcnt vmcnt(0) lgkmcnt(0)
	v_pk_add_f32 v[0:1], v[0:1], v[4:5]
	v_or_b32_e32 v4, v10, v109
	v_ashrrev_i32_e32 v5, 31, v4
	v_pk_add_f32 v[2:3], v[2:3], v[6:7]
	v_lshlrev_b64 v[4:5], 13, v[4:5]
	global_store_dwordx4 v[8:9], v[0:3], off
	v_lshl_add_u64 v[8:9], v[96:97], 0, v[4:5]
	global_load_dwordx4 v[4:7], v[8:9], off
	ds_read_b128 v[0:3], v98 offset:6528
	s_waitcnt vmcnt(0) lgkmcnt(0)
	v_pk_add_f32 v[2:3], v[2:3], v[6:7]
	v_pk_add_f32 v[0:1], v[0:1], v[4:5]
	global_store_dwordx4 v[8:9], v[0:3], off
	s_branch .LBB0_191

; DEV f32x4 mfma16(bf16x8 a, bf16x8 b, f32x4 c) { return __builtin_amdgcn_mfma_f32_16x16x32_bf16(a, b, c, 0, 0, 0); }
; DEV void gemm_tile(const u16* __restrict__ A, size_t lda, const u16* __restrict__ Bt, size_t ldb, int K,
;                    u16* sA, u16* sB, f32x4 (&acc)[8][4]) {
;     ...
;   for (int kt = 0; kt < nk; ++kt) {
;     const int st = kt & 1;
;     if (kt + 1 < nk) S_STORE(st ^ 1)
;     if (kt + 2 < nk) G_LOAD((kt + 2) << 5)
;     {
;       const u16* pa = sAr + st * 12288;
;       const u16* pb = sBr + st * 12288;
;       bf16x8 b[4];
; #pragma unroll
;       for (int ni = 0; ni < 4; ++ni) b[ni] = *(const bf16x8*)(pb + ni * 16 * 32);
; #pragma unroll
;       for (int mh = 0; mh < 2; ++mh) {
;         bf16x8 a[4];
; #pragma unroll
;         for (int mi = 0; mi < 4; ++mi) a[mi] = *(const bf16x8*)(pa + (mh * 64 + mi * 16) * 32);
; #pragma unroll
;         for (int mi = 0; mi < 4; ++mi)
; #pragma unroll
;           for (int ni = 0; ni < 4; ++ni) acc[mh * 4 + mi][ni] = mfma16(a[mi], b[ni], acc[mh * 4 + mi][ni]);
;       }
;     }
;     __syncthreads();
.LBB0_226:
	v_add_u32_e32 v229, s8, v163
	v_add_u32_e32 v228, s8, v162
	ds_read_b128 v[120:123], v229 offset:16384
	ds_read_b128 v[166:169], v228
	ds_read_b128 v[128:131], v229 offset:17408
	ds_read_b128 v[140:143], v229 offset:18432
	ds_read_b128 v[124:127], v229 offset:19456
	ds_read_b128 v[152:155], v228 offset:1024
	ds_read_b128 v[170:173], v228 offset:2048
	ds_read_b128 v[132:135], v228 offset:3072
	s_waitcnt lgkmcnt(6)
	v_mfma_f32_16x16x32_bf16 v[148:151], v[166:169], v[120:123], v[148:151]
	s_waitcnt lgkmcnt(5)
	v_mfma_f32_16x16x32_bf16 v[144:147], v[166:169], v[128:131], v[144:147]
	s_waitcnt lgkmcnt(4)
	v_mfma_f32_16x16x32_bf16 v[116:119], v[166:169], v[140:143], v[116:119]
	s_waitcnt lgkmcnt(3)
	v_mfma_f32_16x16x32_bf16 v[112:115], v[166:169], v[124:127], v[112:115]
	ds_read_b128 v[232:235], v228 offset:4096
	ds_read_b128 v[236:239], v228 offset:5120
	s_waitcnt lgkmcnt(4)
	v_mfma_f32_16x16x32_bf16 v[108:111], v[152:155], v[120:123], v[108:111]
	s_add_i32 m0, s9, 0x0
	v_mfma_f32_16x16x32_bf16 v[104:107], v[152:155], v[128:131], v[104:107]
	global_load_lds_dwordx4 v[136:137], off
	v_lshl_add_u64 v[136:137], v[136:137], 0, 64
	global_load_dwordx4 v[244:247], v[136:137], off
	v_lshl_add_u64 v[136:137], v[136:137], 0, 64
	v_mfma_f32_16x16x32_bf16 v[100:103], v[152:155], v[140:143], v[100:103]
	s_add_i32 m0, s9, 0x1000
	v_mfma_f32_16x16x32_bf16 v[96:99], v[152:155], v[124:127], v[96:99]
	global_load_lds_dwordx4 v[138:139], off
	v_lshl_add_u64 v[138:139], v[138:139], 0, 64
	global_load_dwordx4 v[252:255], v[138:139], off
	v_lshl_add_u64 v[138:139], v[138:139], 0, 64
	s_waitcnt lgkmcnt(3)
	v_mfma_f32_16x16x32_bf16 v[92:95], v[170:173], v[120:123], v[92:95]
	s_add_i32 m0, s9, 0x2000
	v_mfma_f32_16x16x32_bf16 v[88:91], v[170:173], v[128:131], v[88:91]
	global_load_lds_dwordx4 v[174:175], off
	v_lshl_add_u64 v[174:175], v[174:175], 0, 64
	global_load_dwordx4 v[208:211], v[174:175], off
	v_lshl_add_u64 v[174:175], v[174:175], 0, 64
	v_mfma_f32_16x16x32_bf16 v[84:87], v[170:173], v[140:143], v[84:87]
	s_add_i32 m0, s9, 0x3000
	v_mfma_f32_16x16x32_bf16 v[80:83], v[170:173], v[124:127], v[80:83]
	ds_read_b128 v[240:243], v228 offset:6144
	ds_read_b128 v[166:169], v228 offset:7168
	s_waitcnt lgkmcnt(4)
	v_mfma_f32_16x16x32_bf16 v[76:79], v[132:135], v[120:123], v[76:79]
	global_load_lds_dwordx4 v[176:177], off
	v_lshl_add_u64 v[176:177], v[176:177], 0, 64
	global_load_dwordx4 v[212:215], v[176:177], off
	v_lshl_add_u64 v[176:177], v[176:177], 0, 64
	v_mfma_f32_16x16x32_bf16 v[72:75], v[132:135], v[128:131], v[72:75]
	s_add_i32 m0, s9, 0x4000
	v_mfma_f32_16x16x32_bf16 v[68:71], v[132:135], v[140:143], v[68:71]
	global_load_lds_dwordx4 v[186:187], off
	v_lshl_add_u64 v[186:187], v[186:187], 0, 64
	global_load_dwordx4 v[216:219], v[186:187], off
	v_lshl_add_u64 v[186:187], v[186:187], 0, 64
	v_mfma_f32_16x16x32_bf16 v[64:67], v[132:135], v[124:127], v[64:67]
	s_add_i32 m0, s9, 0x5000
	s_waitcnt lgkmcnt(3)
	v_mfma_f32_16x16x32_bf16 v[60:63], v[232:235], v[120:123], v[60:63]
	global_load_lds_dwordx4 v[188:189], off
	v_lshl_add_u64 v[188:189], v[188:189], 0, 64
	global_load_dwordx4 v[220:223], v[188:189], off
	v_lshl_add_u64 v[188:189], v[188:189], 0, 64
	v_mfma_f32_16x16x32_bf16 v[56:59], v[232:235], v[128:131], v[56:59]
	s_add_i32 s9, s8, s5
	s_add_i32 s8, s8, 0x6000
	v_mfma_f32_16x16x32_bf16 v[52:55], v[232:235], v[140:143], v[52:55]
	s_cmp_eq_u32 s8, 0x12000
	s_cselect_b32 s8, 0, s8
	v_mfma_f32_16x16x32_bf16 v[48:51], v[232:235], v[124:127], v[48:51]
	s_add_u32 s6, s6, 64
	s_addc_u32 s7, s7, 0
	s_cmpk_lg_i32 s6, 0xf80
	s_waitcnt lgkmcnt(2)
	v_mfma_f32_16x16x32_bf16 v[44:47], v[236:239], v[120:123], v[44:47]
	v_mfma_f32_16x16x32_bf16 v[40:43], v[236:239], v[128:131], v[40:43]
	v_mfma_f32_16x16x32_bf16 v[36:39], v[236:239], v[140:143], v[36:39]
	v_mfma_f32_16x16x32_bf16 v[32:35], v[236:239], v[124:127], v[32:35]
	s_waitcnt lgkmcnt(1)
	v_mfma_f32_16x16x32_bf16 v[28:31], v[240:243], v[120:123], v[28:31]
	v_mfma_f32_16x16x32_bf16 v[24:27], v[240:243], v[128:131], v[24:27]
	v_mfma_f32_16x16x32_bf16 v[20:23], v[240:243], v[140:143], v[20:23]
	v_mfma_f32_16x16x32_bf16 v[16:19], v[240:243], v[124:127], v[16:19]
	s_waitcnt lgkmcnt(0)
	s_waitcnt vmcnt(12)
	s_barrier
	v_mfma_f32_16x16x32_bf16 v[12:15], v[166:169], v[120:123], v[12:15]
	v_mfma_f32_16x16x32_bf16 v[8:11], v[166:169], v[128:131], v[8:11]
	v_mfma_f32_16x16x32_bf16 v[4:7], v[166:169], v[140:143], v[4:7]
	v_mfma_f32_16x16x32_bf16 v[0:3], v[166:169], v[124:127], v[0:3]
	v_add_u32_e32 v229, s8, v163
	v_add_u32_e32 v228, s8, v162
	ds_read_b128 v[120:123], v229 offset:16384
	ds_read_b128 v[166:169], v228
	ds_read_b128 v[128:131], v229 offset:17408
	ds_read_b128 v[140:143], v229 offset:18432
	ds_read_b128 v[124:127], v229 offset:19456
	ds_read_b128 v[152:155], v228 offset:1024
	ds_read_b128 v[170:173], v228 offset:2048
	ds_read_b128 v[132:135], v228 offset:3072
	s_waitcnt lgkmcnt(6)
	v_mfma_f32_16x16x32_bf16 v[148:151], v[166:169], v[120:123], v[148:151]
	s_waitcnt lgkmcnt(5)
	v_mfma_f32_16x16x32_bf16 v[144:147], v[166:169], v[128:131], v[144:147]
	s_waitcnt lgkmcnt(4)
	v_mfma_f32_16x16x32_bf16 v[116:119], v[166:169], v[140:143], v[116:119]
	s_waitcnt lgkmcnt(3)
	v_mfma_f32_16x16x32_bf16 v[112:115], v[166:169], v[124:127], v[112:115]
	ds_read_b128 v[232:235], v228 offset:4096
	ds_read_b128 v[236:239], v228 offset:5120
	s_waitcnt lgkmcnt(4)
	v_mfma_f32_16x16x32_bf16 v[108:111], v[152:155], v[120:123], v[108:111]
	v_mfma_f32_16x16x32_bf16 v[104:107], v[152:155], v[128:131], v[104:107]
	v_mfma_f32_16x16x32_bf16 v[100:103], v[152:155], v[140:143], v[100:103]
	v_mfma_f32_16x16x32_bf16 v[96:99], v[152:155], v[124:127], v[96:99]
	s_waitcnt lgkmcnt(3)
; DEV f32x4 mfma16(bf16x8 a, bf16x8 b, f32x4 c) { return __builtin_amdgcn_mfma_f32_16x16x32_bf16(a, b, c, 0, 0, 0); }
; DEV void gemm_tile(const u16* __restrict__ A, size_t lda, const u16* __restrict__ Bt, size_t ldb, int K,
;                    u16* sA, u16* sB, f32x4 (&acc)[8][4]) {
;     ...
;   for (int kt = 0; kt < nk; ++kt) {
;     const int st = kt & 1;
;     if (kt + 1 < nk) S_STORE(st ^ 1)
;     if (kt + 2 < nk) G_LOAD((kt + 2) << 5)
;     {
;       const u16* pa = sAr + st * 12288;
;       const u16* pb = sBr + st * 12288;
;       bf16x8 b[4];
; #pragma unroll
;       for (int ni = 0; ni < 4; ++ni) b[ni] = *(const bf16x8*)(pb + ni * 16 * 32);
; #pragma unroll
;       for (int mh = 0; mh < 2; ++mh) {
;         bf16x8 a[4];
; #pragma unroll
;         for (int mi = 0; mi < 4; ++mi) a[mi] = *(const bf16x8*)(pa + (mh * 64 + mi * 16) * 32);
; #pragma unroll
;         for (int mi = 0; mi < 4; ++mi)
; #pragma unroll
;           for (int ni = 0; ni < 4; ++ni) acc[mh * 4 + mi][ni] = mfma16(a[mi], b[ni], acc[mh * 4 + mi][ni]);
;       }
;     }
;     __syncthreads();
	v_mfma_f32_16x16x32_bf16 v[92:95], v[170:173], v[120:123], v[92:95]
	v_mfma_f32_16x16x32_bf16 v[88:91], v[170:173], v[128:131], v[88:91]
	v_mfma_f32_16x16x32_bf16 v[84:87], v[170:173], v[140:143], v[84:87]
	v_mfma_f32_16x16x32_bf16 v[80:83], v[170:173], v[124:127], v[80:83]
	ds_read_b128 v[240:243], v228 offset:6144
	ds_read_b128 v[166:169], v228 offset:7168
	s_waitcnt lgkmcnt(4)
	v_mfma_f32_16x16x32_bf16 v[76:79], v[132:135], v[120:123], v[76:79]
	s_waitcnt vmcnt(0)
	v_add_u32_e32 v231, s9, v230
	v_mfma_f32_16x16x32_bf16 v[72:75], v[132:135], v[128:131], v[72:75]
	ds_write_b128 v231, v[244:247]
	v_mfma_f32_16x16x32_bf16 v[68:71], v[132:135], v[140:143], v[68:71]
	ds_write_b128 v231, v[252:255] offset:4096
	v_mfma_f32_16x16x32_bf16 v[64:67], v[132:135], v[124:127], v[64:67]
	ds_write_b128 v231, v[208:211] offset:8192
	s_waitcnt lgkmcnt(6)
	v_mfma_f32_16x16x32_bf16 v[60:63], v[232:235], v[120:123], v[60:63]
	ds_write_b128 v231, v[212:215] offset:12288
	v_mfma_f32_16x16x32_bf16 v[56:59], v[232:235], v[128:131], v[56:59]
	ds_write_b128 v231, v[216:219] offset:16384
	v_mfma_f32_16x16x32_bf16 v[52:55], v[232:235], v[140:143], v[52:55]
	ds_write_b128 v231, v[220:223] offset:20480
	v_mfma_f32_16x16x32_bf16 v[48:51], v[232:235], v[124:127], v[48:51]
	s_add_i32 s9, s8, s5
	s_add_i32 s8, s8, 0x6000
	s_waitcnt lgkmcnt(8)
	v_mfma_f32_16x16x32_bf16 v[44:47], v[236:239], v[120:123], v[44:47]
	s_cmp_eq_u32 s8, 0x12000
	s_cselect_b32 s8, 0, s8
	v_mfma_f32_16x16x32_bf16 v[40:43], v[236:239], v[128:131], v[40:43]
	s_add_u32 s6, s6, 64
	s_addc_u32 s7, s7, 0
	s_cmpk_lg_i32 s6, 0xf80
	v_mfma_f32_16x16x32_bf16 v[36:39], v[236:239], v[140:143], v[36:39]
	v_mfma_f32_16x16x32_bf16 v[32:35], v[236:239], v[124:127], v[32:35]
	s_waitcnt lgkmcnt(7)
	v_mfma_f32_16x16x32_bf16 v[28:31], v[240:243], v[120:123], v[28:31]
	v_mfma_f32_16x16x32_bf16 v[24:27], v[240:243], v[128:131], v[24:27]
	v_mfma_f32_16x16x32_bf16 v[20:23], v[240:243], v[140:143], v[20:23]
	v_mfma_f32_16x16x32_bf16 v[16:19], v[240:243], v[124:127], v[16:19]
	s_waitcnt lgkmcnt(6)
	s_waitcnt lgkmcnt(0)
	s_barrier
	v_mfma_f32_16x16x32_bf16 v[12:15], v[166:169], v[120:123], v[12:15]
	v_mfma_f32_16x16x32_bf16 v[8:11], v[166:169], v[128:131], v[8:11]
	v_mfma_f32_16x16x32_bf16 v[4:7], v[166:169], v[140:143], v[4:7]
	v_mfma_f32_16x16x32_bf16 v[0:3], v[166:169], v[124:127], v[0:3]
	s_cbranch_scc1 .LBB0_226
	ds_read_b128 v[120:123], v163 offset:16384
	ds_read_b128 v[124:127], v163 offset:17408
	ds_read_b128 v[128:131], v163 offset:18432
	ds_read_b128 v[132:135], v163 offset:19456
	ds_read_b128 v[136:139], v162
	ds_read_b128 v[140:143], v162 offset:1024
	ds_read_b128 v[152:155], v162 offset:2048
	ds_read_b128 v[158:161], v162 offset:3072
	s_waitcnt lgkmcnt(3)
	v_mfma_f32_16x16x32_bf16 v[148:151], v[136:139], v[120:123], v[148:151]
	v_mfma_f32_16x16x32_bf16 v[144:147], v[136:139], v[124:127], v[144:147]
	v_mfma_f32_16x16x32_bf16 v[116:119], v[136:139], v[128:131], v[116:119]
	v_mfma_f32_16x16x32_bf16 v[112:115], v[136:139], v[132:135], v[112:115]
	s_waitcnt lgkmcnt(2)
	v_mfma_f32_16x16x32_bf16 v[108:111], v[140:143], v[120:123], v[108:111]
	v_mfma_f32_16x16x32_bf16 v[104:107], v[140:143], v[124:127], v[104:107]
	v_mfma_f32_16x16x32_bf16 v[100:103], v[140:143], v[128:131], v[100:103]
	v_mfma_f32_16x16x32_bf16 v[96:99], v[140:143], v[132:135], v[96:99]
	s_waitcnt lgkmcnt(1)
	v_mfma_f32_16x16x32_bf16 v[92:95], v[152:155], v[120:123], v[92:95]
	v_mfma_f32_16x16x32_bf16 v[88:91], v[152:155], v[124:127], v[88:91]
	v_mfma_f32_16x16x32_bf16 v[84:87], v[152:155], v[128:131], v[84:87]
	v_mfma_f32_16x16x32_bf16 v[80:83], v[152:155], v[132:135], v[80:83]
	s_waitcnt lgkmcnt(0)
	v_mfma_f32_16x16x32_bf16 v[76:79], v[158:161], v[120:123], v[76:79]
	v_mfma_f32_16x16x32_bf16 v[72:75], v[158:161], v[124:127], v[72:75]
	v_mfma_f32_16x16x32_bf16 v[68:71], v[158:161], v[128:131], v[68:71]
	v_mfma_f32_16x16x32_bf16 v[64:67], v[158:161], v[132:135], v[64:67]
	ds_read_b128 v[136:139], v162 offset:4096
	ds_read_b128 v[140:143], v162 offset:5120
	ds_read_b128 v[152:155], v162 offset:6144
	ds_read_b128 v[158:161], v162 offset:7168
	s_waitcnt lgkmcnt(0)
	s_waitcnt vmcnt(0)
	s_barrier
	v_mfma_f32_16x16x32_bf16 v[60:63], v[136:139], v[120:123], v[60:63]
	v_mfma_f32_16x16x32_bf16 v[56:59], v[136:139], v[124:127], v[56:59]
	v_mfma_f32_16x16x32_bf16 v[52:55], v[136:139], v[128:131], v[52:55]
	v_mfma_f32_16x16x32_bf16 v[48:51], v[136:139], v[132:135], v[48:51]
	v_mfma_f32_16x16x32_bf16 v[44:47], v[140:143], v[120:123], v[44:47]
	v_mfma_f32_16x16x32_bf16 v[40:43], v[140:143], v[124:127], v[40:43]
	v_mfma_f32_16x16x32_bf16 v[36:39], v[140:143], v[128:131], v[36:39]
	v_mfma_f32_16x16x32_bf16 v[32:35], v[140:143], v[132:135], v[32:35]
	v_mfma_f32_16x16x32_bf16 v[28:31], v[152:155], v[120:123], v[28:31]
	v_mfma_f32_16x16x32_bf16 v[24:27], v[152:155], v[124:127], v[24:27]
	v_mfma_f32_16x16x32_bf16 v[20:23], v[152:155], v[128:131], v[20:23]
	v_mfma_f32_16x16x32_bf16 v[16:19], v[152:155], v[132:135], v[16:19]
	v_mfma_f32_16x16x32_bf16 v[12:15], v[158:161], v[120:123], v[12:15]
	v_mfma_f32_16x16x32_bf16 v[8:11], v[158:161], v[124:127], v[8:11]
	v_mfma_f32_16x16x32_bf16 v[4:7], v[158:161], v[128:131], v[4:7]
	v_mfma_f32_16x16x32_bf16 v[0:3], v[158:161], v[132:135], v[0:3]
	ds_read_b128 v[128:131], v163 offset:40960
	ds_read_b128 v[132:135], v163 offset:41984
	ds_read_b128 v[136:139], v163 offset:43008
	ds_read_b128 v[140:143], v163 offset:44032
	ds_read_b128 v[152:155], v162 offset:24576
	ds_read_b128 v[158:161], v162 offset:25600
	ds_read_b128 v[164:167], v162 offset:26624
	ds_read_b128 v[168:171], v162 offset:27648
	s_waitcnt lgkmcnt(3)
	v_mfma_f32_16x16x32_bf16 v[124:127], v[152:155], v[128:131], v[148:151]
	v_mfma_f32_16x16x32_bf16 v[120:123], v[152:155], v[132:135], v[144:147]
	v_mfma_f32_16x16x32_bf16 v[116:119], v[152:155], v[136:139], v[116:119]
	v_mfma_f32_16x16x32_bf16 v[112:115], v[152:155], v[140:143], v[112:115]
	s_waitcnt lgkmcnt(2)
	v_mfma_f32_16x16x32_bf16 v[108:111], v[158:161], v[128:131], v[108:111]
	v_mfma_f32_16x16x32_bf16 v[104:107], v[158:161], v[132:135], v[104:107]
	v_mfma_f32_16x16x32_bf16 v[100:103], v[158:161], v[136:139], v[100:103]
	v_mfma_f32_16x16x32_bf16 v[96:99], v[158:161], v[140:143], v[96:99]
	ds_read_b128 v[144:147], v162 offset:28672
	ds_read_b128 v[148:151], v162 offset:29696
	ds_read_b128 v[152:155], v162 offset:30720
	ds_read_b128 v[158:161], v162 offset:31744
	s_waitcnt lgkmcnt(0)
	s_barrier
; DEV f32x4 mfma16(bf16x8 a, bf16x8 b, f32x4 c) { return __builtin_amdgcn_mfma_f32_16x16x32_bf16(a, b, c, 0, 0, 0); }
; DEV void gemm_tile(const u16* __restrict__ A, size_t lda, const u16* __restrict__ Bt, size_t ldb, int K,
;                    u16* sA, u16* sB, f32x4 (&acc)[8][4]) {
;     ...
;       for (int ni = 0; ni < 4; ++ni) b[ni] = *(const bf16x8*)(pb + ni * 16 * 32);
; #pragma unroll
;       for (int mh = 0; mh < 2; ++mh) {
;         bf16x8 a[4];
; #pragma unroll
;         for (int mi = 0; mi < 4; ++mi) a[mi] = *(const bf16x8*)(pa + (mh * 64 + mi * 16) * 32);
; #pragma unroll
;         for (int mi = 0; mi < 4; ++mi)
; #pragma unroll
;           for (int ni = 0; ni < 4; ++ni) acc[mh * 4 + mi][ni] = mfma16(a[mi], b[ni], acc[mh * 4 + mi][ni]);
; DEV void store_tile_bf16(const f32x4 (&acc)[8][4], u16* __restrict__ OUT, size_t ld, int m0, int n0, int ncols,
;                          unsigned char* smem) {
;     ...
; #pragma unroll
;   for (int mh = 0; mh < 2; ++mh) {
; #pragma unroll
;     for (int mi = 0; mi < 4; ++mi)
; #pragma unroll
;       for (int ni = 0; ni < 4; ++ni)
; #pragma unroll
;         for (int j = 0; j < 4; ++j) st[(mi * 16 + fq * 4 + j) * 72 + ni * 16 + fr] = f2bf(acc[mh * 4 + mi][ni][j]);
	v_mfma_f32_16x16x32_bf16 v[92:95], v[164:167], v[128:131], v[92:95]
	v_mfma_f32_16x16x32_bf16 v[76:79], v[168:171], v[128:131], v[76:79]
	v_mfma_f32_16x16x32_bf16 v[60:63], v[144:147], v[128:131], v[60:63]
	v_mfma_f32_16x16x32_bf16 v[44:47], v[148:151], v[128:131], v[44:47]
	v_mfma_f32_16x16x32_bf16 v[28:31], v[152:155], v[128:131], v[28:31]
	v_mfma_f32_16x16x32_bf16 v[12:15], v[158:161], v[128:131], v[12:15]
	v_mov_b32_e32 v129, v178
	s_nop 0
	v_lshrrev_b32_e32 v128, 6, v129
	v_mfma_f32_16x16x32_bf16 v[88:91], v[164:167], v[132:135], v[88:91]
	v_mul_lo_u32 v131, v128, s75
	v_lshrrev_b32_e32 v128, 2, v129
	v_and_b32_e32 v130, 15, v129
	v_mfma_f32_16x16x32_bf16 v[72:75], v[168:171], v[132:135], v[72:75]
	v_lshl_or_b32 v130, v130, 1, v131
	v_mfma_f32_16x16x32_bf16 v[56:59], v[144:147], v[132:135], v[56:59]
	v_mfma_f32_16x16x32_bf16 v[40:43], v[148:151], v[132:135], v[40:43]
	v_mfma_f32_16x16x32_bf16 v[24:27], v[152:155], v[132:135], v[24:27]
	v_mfma_f32_16x16x32_bf16 v[8:11], v[158:161], v[132:135], v[8:11]
	v_lshlrev_b32_e32 v133, 3, v129
	v_and_b32_e32 v132, 12, v128
	v_and_b32_e32 v128, 64, v129
	v_and_b32_e32 v133, 56, v133
	v_or3_b32 v128, v128, s18, v133
	v_lshl_or_b32 v131, v133, 1, v131
	v_bfe_u32 v133, v129, 3, 3
	v_and_b32_e32 v129, 0xffffff80, v129
	v_add_u32_e32 v134, s4, v129
	v_bfe_u32 v135, v124, 16, 1
	s_movk_i32 s4, 0x90
	v_add3_u32 v135, v124, v135, s71
	v_mad_u32_u24 v124, v132, s4, v130
	v_bfe_u32 v130, v125, 16, 1
	v_add3_u32 v125, v125, v130, s71
	ds_write_b16_d16_hi v124, v125 offset:144
	v_bfe_u32 v125, v126, 16, 1
	v_add3_u32 v125, v126, v125, s71
	ds_write_b16_d16_hi v124, v125 offset:288
	v_bfe_u32 v125, v127, 16, 1
	v_add3_u32 v125, v127, v125, s71
	ds_write_b16_d16_hi v124, v125 offset:432
	v_bfe_u32 v125, v120, 16, 1
	v_add3_u32 v120, v120, v125, s71
	ds_write_b16_d16_hi v124, v120 offset:32
	v_bfe_u32 v120, v121, 16, 1
	v_add3_u32 v120, v121, v120, s71
	ds_write_b16_d16_hi v124, v120 offset:176
	v_bfe_u32 v120, v122, 16, 1
	v_add3_u32 v120, v122, v120, s71
	ds_write_b16_d16_hi v124, v120 offset:320
	v_bfe_u32 v120, v123, 16, 1
	v_add3_u32 v120, v123, v120, s71
	ds_write_b16_d16_hi v124, v120 offset:464
	v_bfe_u32 v120, v116, 16, 1
	v_add3_u32 v116, v116, v120, s71
	ds_write_b16_d16_hi v124, v116 offset:64
	v_bfe_u32 v116, v117, 16, 1
	v_add3_u32 v116, v117, v116, s71
	ds_write_b16_d16_hi v124, v116 offset:208
	v_bfe_u32 v116, v118, 16, 1
	v_add3_u32 v116, v118, v116, s71
	ds_write_b16_d16_hi v124, v116 offset:352
	v_bfe_u32 v116, v119, 16, 1
	v_add3_u32 v116, v119, v116, s71
	ds_write_b16_d16_hi v124, v116 offset:496
	v_bfe_u32 v116, v112, 16, 1
	v_add3_u32 v112, v112, v116, s71
	ds_write_b16_d16_hi v124, v112 offset:96
	v_bfe_u32 v112, v113, 16, 1
	v_add3_u32 v112, v113, v112, s71
	ds_write_b16_d16_hi v124, v112 offset:240
	v_bfe_u32 v112, v114, 16, 1
	v_add3_u32 v112, v114, v112, s71
	ds_write_b16_d16_hi v124, v112 offset:384
	v_bfe_u32 v112, v115, 16, 1
	v_add3_u32 v112, v115, v112, s71
	ds_write_b16_d16_hi v124, v112 offset:528
	v_bfe_u32 v112, v108, 16, 1
	v_add3_u32 v108, v108, v112, s71
	ds_write_b16_d16_hi v124, v108 offset:2304
	v_bfe_u32 v108, v109, 16, 1
	v_add3_u32 v108, v109, v108, s71
	ds_write_b16_d16_hi v124, v108 offset:2448
	v_bfe_u32 v108, v110, 16, 1
	v_add3_u32 v108, v110, v108, s71
	ds_write_b16_d16_hi v124, v108 offset:2592
	v_bfe_u32 v108, v111, 16, 1
	v_add3_u32 v108, v111, v108, s71
	ds_write_b16_d16_hi v124, v108 offset:2736
	v_bfe_u32 v108, v104, 16, 1
	v_add3_u32 v104, v104, v108, s71
	ds_write_b16_d16_hi v124, v104 offset:2336
	v_bfe_u32 v104, v105, 16, 1
	v_add3_u32 v104, v105, v104, s71
	ds_write_b16_d16_hi v124, v104 offset:2480
	v_bfe_u32 v104, v106, 16, 1
	v_add3_u32 v104, v106, v104, s71
	ds_write_b16_d16_hi v124, v104 offset:2624
	v_bfe_u32 v104, v107, 16, 1
	v_add3_u32 v104, v107, v104, s71
	ds_write_b16_d16_hi v124, v104 offset:2768
	v_bfe_u32 v104, v100, 16, 1
	v_add3_u32 v100, v100, v104, s71
	ds_write_b16_d16_hi v124, v100 offset:2368
	v_bfe_u32 v100, v101, 16, 1
	v_add3_u32 v100, v101, v100, s71
	ds_write_b16_d16_hi v124, v100 offset:2512
	v_bfe_u32 v100, v102, 16, 1
	v_add3_u32 v100, v102, v100, s71
	ds_write_b16_d16_hi v124, v100 offset:2656
	v_bfe_u32 v100, v103, 16, 1
	v_add3_u32 v100, v103, v100, s71
	ds_write_b16_d16_hi v124, v100 offset:2800
	v_bfe_u32 v100, v96, 16, 1
	v_add3_u32 v96, v96, v100, s71
	ds_write_b16_d16_hi v124, v96 offset:2400
	v_bfe_u32 v96, v97, 16, 1
	v_add3_u32 v96, v97, v96, s71
	ds_write_b16_d16_hi v124, v96 offset:2544
	v_bfe_u32 v96, v98, 16, 1
	v_add3_u32 v96, v98, v96, s71
	ds_write_b16_d16_hi v124, v96 offset:2688
	v_bfe_u32 v96, v99, 16, 1
	v_add3_u32 v96, v99, v96, s71
	ds_write_b16_d16_hi v124, v96 offset:2832
	v_bfe_u32 v96, v92, 16, 1
	v_add3_u32 v92, v92, v96, s71
	ds_write_b16_d16_hi v124, v92 offset:4608
	v_bfe_u32 v92, v93, 16, 1
	v_add3_u32 v92, v93, v92, s71
	ds_write_b16_d16_hi v124, v92 offset:4752
	v_bfe_u32 v92, v94, 16, 1
	v_add3_u32 v92, v94, v92, s71
	ds_write_b16_d16_hi v124, v92 offset:4896
	v_bfe_u32 v92, v95, 16, 1
	v_add3_u32 v92, v95, v92, s71
	ds_write_b16_d16_hi v124, v92 offset:5040
	v_bfe_u32 v92, v88, 16, 1
	v_add3_u32 v88, v88, v92, s71
	ds_write_b16_d16_hi v124, v88 offset:4640
	v_bfe_u32 v88, v89, 16, 1
	v_add3_u32 v88, v89, v88, s71
	v_mfma_f32_16x16x32_bf16 v[84:87], v[164:167], v[136:139], v[84:87]
	ds_write_b16_d16_hi v124, v88 offset:4784
	v_bfe_u32 v88, v90, 16, 1
	v_add3_u32 v88, v90, v88, s71
	ds_write_b16_d16_hi v124, v88 offset:4928
	v_bfe_u32 v88, v91, 16, 1
	v_add3_u32 v88, v91, v88, s71
; DEV void store_tile_bf16(const f32x4 (&acc)[8][4], u16* __restrict__ OUT, size_t ld, int m0, int n0, int ncols,
;                          unsigned char* smem) {
;     ...
; #pragma unroll
;   for (int mh = 0; mh < 2; ++mh) {
; #pragma unroll
;     for (int mi = 0; mi < 4; ++mi)
; #pragma unroll
;       for (int ni = 0; ni < 4; ++ni)
; #pragma unroll
;         for (int j = 0; j < 4; ++j) st[(mi * 16 + fq * 4 + j) * 72 + ni * 16 + fr] = f2bf(acc[mh * 4 + mi][ni][j]);
;     const int chunk = lane & 7;
;     const int c0 = n0 + wc * 64 + chunk * 8;
; #pragma unroll
;     for (int itr = 0; itr < 8; ++itr) {
;       const int rl = (lane >> 3) + 8 * itr;
;       const u32x4 v = *(const u32x4*)(st + rl * 72 + chunk * 8);
;       if (c0 + 8 <= ncols) *(u32x4*)(OUT + (size_t)(m0 + wr * 128 + mh * 64 + rl) * ld + c0) = v;
;     }
	ds_write_b16_d16_hi v124, v88 offset:5072
	s_nop 0
	v_bfe_u32 v88, v84, 16, 1
	v_add3_u32 v84, v84, v88, s71
	ds_write_b16_d16_hi v124, v84 offset:4672
	v_bfe_u32 v84, v85, 16, 1
	v_add3_u32 v84, v85, v84, s71
	v_mfma_f32_16x16x32_bf16 v[80:83], v[164:167], v[140:143], v[80:83]
	ds_write_b16_d16_hi v124, v84 offset:4816
	v_bfe_u32 v84, v86, 16, 1
	v_add3_u32 v84, v86, v84, s71
	ds_write_b16_d16_hi v124, v84 offset:4960
	v_bfe_u32 v84, v87, 16, 1
	v_add3_u32 v84, v87, v84, s71
	ds_write_b16_d16_hi v124, v84 offset:5104
	s_nop 0
	v_bfe_u32 v84, v80, 16, 1
	v_add3_u32 v80, v80, v84, s71
	ds_write_b16_d16_hi v124, v80 offset:4704
	v_bfe_u32 v80, v81, 16, 1
	v_add3_u32 v80, v81, v80, s71
	ds_write_b16_d16_hi v124, v80 offset:4848
	v_bfe_u32 v80, v82, 16, 1
	v_add3_u32 v80, v82, v80, s71
	ds_write_b16_d16_hi v124, v80 offset:4992
	v_bfe_u32 v80, v83, 16, 1
	v_add3_u32 v80, v83, v80, s71
	ds_write_b16_d16_hi v124, v80 offset:5136
	v_bfe_u32 v80, v76, 16, 1
	v_add3_u32 v76, v76, v80, s71
	ds_write_b16_d16_hi v124, v76 offset:6912
	v_bfe_u32 v76, v77, 16, 1
	v_add3_u32 v76, v77, v76, s71
	ds_write_b16_d16_hi v124, v76 offset:7056
	v_bfe_u32 v76, v78, 16, 1
	v_add3_u32 v76, v78, v76, s71
	ds_write_b16_d16_hi v124, v76 offset:7200
	v_bfe_u32 v76, v79, 16, 1
	v_add3_u32 v76, v79, v76, s71
	ds_write_b16_d16_hi v124, v76 offset:7344
	v_bfe_u32 v76, v72, 16, 1
	v_add3_u32 v72, v72, v76, s71
	ds_write_b16_d16_hi v124, v72 offset:6944
	v_bfe_u32 v72, v73, 16, 1
	v_add3_u32 v72, v73, v72, s71
	v_mfma_f32_16x16x32_bf16 v[68:71], v[168:171], v[136:139], v[68:71]
	ds_write_b16_d16_hi v124, v72 offset:7088
	v_bfe_u32 v72, v74, 16, 1
	v_add3_u32 v72, v74, v72, s71
	ds_write_b16_d16_hi v124, v72 offset:7232
	v_bfe_u32 v72, v75, 16, 1
	v_add3_u32 v72, v75, v72, s71
	ds_write_b16_d16_hi v124, v72 offset:7376
	s_nop 0
	v_bfe_u32 v72, v68, 16, 1
	v_add3_u32 v68, v68, v72, s71
	ds_write_b16_d16_hi v124, v68 offset:6976
	v_bfe_u32 v68, v69, 16, 1
	v_add3_u32 v68, v69, v68, s71
	v_mfma_f32_16x16x32_bf16 v[64:67], v[168:171], v[140:143], v[64:67]
	ds_write_b16_d16_hi v124, v68 offset:7120
	v_bfe_u32 v68, v70, 16, 1
	v_add3_u32 v68, v70, v68, s71
	ds_write_b16_d16_hi v124, v68 offset:7264
	v_bfe_u32 v68, v71, 16, 1
	v_add3_u32 v68, v71, v68, s71
	ds_write_b16_d16_hi v124, v68 offset:7408
	s_nop 0
	v_bfe_u32 v68, v64, 16, 1
	v_add3_u32 v64, v64, v68, s71
	ds_write_b16_d16_hi v124, v64 offset:7008
	v_bfe_u32 v64, v65, 16, 1
	v_add3_u32 v64, v65, v64, s71
	ds_write_b16_d16_hi v124, v64 offset:7152
	v_bfe_u32 v64, v66, 16, 1
	v_mfma_f32_16x16x32_bf16 v[52:55], v[144:147], v[136:139], v[52:55]
	v_add3_u32 v64, v66, v64, s71
	ds_write_b16_d16_hi v124, v64 offset:7296
	v_bfe_u32 v64, v67, 16, 1
	v_mfma_f32_16x16x32_bf16 v[48:51], v[144:147], v[140:143], v[48:51]
	v_ashrrev_i32_e32 v129, 31, v128
	v_add3_u32 v64, v67, v64, s71
	v_cmp_gt_i32_e32 vcc, s33, v128
	v_mfma_f32_16x16x32_bf16 v[36:39], v[148:151], v[136:139], v[36:39]
	v_lshl_add_u64 v[128:129], v[128:129], 1, s[68:69]
	ds_write_b16_d16_hi v124, v64 offset:7440
	v_mad_u32_u24 v66, v133, s4, v131
	v_mfma_f32_16x16x32_bf16 v[32:35], v[148:151], v[140:143], v[32:35]
	v_or_b32_e32 v64, v134, v133
	ds_write_b16_d16_hi v124, v135
	v_mfma_f32_16x16x32_bf16 v[20:23], v[152:155], v[136:139], v[20:23]
	v_mfma_f32_16x16x32_bf16 v[16:19], v[152:155], v[140:143], v[16:19]
	v_mfma_f32_16x16x32_bf16 v[4:7], v[158:161], v[136:139], v[4:7]
	v_mfma_f32_16x16x32_bf16 v[0:3], v[158:161], v[140:143], v[0:3]
	s_and_saveexec_b64 s[4:5], vcc
	s_cbranch_execz .LBB0_229
	ds_read_b128 v[68:71], v66
	v_ashrrev_i32_e32 v65, 31, v64
	v_lshlrev_b64 v[72:73], 13, v[64:65]
	v_lshl_add_u64 v[72:73], v[128:129], 0, v[72:73]
	s_waitcnt lgkmcnt(0)
	global_store_dwordx4 v[72:73], v[68:71], off
	ds_read_b128 v[68:71], v66 offset:1152
	v_or_b32_e32 v72, 8, v64
	v_ashrrev_i32_e32 v73, 31, v72
	v_lshlrev_b64 v[72:73], 13, v[72:73]
	v_lshl_add_u64 v[72:73], v[128:129], 0, v[72:73]
	s_waitcnt lgkmcnt(0)
	global_store_dwordx4 v[72:73], v[68:71], off
	ds_read_b128 v[68:71], v66 offset:2304
	v_or_b32_e32 v72, 16, v64
	v_ashrrev_i32_e32 v73, 31, v72
	v_lshlrev_b64 v[72:73], 13, v[72:73]
	v_lshl_add_u64 v[72:73], v[128:129], 0, v[72:73]
	s_waitcnt lgkmcnt(0)
	global_store_dwordx4 v[72:73], v[68:71], off
	ds_read_b128 v[68:71], v66 offset:3456
	v_or_b32_e32 v72, 24, v64
	v_ashrrev_i32_e32 v73, 31, v72
	v_lshlrev_b64 v[72:73], 13, v[72:73]
	v_lshl_add_u64 v[72:73], v[128:129], 0, v[72:73]
	s_waitcnt lgkmcnt(0)
	global_store_dwordx4 v[72:73], v[68:71], off
	ds_read_b128 v[68:71], v66 offset:4608
	v_or_b32_e32 v72, 32, v64
	v_ashrrev_i32_e32 v73, 31, v72
	v_lshlrev_b64 v[72:73], 13, v[72:73]
	v_lshl_add_u64 v[72:73], v[128:129], 0, v[72:73]
	s_waitcnt lgkmcnt(0)
	global_store_dwordx4 v[72:73], v[68:71], off
	ds_read_b128 v[68:71], v66 offset:5760
	v_or_b32_e32 v72, 40, v64
	v_ashrrev_i32_e32 v73, 31, v72
	v_lshlrev_b64 v[72:73], 13, v[72:73]
	v_lshl_add_u64 v[72:73], v[128:129], 0, v[72:73]
	s_waitcnt lgkmcnt(0)
	global_store_dwordx4 v[72:73], v[68:71], off
	ds_read_b128 v[68:71], v66 offset:6912
	v_or_b32_e32 v72, 48, v64
	v_ashrrev_i32_e32 v73, 31, v72
	v_lshlrev_b64 v[72:73], 13, v[72:73]
	v_lshl_add_u64 v[72:73], v[128:129], 0, v[72:73]
	s_waitcnt lgkmcnt(0)
	global_store_dwordx4 v[72:73], v[68:71], off
	ds_read_b128 v[68:71], v66 offset:8064
	v_or_b32_e32 v72, 56, v64
	v_ashrrev_i32_e32 v73, 31, v72
	v_lshlrev_b64 v[72:73], 13, v[72:73]
	v_lshl_add_u64 v[72:73], v[128:129], 0, v[72:73]
	s_waitcnt lgkmcnt(0)
	global_store_dwordx4 v[72:73], v[68:71], off

; DEV f32x4 mfma16(bf16x8 a, bf16x8 b, f32x4 c) { return __builtin_amdgcn_mfma_f32_16x16x32_bf16(a, b, c, 0, 0, 0); }
; DEV void gemm_tile(const u16* __restrict__ A, size_t lda, const u16* __restrict__ Bt, size_t ldb, int K,
;                    u16* sA, u16* sB, f32x4 (&acc)[8][4]) {
;     ...
;   for (int kt = 0; kt < nk; ++kt) {
;     const int st = kt & 1;
;     if (kt + 1 < nk) S_STORE(st ^ 1)
;     if (kt + 2 < nk) G_LOAD((kt + 2) << 5)
;     {
;       const u16* pa = sAr + st * 12288;
;       const u16* pb = sBr + st * 12288;
;       bf16x8 b[4];
; #pragma unroll
;       for (int ni = 0; ni < 4; ++ni) b[ni] = *(const bf16x8*)(pb + ni * 16 * 32);
; #pragma unroll
;       for (int mh = 0; mh < 2; ++mh) {
;         bf16x8 a[4];
; #pragma unroll
;         for (int mi = 0; mi < 4; ++mi) a[mi] = *(const bf16x8*)(pa + (mh * 64 + mi * 16) * 32);
; #pragma unroll
;         for (int mi = 0; mi < 4; ++mi)
; #pragma unroll
;           for (int ni = 0; ni < 4; ++ni) acc[mh * 4 + mi][ni] = mfma16(a[mi], b[ni], acc[mh * 4 + mi][ni]);
;       }
;     }
;     __syncthreads();
;   }
.LBB0_251:
	v_add_u32_e32 v229, s8, v163
	v_add_u32_e32 v228, s8, v162
	ds_read_b128 v[124:127], v229 offset:16384
	ds_read_b128 v[166:169], v228
	ds_read_b128 v[132:135], v229 offset:17408
	ds_read_b128 v[144:147], v229 offset:18432
	ds_read_b128 v[128:131], v229 offset:19456
	ds_read_b128 v[152:155], v228 offset:1024
	ds_read_b128 v[170:173], v228 offset:2048
	ds_read_b128 v[136:139], v228 offset:3072
	s_waitcnt lgkmcnt(6)
	v_mfma_f32_16x16x32_bf16 v[148:151], v[166:169], v[124:127], v[148:151]
	s_waitcnt lgkmcnt(5)
	v_mfma_f32_16x16x32_bf16 v[120:123], v[166:169], v[132:135], v[120:123]
	s_waitcnt lgkmcnt(4)
	v_mfma_f32_16x16x32_bf16 v[116:119], v[166:169], v[144:147], v[116:119]
	s_waitcnt lgkmcnt(3)
	v_mfma_f32_16x16x32_bf16 v[112:115], v[166:169], v[128:131], v[112:115]
	ds_read_b128 v[232:235], v228 offset:4096
	ds_read_b128 v[236:239], v228 offset:5120
	s_waitcnt lgkmcnt(4)
	v_mfma_f32_16x16x32_bf16 v[108:111], v[152:155], v[124:127], v[108:111]
	s_add_i32 m0, s9, 0x0
	v_mfma_f32_16x16x32_bf16 v[104:107], v[152:155], v[132:135], v[104:107]
	global_load_lds_dwordx4 v[140:141], off
	v_lshl_add_u64 v[140:141], v[140:141], 0, 64
	global_load_dwordx4 v[244:247], v[140:141], off
	v_lshl_add_u64 v[140:141], v[140:141], 0, 64
	v_mfma_f32_16x16x32_bf16 v[100:103], v[152:155], v[144:147], v[100:103]
	s_add_i32 m0, s9, 0x1000
	v_mfma_f32_16x16x32_bf16 v[96:99], v[152:155], v[128:131], v[96:99]
	global_load_lds_dwordx4 v[142:143], off
	v_lshl_add_u64 v[142:143], v[142:143], 0, 64
	global_load_dwordx4 v[252:255], v[142:143], off
	v_lshl_add_u64 v[142:143], v[142:143], 0, 64
	s_waitcnt lgkmcnt(3)
	v_mfma_f32_16x16x32_bf16 v[92:95], v[170:173], v[124:127], v[92:95]
	s_add_i32 m0, s9, 0x2000
	v_mfma_f32_16x16x32_bf16 v[88:91], v[170:173], v[132:135], v[88:91]
	global_load_lds_dwordx4 v[174:175], off
	v_lshl_add_u64 v[174:175], v[174:175], 0, 64
	global_load_dwordx4 v[208:211], v[174:175], off
	v_lshl_add_u64 v[174:175], v[174:175], 0, 64
	v_mfma_f32_16x16x32_bf16 v[84:87], v[170:173], v[144:147], v[84:87]
	s_add_i32 m0, s9, 0x3000
	v_mfma_f32_16x16x32_bf16 v[80:83], v[170:173], v[128:131], v[80:83]
	ds_read_b128 v[240:243], v228 offset:6144
	ds_read_b128 v[166:169], v228 offset:7168
	s_waitcnt lgkmcnt(4)
	v_mfma_f32_16x16x32_bf16 v[76:79], v[136:139], v[124:127], v[76:79]
	global_load_lds_dwordx4 v[176:177], off
	v_lshl_add_u64 v[176:177], v[176:177], 0, 64
	global_load_dwordx4 v[212:215], v[176:177], off
	v_lshl_add_u64 v[176:177], v[176:177], 0, 64
	v_mfma_f32_16x16x32_bf16 v[72:75], v[136:139], v[132:135], v[72:75]
	s_add_i32 m0, s9, 0x4000
	v_mfma_f32_16x16x32_bf16 v[68:71], v[136:139], v[144:147], v[68:71]
	global_load_lds_dwordx4 v[186:187], off
	v_lshl_add_u64 v[186:187], v[186:187], 0, 64
	global_load_dwordx4 v[216:219], v[186:187], off
	v_lshl_add_u64 v[186:187], v[186:187], 0, 64
	v_mfma_f32_16x16x32_bf16 v[64:67], v[136:139], v[128:131], v[64:67]
	s_add_i32 m0, s9, 0x5000
	s_waitcnt lgkmcnt(3)
	v_mfma_f32_16x16x32_bf16 v[60:63], v[232:235], v[124:127], v[60:63]
	global_load_lds_dwordx4 v[188:189], off
	v_lshl_add_u64 v[188:189], v[188:189], 0, 64
	global_load_dwordx4 v[220:223], v[188:189], off
	v_lshl_add_u64 v[188:189], v[188:189], 0, 64
	v_mfma_f32_16x16x32_bf16 v[56:59], v[232:235], v[132:135], v[56:59]
	s_add_i32 s9, s8, s5
	s_add_i32 s8, s8, 0x6000
	v_mfma_f32_16x16x32_bf16 v[52:55], v[232:235], v[144:147], v[52:55]
	s_cmp_eq_u32 s8, 0x12000
	s_cselect_b32 s8, 0, s8
	v_mfma_f32_16x16x32_bf16 v[48:51], v[232:235], v[128:131], v[48:51]
	s_add_u32 s6, s6, 64
	s_addc_u32 s7, s7, 0
	s_cmpk_lg_i32 s6, 0xf80
	s_waitcnt lgkmcnt(2)
	v_mfma_f32_16x16x32_bf16 v[44:47], v[236:239], v[124:127], v[44:47]
	v_mfma_f32_16x16x32_bf16 v[40:43], v[236:239], v[132:135], v[40:43]
	v_mfma_f32_16x16x32_bf16 v[36:39], v[236:239], v[144:147], v[36:39]
	v_mfma_f32_16x16x32_bf16 v[32:35], v[236:239], v[128:131], v[32:35]
	s_waitcnt lgkmcnt(1)
	v_mfma_f32_16x16x32_bf16 v[28:31], v[240:243], v[124:127], v[28:31]
	v_mfma_f32_16x16x32_bf16 v[24:27], v[240:243], v[132:135], v[24:27]
	v_mfma_f32_16x16x32_bf16 v[20:23], v[240:243], v[144:147], v[20:23]
	v_mfma_f32_16x16x32_bf16 v[16:19], v[240:243], v[128:131], v[16:19]
	s_waitcnt lgkmcnt(0)
	s_waitcnt vmcnt(12)
	s_barrier
	v_mfma_f32_16x16x32_bf16 v[12:15], v[166:169], v[124:127], v[12:15]
	v_mfma_f32_16x16x32_bf16 v[8:11], v[166:169], v[132:135], v[8:11]
	v_mfma_f32_16x16x32_bf16 v[4:7], v[166:169], v[144:147], v[4:7]
	v_mfma_f32_16x16x32_bf16 v[0:3], v[166:169], v[128:131], v[0:3]
	v_add_u32_e32 v229, s8, v163
	v_add_u32_e32 v228, s8, v162
	ds_read_b128 v[124:127], v229 offset:16384
	ds_read_b128 v[166:169], v228
	ds_read_b128 v[132:135], v229 offset:17408
	ds_read_b128 v[144:147], v229 offset:18432
	ds_read_b128 v[128:131], v229 offset:19456
	ds_read_b128 v[152:155], v228 offset:1024
	ds_read_b128 v[170:173], v228 offset:2048
	ds_read_b128 v[136:139], v228 offset:3072
	s_waitcnt lgkmcnt(6)
	v_mfma_f32_16x16x32_bf16 v[148:151], v[166:169], v[124:127], v[148:151]
	s_waitcnt lgkmcnt(5)
	v_mfma_f32_16x16x32_bf16 v[120:123], v[166:169], v[132:135], v[120:123]
	s_waitcnt lgkmcnt(4)
	v_mfma_f32_16x16x32_bf16 v[116:119], v[166:169], v[144:147], v[116:119]
	s_waitcnt lgkmcnt(3)
	v_mfma_f32_16x16x32_bf16 v[112:115], v[166:169], v[128:131], v[112:115]
	ds_read_b128 v[232:235], v228 offset:4096
	ds_read_b128 v[236:239], v228 offset:5120
	s_waitcnt lgkmcnt(4)
	v_mfma_f32_16x16x32_bf16 v[108:111], v[152:155], v[124:127], v[108:111]
	v_mfma_f32_16x16x32_bf16 v[104:107], v[152:155], v[132:135], v[104:107]
	v_mfma_f32_16x16x32_bf16 v[100:103], v[152:155], v[144:147], v[100:103]
	v_mfma_f32_16x16x32_bf16 v[96:99], v[152:155], v[128:131], v[96:99]
	s_waitcnt lgkmcnt(3)
; DEV f32x4 mfma16(bf16x8 a, bf16x8 b, f32x4 c) { return __builtin_amdgcn_mfma_f32_16x16x32_bf16(a, b, c, 0, 0, 0); }
; DEV void gemm_tile(const u16* __restrict__ A, size_t lda, const u16* __restrict__ Bt, size_t ldb, int K,
;                    u16* sA, u16* sB, f32x4 (&acc)[8][4]) {
;     ...
;   for (int kt = 0; kt < nk; ++kt) {
;     const int st = kt & 1;
;     if (kt + 1 < nk) S_STORE(st ^ 1)
;     if (kt + 2 < nk) G_LOAD((kt + 2) << 5)
;     {
;       const u16* pa = sAr + st * 12288;
;       const u16* pb = sBr + st * 12288;
;       bf16x8 b[4];
; #pragma unroll
;       for (int ni = 0; ni < 4; ++ni) b[ni] = *(const bf16x8*)(pb + ni * 16 * 32);
; #pragma unroll
;       for (int mh = 0; mh < 2; ++mh) {
;         bf16x8 a[4];
; #pragma unroll
;         for (int mi = 0; mi < 4; ++mi) a[mi] = *(const bf16x8*)(pa + (mh * 64 + mi * 16) * 32);
; #pragma unroll
;         for (int mi = 0; mi < 4; ++mi)
; #pragma unroll
;           for (int ni = 0; ni < 4; ++ni) acc[mh * 4 + mi][ni] = mfma16(a[mi], b[ni], acc[mh * 4 + mi][ni]);
;       }
;     }
;     __syncthreads();
;   }
	v_mfma_f32_16x16x32_bf16 v[92:95], v[170:173], v[124:127], v[92:95]
	v_mfma_f32_16x16x32_bf16 v[88:91], v[170:173], v[132:135], v[88:91]
	v_mfma_f32_16x16x32_bf16 v[84:87], v[170:173], v[144:147], v[84:87]
	v_mfma_f32_16x16x32_bf16 v[80:83], v[170:173], v[128:131], v[80:83]
	ds_read_b128 v[240:243], v228 offset:6144
	ds_read_b128 v[166:169], v228 offset:7168
	s_waitcnt lgkmcnt(4)
	v_mfma_f32_16x16x32_bf16 v[76:79], v[136:139], v[124:127], v[76:79]
	s_waitcnt vmcnt(0)
	v_add_u32_e32 v231, s9, v230
	v_mfma_f32_16x16x32_bf16 v[72:75], v[136:139], v[132:135], v[72:75]
	ds_write_b128 v231, v[244:247]
	v_mfma_f32_16x16x32_bf16 v[68:71], v[136:139], v[144:147], v[68:71]
	ds_write_b128 v231, v[252:255] offset:4096
	v_mfma_f32_16x16x32_bf16 v[64:67], v[136:139], v[128:131], v[64:67]
	ds_write_b128 v231, v[208:211] offset:8192
	s_waitcnt lgkmcnt(6)
	v_mfma_f32_16x16x32_bf16 v[60:63], v[232:235], v[124:127], v[60:63]
	ds_write_b128 v231, v[212:215] offset:12288
	v_mfma_f32_16x16x32_bf16 v[56:59], v[232:235], v[132:135], v[56:59]
	ds_write_b128 v231, v[216:219] offset:16384
	v_mfma_f32_16x16x32_bf16 v[52:55], v[232:235], v[144:147], v[52:55]
	ds_write_b128 v231, v[220:223] offset:20480
	v_mfma_f32_16x16x32_bf16 v[48:51], v[232:235], v[128:131], v[48:51]
	s_add_i32 s9, s8, s5
	s_add_i32 s8, s8, 0x6000
	s_waitcnt lgkmcnt(8)
	v_mfma_f32_16x16x32_bf16 v[44:47], v[236:239], v[124:127], v[44:47]
	s_cmp_eq_u32 s8, 0x12000
	s_cselect_b32 s8, 0, s8
	v_mfma_f32_16x16x32_bf16 v[40:43], v[236:239], v[132:135], v[40:43]
	s_add_u32 s6, s6, 64
	s_addc_u32 s7, s7, 0
	s_cmpk_lg_i32 s6, 0xf80
	v_mfma_f32_16x16x32_bf16 v[36:39], v[236:239], v[144:147], v[36:39]
	v_mfma_f32_16x16x32_bf16 v[32:35], v[236:239], v[128:131], v[32:35]
	s_waitcnt lgkmcnt(7)
	v_mfma_f32_16x16x32_bf16 v[28:31], v[240:243], v[124:127], v[28:31]
	v_mfma_f32_16x16x32_bf16 v[24:27], v[240:243], v[132:135], v[24:27]
	v_mfma_f32_16x16x32_bf16 v[20:23], v[240:243], v[144:147], v[20:23]
	v_mfma_f32_16x16x32_bf16 v[16:19], v[240:243], v[128:131], v[16:19]
	s_waitcnt lgkmcnt(6)
	s_waitcnt lgkmcnt(0)
	s_barrier
	v_mfma_f32_16x16x32_bf16 v[12:15], v[166:169], v[124:127], v[12:15]
	v_mfma_f32_16x16x32_bf16 v[8:11], v[166:169], v[132:135], v[8:11]
	v_mfma_f32_16x16x32_bf16 v[4:7], v[166:169], v[144:147], v[4:7]
	v_mfma_f32_16x16x32_bf16 v[0:3], v[166:169], v[128:131], v[0:3]
	s_cbranch_scc1 .LBB0_251
	ds_read_b128 v[124:127], v163 offset:16384
	ds_read_b128 v[128:131], v163 offset:17408
	ds_read_b128 v[132:135], v163 offset:18432
	ds_read_b128 v[136:139], v163 offset:19456
	ds_read_b128 v[140:143], v162
	ds_read_b128 v[144:147], v162 offset:1024
	ds_read_b128 v[152:155], v162 offset:2048
	ds_read_b128 v[158:161], v162 offset:3072
	s_movk_i32 s5, 0x2200
	s_waitcnt lgkmcnt(3)
	v_mfma_f32_16x16x32_bf16 v[148:151], v[140:143], v[124:127], v[148:151]
	v_mfma_f32_16x16x32_bf16 v[120:123], v[140:143], v[128:131], v[120:123]
	v_mfma_f32_16x16x32_bf16 v[116:119], v[140:143], v[132:135], v[116:119]
	v_mfma_f32_16x16x32_bf16 v[112:115], v[140:143], v[136:139], v[112:115]
	s_waitcnt lgkmcnt(2)
	v_mfma_f32_16x16x32_bf16 v[108:111], v[144:147], v[124:127], v[108:111]
	v_mfma_f32_16x16x32_bf16 v[104:107], v[144:147], v[128:131], v[104:107]
	v_mfma_f32_16x16x32_bf16 v[100:103], v[144:147], v[132:135], v[100:103]
	v_mfma_f32_16x16x32_bf16 v[96:99], v[144:147], v[136:139], v[96:99]
	s_waitcnt lgkmcnt(1)
	v_mfma_f32_16x16x32_bf16 v[92:95], v[152:155], v[124:127], v[92:95]
	v_mfma_f32_16x16x32_bf16 v[88:91], v[152:155], v[128:131], v[88:91]
	v_mfma_f32_16x16x32_bf16 v[84:87], v[152:155], v[132:135], v[84:87]
	v_mfma_f32_16x16x32_bf16 v[80:83], v[152:155], v[136:139], v[80:83]
	s_waitcnt lgkmcnt(0)
	v_mfma_f32_16x16x32_bf16 v[76:79], v[158:161], v[124:127], v[76:79]
	v_mfma_f32_16x16x32_bf16 v[72:75], v[158:161], v[128:131], v[72:75]
	v_mfma_f32_16x16x32_bf16 v[68:71], v[158:161], v[132:135], v[68:71]
	v_mfma_f32_16x16x32_bf16 v[64:67], v[158:161], v[136:139], v[64:67]
	ds_read_b128 v[140:143], v162 offset:4096
	ds_read_b128 v[144:147], v162 offset:5120
	ds_read_b128 v[152:155], v162 offset:6144
	ds_read_b128 v[158:161], v162 offset:7168
	s_waitcnt lgkmcnt(0)
	s_waitcnt vmcnt(0)
	s_barrier
	v_mfma_f32_16x16x32_bf16 v[60:63], v[140:143], v[124:127], v[60:63]
	v_mfma_f32_16x16x32_bf16 v[56:59], v[140:143], v[128:131], v[56:59]
	v_mfma_f32_16x16x32_bf16 v[52:55], v[140:143], v[132:135], v[52:55]
	v_mfma_f32_16x16x32_bf16 v[48:51], v[140:143], v[136:139], v[48:51]
	v_mfma_f32_16x16x32_bf16 v[44:47], v[144:147], v[124:127], v[44:47]
	v_mfma_f32_16x16x32_bf16 v[40:43], v[144:147], v[128:131], v[40:43]
	v_mfma_f32_16x16x32_bf16 v[36:39], v[144:147], v[132:135], v[36:39]
	v_mfma_f32_16x16x32_bf16 v[32:35], v[144:147], v[136:139], v[32:35]
	v_mfma_f32_16x16x32_bf16 v[28:31], v[152:155], v[124:127], v[28:31]
	v_mfma_f32_16x16x32_bf16 v[24:27], v[152:155], v[128:131], v[24:27]
	v_mfma_f32_16x16x32_bf16 v[20:23], v[152:155], v[132:135], v[20:23]
	v_mfma_f32_16x16x32_bf16 v[16:19], v[152:155], v[136:139], v[16:19]
	v_mfma_f32_16x16x32_bf16 v[12:15], v[158:161], v[124:127], v[12:15]
	v_mfma_f32_16x16x32_bf16 v[8:11], v[158:161], v[128:131], v[8:11]
	v_mfma_f32_16x16x32_bf16 v[4:7], v[158:161], v[132:135], v[4:7]
	v_mfma_f32_16x16x32_bf16 v[0:3], v[158:161], v[136:139], v[0:3]
	ds_read_b128 v[124:127], v163 offset:40960
	ds_read_b128 v[128:131], v163 offset:41984
	ds_read_b128 v[132:135], v163 offset:43008
	ds_read_b128 v[136:139], v163 offset:44032
	ds_read_b128 v[140:143], v162 offset:24576
	ds_read_b128 v[144:147], v162 offset:25600
	ds_read_b128 v[152:155], v162 offset:26624
	ds_read_b128 v[158:161], v162 offset:27648
	s_waitcnt lgkmcnt(3)
	v_mfma_f32_16x16x32_bf16 v[148:151], v[140:143], v[124:127], v[148:151]
	v_mfma_f32_16x16x32_bf16 v[120:123], v[140:143], v[128:131], v[120:123]
	v_mfma_f32_16x16x32_bf16 v[116:119], v[140:143], v[132:135], v[116:119]
	v_mfma_f32_16x16x32_bf16 v[112:115], v[140:143], v[136:139], v[112:115]
	s_waitcnt lgkmcnt(2)
	v_mfma_f32_16x16x32_bf16 v[108:111], v[144:147], v[124:127], v[108:111]
	v_mfma_f32_16x16x32_bf16 v[140:143], v[144:147], v[128:131], v[104:107]
	v_mfma_f32_16x16x32_bf16 v[164:167], v[144:147], v[132:135], v[100:103]
	v_mfma_f32_16x16x32_bf16 v[96:99], v[144:147], v[136:139], v[96:99]
	s_waitcnt lgkmcnt(1)
	v_mfma_f32_16x16x32_bf16 v[92:95], v[152:155], v[124:127], v[92:95]
	v_mfma_f32_16x16x32_bf16 v[88:91], v[152:155], v[128:131], v[88:91]
	v_mfma_f32_16x16x32_bf16 v[84:87], v[152:155], v[132:135], v[84:87]
	v_mfma_f32_16x16x32_bf16 v[80:83], v[152:155], v[136:139], v[80:83]
	ds_read_b128 v[100:103], v162 offset:28672
	ds_read_b128 v[104:107], v162 offset:29696
	ds_read_b128 v[144:147], v162 offset:30720
	ds_read_b128 v[152:155], v162 offset:31744
	s_waitcnt lgkmcnt(0)
	s_barrier
; DEV int TID() { int t = threadIdx.x; asm volatile("" : "+v"(t)); return t; }
; DEV void store_tile_f32_add(const f32x4 (&acc)[8][4], const float* xres, float* out, int m0, int n0, unsigned char* smem) {
;   const int tid = TID(), lane = tid & 63, wid = tid >> 6;
;   const int wr = wid >> 1, wc = wid & 1, fr = lane & 15, fq = lane >> 4;
;   float* st = (float*)(smem + wid * 8704);
;   const int chunk = lane & 15;
; #pragma unroll
;   for (int mq = 0; mq < 4; ++mq) {
; #pragma unroll
;     for (int mh = 0; mh < 2; ++mh)
; #pragma unroll
;       for (int ni = 0; ni < 4; ++ni)
; #pragma unroll
;         for (int j = 0; j < 4; ++j) st[(mh * 16 + fq * 4 + j) * 68 + ni * 16 + fr] = acc[mq * 2 + mh][ni][j];
; #pragma unroll
;     for (int itr = 0; itr < 8; ++itr) {
;       const int rl = (lane >> 4) + 4 * itr;
;       const f32x4 v = *(const f32x4*)(st + rl * 68 + chunk * 4);
;       const size_t idx = (size_t)(m0 + wr * 128 + mq * 32 + rl) * 2048 + n0 + wc * 64 + chunk * 4;
;       const f32x4 x = *(const f32x4*)(xres + idx);
;       *(f32x4*)(out + idx) = x + v;
;     }
	v_mfma_f32_16x16x32_bf16 v[60:63], v[100:103], v[124:127], v[60:63]
	v_mfma_f32_16x16x32_bf16 v[56:59], v[100:103], v[128:131], v[56:59]
	v_mfma_f32_16x16x32_bf16 v[52:55], v[100:103], v[132:135], v[52:55]
	v_mfma_f32_16x16x32_bf16 v[48:51], v[100:103], v[136:139], v[48:51]
	v_mov_b32_e32 v100, v178
	s_nop 0
	v_lshrrev_b32_e32 v101, 6, v100
	v_and_b32_e32 v103, 15, v100
	v_mfma_f32_16x16x32_bf16 v[44:47], v[104:107], v[124:127], v[44:47]
	v_mul_lo_u32 v101, v101, s5
	v_bfe_u32 v102, v100, 4, 2
	v_mfma_f32_16x16x32_bf16 v[40:43], v[104:107], v[128:131], v[40:43]
	v_mfma_f32_16x16x32_bf16 v[36:39], v[104:107], v[132:135], v[36:39]
	v_mfma_f32_16x16x32_bf16 v[32:35], v[104:107], v[136:139], v[32:35]
	v_lshlrev_b32_e32 v104, 2, v103
	v_or_b32_e32 v105, v101, v104
	v_and_b32_e32 v101, 0xffffff80, v100
	v_mad_u32_u24 v107, v103, 12, v105
	v_add_u32_e32 v103, s4, v101
	v_mov_b32_e32 v101, s3
	s_movk_i32 s3, 0x440
	v_mad_u32_u24 v106, v102, s3, v105
	ds_write_b32 v106, v148
	ds_write_b32 v106, v149 offset:272
	ds_write_b32 v106, v150 offset:544
	ds_write_b32 v106, v151 offset:816
	ds_write_b32 v106, v120 offset:64
	ds_write_b32 v106, v121 offset:336
	ds_write_b32 v106, v122 offset:608
	ds_write_b32 v106, v123 offset:880
	ds_write_b32 v106, v116 offset:128
	ds_write_b32 v106, v117 offset:400
	ds_write_b32 v106, v118 offset:672
	ds_write_b32 v106, v119 offset:944
	ds_write_b32 v106, v112 offset:192
	ds_write_b32 v106, v113 offset:464
	ds_write_b32 v106, v114 offset:736
	ds_write_b32 v106, v115 offset:1008
	ds_write_b32 v106, v108 offset:4352
	ds_write_b32 v106, v109 offset:4624
	ds_write_b32 v106, v110 offset:4896
	ds_write_b32 v106, v111 offset:5168
	ds_write_b32 v106, v140 offset:4416
	ds_write_b32 v106, v141 offset:4688
	ds_write_b32 v106, v142 offset:4960
	ds_write_b32 v106, v143 offset:5232
	ds_write_b32 v106, v164 offset:4480
	ds_write_b32 v106, v165 offset:4752
	ds_write_b32 v106, v166 offset:5024
	ds_write_b32 v106, v167 offset:5296
	ds_write_b32 v106, v96 offset:4544
	ds_write_b32 v106, v97 offset:4816
	ds_write_b32 v106, v98 offset:5088
	ds_write_b32 v106, v99 offset:5360
	v_or_b32_e32 v108, v103, v102
	v_and_b32_e32 v100, 64, v100
	v_ashrrev_i32_e32 v109, 31, v108
	v_or3_b32 v100, v104, v100, s2
	v_lshlrev_b64 v[108:109], 11, v[108:109]
	v_lshl_add_u64 v[108:109], v[100:101], 0, v[108:109]
	v_lshlrev_b64 v[112:113], 2, v[108:109]
	v_lshl_add_u64 v[108:109], s[20:21], 0, v[112:113]
	global_load_dwordx4 v[108:111], v[108:109], off
	s_movk_i32 s2, 0x110
	v_mad_u32_u24 v104, v102, s2, v107
	ds_read_b128 v[96:99], v104
	v_readlane_b32 s4, v251, 7
	v_readlane_b32 s6, v251, 9
	v_readlane_b32 s7, v251, 10
	v_or_b32_e32 v105, 20, v102
	v_mfma_f32_16x16x32_bf16 v[64:67], v[158:161], v[136:139], v[64:67]
	v_readlane_b32 s5, v251, 8
	s_waitcnt vmcnt(0) lgkmcnt(0)
	v_pk_add_f32 v[98:99], v[98:99], v[110:111]
	v_pk_add_f32 v[96:97], v[96:97], v[108:109]
	v_lshl_add_u64 v[108:109], s[6:7], 0, v[112:113]
	global_store_dwordx4 v[108:109], v[96:99], off
	v_or_b32_e32 v109, 4, v102
	v_or_b32_e32 v108, 28, v102
	v_or_b32_e32 v98, v109, v103
	v_ashrrev_i32_e32 v99, 31, v98
	v_lshlrev_b64 v[98:99], 11, v[98:99]
	v_lshl_add_u64 v[98:99], v[98:99], 0, v[100:101]
	v_lshlrev_b64 v[98:99], 2, v[98:99]
	v_lshl_add_u64 v[114:115], s[20:21], 0, v[98:99]
	global_load_dwordx4 v[114:117], v[114:115], off
	v_mad_u32_u24 v96, v109, s2, v107
	ds_read_b128 v[110:113], v96
	v_lshl_add_u64 v[98:99], s[6:7], 0, v[98:99]
	v_or_b32_e32 v97, 8, v102
	v_or_b32_e32 v107, 24, v102
	v_mfma_f32_16x16x32_bf16 v[76:79], v[158:161], v[124:127], v[76:79]
	s_waitcnt vmcnt(0) lgkmcnt(0)
	v_pk_add_f32 v[112:113], v[112:113], v[116:117]
	v_pk_add_f32 v[110:111], v[110:111], v[114:115]
	global_store_dwordx4 v[98:99], v[110:113], off
	v_or_b32_e32 v98, v97, v103
	v_ashrrev_i32_e32 v99, 31, v98
	v_lshlrev_b64 v[98:99], 11, v[98:99]
	v_lshl_add_u64 v[98:99], v[98:99], 0, v[100:101]
	v_lshlrev_b64 v[98:99], 2, v[98:99]
	v_lshl_add_u64 v[114:115], s[20:21], 0, v[98:99]
	global_load_dwordx4 v[114:117], v[114:115], off
	ds_read_b128 v[110:113], v96 offset:1088
	v_lshl_add_u64 v[98:99], s[6:7], 0, v[98:99]
	v_mfma_f32_16x16x32_bf16 v[72:75], v[158:161], v[128:131], v[72:75]
	s_waitcnt vmcnt(0) lgkmcnt(0)
	v_pk_add_f32 v[112:113], v[112:113], v[116:117]
	v_pk_add_f32 v[110:111], v[110:111], v[114:115]
	global_store_dwordx4 v[98:99], v[110:113], off
	v_or_b32_e32 v98, 12, v102
	v_or_b32_e32 v114, v98, v103
	v_ashrrev_i32_e32 v115, 31, v114
	v_lshlrev_b64 v[114:115], 11, v[114:115]
	v_lshl_add_u64 v[114:115], v[114:115], 0, v[100:101]
	v_lshlrev_b64 v[118:119], 2, v[114:115]
	v_lshl_add_u64 v[114:115], s[20:21], 0, v[118:119]
	global_load_dwordx4 v[114:117], v[114:115], off
	ds_read_b128 v[110:113], v96 offset:2176
	v_or_b32_e32 v99, 16, v102
	v_mfma_f32_16x16x32_bf16 v[68:71], v[158:161], v[132:135], v[68:71]
	s_waitcnt vmcnt(0) lgkmcnt(0)
	v_pk_add_f32 v[112:113], v[112:113], v[116:117]
	v_pk_add_f32 v[110:111], v[110:111], v[114:115]
	v_lshl_add_u64 v[114:115], s[6:7], 0, v[118:119]
	global_store_dwordx4 v[114:115], v[110:113], off
	v_or_b32_e32 v114, v99, v103
	v_ashrrev_i32_e32 v115, 31, v114
	v_lshlrev_b64 v[114:115], 11, v[114:115]
	v_lshl_add_u64 v[114:115], v[114:115], 0, v[100:101]
	v_lshlrev_b64 v[118:119], 2, v[114:115]
	v_lshl_add_u64 v[114:115], s[20:21], 0, v[118:119]
	global_load_dwordx4 v[114:117], v[114:115], off
	ds_read_b128 v[110:113], v96 offset:3264
	v_mfma_f32_16x16x32_bf16 v[28:31], v[144:147], v[124:127], v[28:31]
	s_waitcnt vmcnt(0) lgkmcnt(0)
; DEV void store_tile_f32_add(const f32x4 (&acc)[8][4], const float* xres, float* out, int m0, int n0, unsigned char* smem) {
;     ...
; #pragma unroll
;   for (int mq = 0; mq < 4; ++mq) {
; #pragma unroll
;     for (int mh = 0; mh < 2; ++mh)
; #pragma unroll
;       for (int ni = 0; ni < 4; ++ni)
; #pragma unroll
;         for (int j = 0; j < 4; ++j) st[(mh * 16 + fq * 4 + j) * 68 + ni * 16 + fr] = acc[mq * 2 + mh][ni][j];
; #pragma unroll
;     for (int itr = 0; itr < 8; ++itr) {
;       const int rl = (lane >> 4) + 4 * itr;
;       const f32x4 v = *(const f32x4*)(st + rl * 68 + chunk * 4);
;       const size_t idx = (size_t)(m0 + wr * 128 + mq * 32 + rl) * 2048 + n0 + wc * 64 + chunk * 4;
;       const f32x4 x = *(const f32x4*)(xres + idx);
;       *(f32x4*)(out + idx) = x + v;
;     }
	v_pk_add_f32 v[112:113], v[112:113], v[116:117]
	v_pk_add_f32 v[110:111], v[110:111], v[114:115]
	v_lshl_add_u64 v[114:115], s[6:7], 0, v[118:119]
	global_store_dwordx4 v[114:115], v[110:113], off
	v_or_b32_e32 v114, v105, v103
	v_ashrrev_i32_e32 v115, 31, v114
	v_lshlrev_b64 v[114:115], 11, v[114:115]
	v_lshl_add_u64 v[114:115], v[114:115], 0, v[100:101]
	v_lshlrev_b64 v[118:119], 2, v[114:115]
	v_lshl_add_u64 v[114:115], s[20:21], 0, v[118:119]
	global_load_dwordx4 v[114:117], v[114:115], off
	ds_read_b128 v[110:113], v96 offset:4352
	v_mfma_f32_16x16x32_bf16 v[0:3], v[152:155], v[136:139], v[0:3]
	s_waitcnt vmcnt(0) lgkmcnt(0)
	v_pk_add_f32 v[112:113], v[112:113], v[116:117]
	v_pk_add_f32 v[110:111], v[110:111], v[114:115]
	v_lshl_add_u64 v[114:115], s[6:7], 0, v[118:119]
	global_store_dwordx4 v[114:115], v[110:113], off
	v_or_b32_e32 v114, v107, v103
	v_ashrrev_i32_e32 v115, 31, v114
	v_lshlrev_b64 v[114:115], 11, v[114:115]
	v_lshl_add_u64 v[114:115], v[114:115], 0, v[100:101]
	v_lshlrev_b64 v[118:119], 2, v[114:115]
	v_lshl_add_u64 v[114:115], s[20:21], 0, v[118:119]
	global_load_dwordx4 v[114:117], v[114:115], off
	ds_read_b128 v[110:113], v96 offset:5440
	v_mfma_f32_16x16x32_bf16 v[24:27], v[144:147], v[128:131], v[24:27]
	s_waitcnt vmcnt(0) lgkmcnt(0)
	v_pk_add_f32 v[112:113], v[112:113], v[116:117]
	v_pk_add_f32 v[110:111], v[110:111], v[114:115]
	v_lshl_add_u64 v[114:115], s[6:7], 0, v[118:119]
	global_store_dwordx4 v[114:115], v[110:113], off
	v_or_b32_e32 v114, v108, v103
	v_ashrrev_i32_e32 v115, 31, v114
	v_lshlrev_b64 v[114:115], 11, v[114:115]
	v_lshl_add_u64 v[114:115], v[114:115], 0, v[100:101]
	v_lshlrev_b64 v[118:119], 2, v[114:115]
	v_lshl_add_u64 v[114:115], s[20:21], 0, v[118:119]
	global_load_dwordx4 v[114:117], v[114:115], off
	ds_read_b128 v[110:113], v96 offset:6528
	v_mfma_f32_16x16x32_bf16 v[20:23], v[144:147], v[132:135], v[20:23]
	s_waitcnt vmcnt(0) lgkmcnt(0)
	v_pk_add_f32 v[112:113], v[112:113], v[116:117]
	v_pk_add_f32 v[110:111], v[110:111], v[114:115]
	v_lshl_add_u64 v[114:115], s[6:7], 0, v[118:119]
	global_store_dwordx4 v[114:115], v[110:113], off
	ds_write_b32 v106, v92
	ds_write_b32 v106, v93 offset:272
	ds_write_b32 v106, v94 offset:544
	ds_write_b32 v106, v95 offset:816
	ds_write_b32 v106, v88 offset:64
	ds_write_b32 v106, v89 offset:336
	ds_write_b32 v106, v90 offset:608
	ds_write_b32 v106, v91 offset:880
	ds_write_b32 v106, v84 offset:128
	ds_write_b32 v106, v85 offset:400
	ds_write_b32 v106, v86 offset:672
	ds_write_b32 v106, v87 offset:944
	ds_write_b32 v106, v80 offset:192
	ds_write_b32 v106, v81 offset:464
	ds_write_b32 v106, v82 offset:736
	ds_write_b32 v106, v83 offset:1008
	ds_write_b32 v106, v76 offset:4352
	ds_write_b32 v106, v77 offset:4624
	ds_write_b32 v106, v78 offset:4896
	ds_write_b32 v106, v79 offset:5168
	ds_write_b32 v106, v72 offset:4416
	ds_write_b32 v106, v73 offset:4688
	ds_write_b32 v106, v74 offset:4960
	ds_write_b32 v106, v75 offset:5232
	ds_write_b32 v106, v68 offset:4480
	ds_write_b32 v106, v69 offset:4752
	ds_write_b32 v106, v70 offset:5024
	ds_write_b32 v106, v71 offset:5296
	ds_write_b32 v106, v64 offset:4544
	ds_write_b32 v106, v65 offset:4816
	ds_write_b32 v106, v66 offset:5088
	ds_write_b32 v106, v67 offset:5360
	v_or_b32_e32 v64, 32, v103
	v_or_b32_e32 v70, v64, v102
	v_ashrrev_i32_e32 v71, 31, v70
	v_lshlrev_b64 v[70:71], 11, v[70:71]
	v_lshl_add_u64 v[70:71], v[70:71], 0, v[100:101]
	v_lshlrev_b64 v[74:75], 2, v[70:71]
	v_lshl_add_u64 v[70:71], s[20:21], 0, v[74:75]
	global_load_dwordx4 v[70:73], v[70:71], off
	ds_read_b128 v[66:69], v104
	v_mfma_f32_16x16x32_bf16 v[16:19], v[144:147], v[136:139], v[16:19]
	s_waitcnt vmcnt(0) lgkmcnt(0)
	v_pk_add_f32 v[68:69], v[68:69], v[72:73]
	v_pk_add_f32 v[66:67], v[66:67], v[70:71]
	v_lshl_add_u64 v[70:71], s[6:7], 0, v[74:75]
	global_store_dwordx4 v[70:71], v[66:69], off
	v_or_b32_e32 v70, v64, v109
	v_ashrrev_i32_e32 v71, 31, v70
	v_lshlrev_b64 v[70:71], 11, v[70:71]
	v_lshl_add_u64 v[70:71], v[70:71], 0, v[100:101]
	v_lshlrev_b64 v[74:75], 2, v[70:71]
	v_lshl_add_u64 v[70:71], s[20:21], 0, v[74:75]
	global_load_dwordx4 v[70:73], v[70:71], off
	ds_read_b128 v[66:69], v96
	v_mfma_f32_16x16x32_bf16 v[12:15], v[152:155], v[124:127], v[12:15]
	s_waitcnt vmcnt(0) lgkmcnt(0)
	v_pk_add_f32 v[68:69], v[68:69], v[72:73]
	v_pk_add_f32 v[66:67], v[66:67], v[70:71]
	v_lshl_add_u64 v[70:71], s[6:7], 0, v[74:75]
	global_store_dwordx4 v[70:71], v[66:69], off
	v_or_b32_e32 v70, v64, v97
	v_ashrrev_i32_e32 v71, 31, v70
	v_lshlrev_b64 v[70:71], 11, v[70:71]
	v_lshl_add_u64 v[70:71], v[70:71], 0, v[100:101]
	v_lshlrev_b64 v[74:75], 2, v[70:71]
	v_lshl_add_u64 v[70:71], s[20:21], 0, v[74:75]
	global_load_dwordx4 v[70:73], v[70:71], off
	ds_read_b128 v[66:69], v96 offset:1088
	v_mfma_f32_16x16x32_bf16 v[8:11], v[152:155], v[128:131], v[8:11]
	s_waitcnt vmcnt(0) lgkmcnt(0)
	v_pk_add_f32 v[68:69], v[68:69], v[72:73]
	v_pk_add_f32 v[66:67], v[66:67], v[70:71]
	v_lshl_add_u64 v[70:71], s[6:7], 0, v[74:75]
	global_store_dwordx4 v[70:71], v[66:69], off
	v_or_b32_e32 v70, v64, v98
	v_ashrrev_i32_e32 v71, 31, v70
	v_lshlrev_b64 v[70:71], 11, v[70:71]
	v_lshl_add_u64 v[70:71], v[70:71], 0, v[100:101]
	v_lshlrev_b64 v[74:75], 2, v[70:71]
	v_lshl_add_u64 v[70:71], s[20:21], 0, v[74:75]
	global_load_dwordx4 v[70:73], v[70:71], off
	ds_read_b128 v[66:69], v96 offset:2176
	v_mfma_f32_16x16x32_bf16 v[4:7], v[152:155], v[132:135], v[4:7]
	s_waitcnt vmcnt(0) lgkmcnt(0)
; DEV void store_tile_f32_add(const f32x4 (&acc)[8][4], const float* xres, float* out, int m0, int n0, unsigned char* smem) {
;     ...
; #pragma unroll
;   for (int mq = 0; mq < 4; ++mq) {
; #pragma unroll
;     for (int mh = 0; mh < 2; ++mh)
; #pragma unroll
;       for (int ni = 0; ni < 4; ++ni)
; #pragma unroll
;         for (int j = 0; j < 4; ++j) st[(mh * 16 + fq * 4 + j) * 68 + ni * 16 + fr] = acc[mq * 2 + mh][ni][j];
; #pragma unroll
;     for (int itr = 0; itr < 8; ++itr) {
;       const int rl = (lane >> 4) + 4 * itr;
;       const f32x4 v = *(const f32x4*)(st + rl * 68 + chunk * 4);
;       const size_t idx = (size_t)(m0 + wr * 128 + mq * 32 + rl) * 2048 + n0 + wc * 64 + chunk * 4;
;       const f32x4 x = *(const f32x4*)(xres + idx);
;       *(f32x4*)(out + idx) = x + v;
;     }
	v_pk_add_f32 v[68:69], v[68:69], v[72:73]
	v_pk_add_f32 v[66:67], v[66:67], v[70:71]
	v_lshl_add_u64 v[70:71], s[6:7], 0, v[74:75]
	global_store_dwordx4 v[70:71], v[66:69], off
	v_or_b32_e32 v70, v64, v99
	v_ashrrev_i32_e32 v71, 31, v70
	v_lshlrev_b64 v[70:71], 11, v[70:71]
	v_lshl_add_u64 v[70:71], v[70:71], 0, v[100:101]
	v_lshlrev_b64 v[74:75], 2, v[70:71]
	v_lshl_add_u64 v[70:71], s[20:21], 0, v[74:75]
	global_load_dwordx4 v[70:73], v[70:71], off
	ds_read_b128 v[66:69], v96 offset:3264
	s_waitcnt vmcnt(0) lgkmcnt(0)
	v_pk_add_f32 v[68:69], v[68:69], v[72:73]
	v_pk_add_f32 v[66:67], v[66:67], v[70:71]
	v_lshl_add_u64 v[70:71], s[6:7], 0, v[74:75]
	global_store_dwordx4 v[70:71], v[66:69], off
	v_or_b32_e32 v70, v64, v105
	v_ashrrev_i32_e32 v71, 31, v70
	v_lshlrev_b64 v[70:71], 11, v[70:71]
	v_lshl_add_u64 v[70:71], v[70:71], 0, v[100:101]
	v_lshlrev_b64 v[74:75], 2, v[70:71]
	v_lshl_add_u64 v[70:71], s[20:21], 0, v[74:75]
	global_load_dwordx4 v[70:73], v[70:71], off
	ds_read_b128 v[66:69], v96 offset:4352
	s_waitcnt vmcnt(0) lgkmcnt(0)
	v_pk_add_f32 v[68:69], v[68:69], v[72:73]
	v_pk_add_f32 v[66:67], v[66:67], v[70:71]
	v_lshl_add_u64 v[70:71], s[6:7], 0, v[74:75]
	global_store_dwordx4 v[70:71], v[66:69], off
	v_or_b32_e32 v70, v64, v107
	v_ashrrev_i32_e32 v71, 31, v70
	v_lshlrev_b64 v[70:71], 11, v[70:71]
	v_lshl_add_u64 v[70:71], v[70:71], 0, v[100:101]
	v_lshlrev_b64 v[74:75], 2, v[70:71]
	v_lshl_add_u64 v[70:71], s[20:21], 0, v[74:75]
	global_load_dwordx4 v[70:73], v[70:71], off
	ds_read_b128 v[66:69], v96 offset:5440
	v_or_b32_e32 v64, v64, v108
	v_ashrrev_i32_e32 v65, 31, v64
	v_lshlrev_b64 v[64:65], 11, v[64:65]
	v_lshl_add_u64 v[64:65], v[64:65], 0, v[100:101]
	v_lshlrev_b64 v[64:65], 2, v[64:65]
	s_waitcnt vmcnt(0) lgkmcnt(0)
	v_pk_add_f32 v[68:69], v[68:69], v[72:73]
	v_pk_add_f32 v[66:67], v[66:67], v[70:71]
	v_lshl_add_u64 v[70:71], s[6:7], 0, v[74:75]
	global_store_dwordx4 v[70:71], v[66:69], off
	v_lshl_add_u64 v[70:71], s[20:21], 0, v[64:65]
	global_load_dwordx4 v[70:73], v[70:71], off
	ds_read_b128 v[66:69], v96 offset:6528
	v_lshl_add_u64 v[64:65], s[6:7], 0, v[64:65]
	s_waitcnt vmcnt(0) lgkmcnt(0)
	v_pk_add_f32 v[68:69], v[68:69], v[72:73]
	v_pk_add_f32 v[66:67], v[66:67], v[70:71]
	global_store_dwordx4 v[64:65], v[66:69], off
	ds_write_b32 v106, v60
	ds_write_b32 v106, v61 offset:272
	ds_write_b32 v106, v62 offset:544
	ds_write_b32 v106, v63 offset:816
	ds_write_b32 v106, v56 offset:64
	ds_write_b32 v106, v57 offset:336
	ds_write_b32 v106, v58 offset:608
	ds_write_b32 v106, v59 offset:880
	ds_write_b32 v106, v52 offset:128
	ds_write_b32 v106, v53 offset:400
	ds_write_b32 v106, v54 offset:672
	ds_write_b32 v106, v55 offset:944
	ds_write_b32 v106, v48 offset:192
	ds_write_b32 v106, v49 offset:464
	ds_write_b32 v106, v50 offset:736
	ds_write_b32 v106, v51 offset:1008
	ds_write_b32 v106, v44 offset:4352
	ds_write_b32 v106, v45 offset:4624
	ds_write_b32 v106, v46 offset:4896
	ds_write_b32 v106, v47 offset:5168
	ds_write_b32 v106, v40 offset:4416
	ds_write_b32 v106, v41 offset:4688
	ds_write_b32 v106, v42 offset:4960
	ds_write_b32 v106, v43 offset:5232
	ds_write_b32 v106, v36 offset:4480
	ds_write_b32 v106, v37 offset:4752
	ds_write_b32 v106, v38 offset:5024
	ds_write_b32 v106, v39 offset:5296
	ds_write_b32 v106, v32 offset:4544
	ds_write_b32 v106, v33 offset:4816
	ds_write_b32 v106, v34 offset:5088
	ds_write_b32 v106, v35 offset:5360
	v_or_b32_e32 v32, 64, v103
	v_or_b32_e32 v38, v32, v102
	v_ashrrev_i32_e32 v39, 31, v38
	v_lshlrev_b64 v[38:39], 11, v[38:39]
	v_lshl_add_u64 v[38:39], v[38:39], 0, v[100:101]
	v_lshlrev_b64 v[42:43], 2, v[38:39]
	v_lshl_add_u64 v[38:39], s[20:21], 0, v[42:43]
	global_load_dwordx4 v[38:41], v[38:39], off
	ds_read_b128 v[34:37], v104
	s_waitcnt vmcnt(0) lgkmcnt(0)
	v_pk_add_f32 v[36:37], v[36:37], v[40:41]
	v_pk_add_f32 v[34:35], v[34:35], v[38:39]
	v_lshl_add_u64 v[38:39], s[6:7], 0, v[42:43]
	global_store_dwordx4 v[38:39], v[34:37], off
	v_or_b32_e32 v38, v32, v109
	v_ashrrev_i32_e32 v39, 31, v38
	v_lshlrev_b64 v[38:39], 11, v[38:39]
	v_lshl_add_u64 v[38:39], v[38:39], 0, v[100:101]
	v_lshlrev_b64 v[42:43], 2, v[38:39]
	v_lshl_add_u64 v[38:39], s[20:21], 0, v[42:43]
	global_load_dwordx4 v[38:41], v[38:39], off
	ds_read_b128 v[34:37], v96
	s_waitcnt vmcnt(0) lgkmcnt(0)
	v_pk_add_f32 v[36:37], v[36:37], v[40:41]
	v_pk_add_f32 v[34:35], v[34:35], v[38:39]
	v_lshl_add_u64 v[38:39], s[6:7], 0, v[42:43]
	global_store_dwordx4 v[38:39], v[34:37], off
	v_or_b32_e32 v38, v32, v97
	v_ashrrev_i32_e32 v39, 31, v38
	v_lshlrev_b64 v[38:39], 11, v[38:39]
	v_lshl_add_u64 v[38:39], v[38:39], 0, v[100:101]
	v_lshlrev_b64 v[42:43], 2, v[38:39]
	v_lshl_add_u64 v[38:39], s[20:21], 0, v[42:43]
	global_load_dwordx4 v[38:41], v[38:39], off
	ds_read_b128 v[34:37], v96 offset:1088
	s_waitcnt vmcnt(0) lgkmcnt(0)
	v_pk_add_f32 v[36:37], v[36:37], v[40:41]
	v_pk_add_f32 v[34:35], v[34:35], v[38:39]
	v_lshl_add_u64 v[38:39], s[6:7], 0, v[42:43]
	global_store_dwordx4 v[38:39], v[34:37], off
	v_or_b32_e32 v38, v32, v98
	v_ashrrev_i32_e32 v39, 31, v38
	v_lshlrev_b64 v[38:39], 11, v[38:39]
	v_lshl_add_u64 v[38:39], v[38:39], 0, v[100:101]
	v_lshlrev_b64 v[42:43], 2, v[38:39]
	v_lshl_add_u64 v[38:39], s[20:21], 0, v[42:43]
	global_load_dwordx4 v[38:41], v[38:39], off
	ds_read_b128 v[34:37], v96 offset:2176
	s_waitcnt vmcnt(0) lgkmcnt(0)
	v_pk_add_f32 v[36:37], v[36:37], v[40:41]
	v_pk_add_f32 v[34:35], v[34:35], v[38:39]
	v_lshl_add_u64 v[38:39], s[6:7], 0, v[42:43]
	global_store_dwordx4 v[38:39], v[34:37], off
	v_or_b32_e32 v38, v32, v99
	v_ashrrev_i32_e32 v39, 31, v38
	v_lshlrev_b64 v[38:39], 11, v[38:39]
	v_lshl_add_u64 v[38:39], v[38:39], 0, v[100:101]
	v_lshlrev_b64 v[42:43], 2, v[38:39]
	v_lshl_add_u64 v[38:39], s[20:21], 0, v[42:43]
	global_load_dwordx4 v[38:41], v[38:39], off
	ds_read_b128 v[34:37], v96 offset:3264
	s_waitcnt vmcnt(0) lgkmcnt(0)
; DEV void store_tile_f32_add(const f32x4 (&acc)[8][4], const float* xres, float* out, int m0, int n0, unsigned char* smem) {
;     ...
; #pragma unroll
;   for (int mq = 0; mq < 4; ++mq) {
; #pragma unroll
;     for (int mh = 0; mh < 2; ++mh)
; #pragma unroll
;       for (int ni = 0; ni < 4; ++ni)
; #pragma unroll
;         for (int j = 0; j < 4; ++j) st[(mh * 16 + fq * 4 + j) * 68 + ni * 16 + fr] = acc[mq * 2 + mh][ni][j];
; #pragma unroll
;     for (int itr = 0; itr < 8; ++itr) {
;       const int rl = (lane >> 4) + 4 * itr;
;       const f32x4 v = *(const f32x4*)(st + rl * 68 + chunk * 4);
;       const size_t idx = (size_t)(m0 + wr * 128 + mq * 32 + rl) * 2048 + n0 + wc * 64 + chunk * 4;
;       const f32x4 x = *(const f32x4*)(xres + idx);
;       *(f32x4*)(out + idx) = x + v;
;     }
	v_pk_add_f32 v[36:37], v[36:37], v[40:41]
	v_pk_add_f32 v[34:35], v[34:35], v[38:39]
	v_lshl_add_u64 v[38:39], s[6:7], 0, v[42:43]
	global_store_dwordx4 v[38:39], v[34:37], off
	v_or_b32_e32 v38, v32, v105
	v_ashrrev_i32_e32 v39, 31, v38
	v_lshlrev_b64 v[38:39], 11, v[38:39]
	v_lshl_add_u64 v[38:39], v[38:39], 0, v[100:101]
	v_lshlrev_b64 v[42:43], 2, v[38:39]
	v_lshl_add_u64 v[38:39], s[20:21], 0, v[42:43]
	global_load_dwordx4 v[38:41], v[38:39], off
	ds_read_b128 v[34:37], v96 offset:4352
	s_waitcnt vmcnt(0) lgkmcnt(0)
	v_pk_add_f32 v[36:37], v[36:37], v[40:41]
	v_pk_add_f32 v[34:35], v[34:35], v[38:39]
	v_lshl_add_u64 v[38:39], s[6:7], 0, v[42:43]
	global_store_dwordx4 v[38:39], v[34:37], off
	v_or_b32_e32 v38, v32, v107
	v_ashrrev_i32_e32 v39, 31, v38
	v_lshlrev_b64 v[38:39], 11, v[38:39]
	v_lshl_add_u64 v[38:39], v[38:39], 0, v[100:101]
	v_lshlrev_b64 v[42:43], 2, v[38:39]
	v_lshl_add_u64 v[38:39], s[20:21], 0, v[42:43]
	global_load_dwordx4 v[38:41], v[38:39], off
	ds_read_b128 v[34:37], v96 offset:5440
	v_or_b32_e32 v32, v32, v108
	v_ashrrev_i32_e32 v33, 31, v32
	v_lshlrev_b64 v[32:33], 11, v[32:33]
	v_lshl_add_u64 v[32:33], v[32:33], 0, v[100:101]
	v_lshlrev_b64 v[32:33], 2, v[32:33]
	s_waitcnt vmcnt(0) lgkmcnt(0)
	v_pk_add_f32 v[36:37], v[36:37], v[40:41]
	v_pk_add_f32 v[34:35], v[34:35], v[38:39]
	v_lshl_add_u64 v[38:39], s[6:7], 0, v[42:43]
	global_store_dwordx4 v[38:39], v[34:37], off
	v_lshl_add_u64 v[38:39], s[20:21], 0, v[32:33]
	global_load_dwordx4 v[38:41], v[38:39], off
	ds_read_b128 v[34:37], v96 offset:6528
	v_lshl_add_u64 v[32:33], s[6:7], 0, v[32:33]
	s_waitcnt vmcnt(0) lgkmcnt(0)
	v_pk_add_f32 v[36:37], v[36:37], v[40:41]
	v_pk_add_f32 v[34:35], v[34:35], v[38:39]
	global_store_dwordx4 v[32:33], v[34:37], off
	ds_write_b32 v106, v28
	ds_write_b32 v106, v29 offset:272
	ds_write_b32 v106, v30 offset:544
	ds_write_b32 v106, v31 offset:816
	ds_write_b32 v106, v24 offset:64
	ds_write_b32 v106, v25 offset:336
	ds_write_b32 v106, v26 offset:608
	ds_write_b32 v106, v27 offset:880
	ds_write_b32 v106, v20 offset:128
	ds_write_b32 v106, v21 offset:400
	ds_write_b32 v106, v22 offset:672
	ds_write_b32 v106, v23 offset:944
	ds_write_b32 v106, v16 offset:192
	ds_write_b32 v106, v17 offset:464
	ds_write_b32 v106, v18 offset:736
	ds_write_b32 v106, v19 offset:1008
	ds_write_b32 v106, v12 offset:4352
	ds_write_b32 v106, v13 offset:4624
	ds_write_b32 v106, v14 offset:4896
	ds_write_b32 v106, v15 offset:5168
	ds_write_b32 v106, v8 offset:4416
	ds_write_b32 v106, v9 offset:4688
	ds_write_b32 v106, v10 offset:4960
	ds_write_b32 v106, v11 offset:5232
	ds_write_b32 v106, v4 offset:4480
	ds_write_b32 v106, v5 offset:4752
	ds_write_b32 v106, v6 offset:5024
	ds_write_b32 v106, v7 offset:5296
	ds_write_b32 v106, v0 offset:4544
	ds_write_b32 v106, v1 offset:4816
	ds_write_b32 v106, v2 offset:5088
	ds_write_b32 v106, v3 offset:5360
	v_or_b32_e32 v0, 0x60, v103
	v_or_b32_e32 v6, v0, v102
	v_ashrrev_i32_e32 v7, 31, v6
	v_lshlrev_b64 v[6:7], 11, v[6:7]
	v_lshl_add_u64 v[6:7], v[6:7], 0, v[100:101]
	v_lshlrev_b64 v[10:11], 2, v[6:7]
	v_lshl_add_u64 v[6:7], s[20:21], 0, v[10:11]
	global_load_dwordx4 v[6:9], v[6:7], off
	ds_read_b128 v[2:5], v104
	s_waitcnt vmcnt(0) lgkmcnt(0)
	v_pk_add_f32 v[4:5], v[4:5], v[8:9]
	v_pk_add_f32 v[2:3], v[2:3], v[6:7]
	v_lshl_add_u64 v[6:7], s[6:7], 0, v[10:11]
	global_store_dwordx4 v[6:7], v[2:5], off
	v_or_b32_e32 v6, v0, v109
	v_ashrrev_i32_e32 v7, 31, v6
	v_lshlrev_b64 v[6:7], 11, v[6:7]
	v_lshl_add_u64 v[6:7], v[6:7], 0, v[100:101]
	v_lshlrev_b64 v[10:11], 2, v[6:7]
	v_lshl_add_u64 v[6:7], s[20:21], 0, v[10:11]
	global_load_dwordx4 v[6:9], v[6:7], off
	ds_read_b128 v[2:5], v96
	s_waitcnt vmcnt(0) lgkmcnt(0)
	v_pk_add_f32 v[4:5], v[4:5], v[8:9]
	v_pk_add_f32 v[2:3], v[2:3], v[6:7]
	v_lshl_add_u64 v[6:7], s[6:7], 0, v[10:11]
	global_store_dwordx4 v[6:7], v[2:5], off
	v_or_b32_e32 v6, v0, v97
	v_ashrrev_i32_e32 v7, 31, v6
	v_lshlrev_b64 v[6:7], 11, v[6:7]
	v_lshl_add_u64 v[6:7], v[6:7], 0, v[100:101]
	v_lshlrev_b64 v[10:11], 2, v[6:7]
	v_lshl_add_u64 v[6:7], s[20:21], 0, v[10:11]
	global_load_dwordx4 v[6:9], v[6:7], off
	ds_read_b128 v[2:5], v96 offset:1088
	s_waitcnt vmcnt(0) lgkmcnt(0)
	v_pk_add_f32 v[4:5], v[4:5], v[8:9]
	v_pk_add_f32 v[2:3], v[2:3], v[6:7]
	v_lshl_add_u64 v[6:7], s[6:7], 0, v[10:11]
	global_store_dwordx4 v[6:7], v[2:5], off
	v_or_b32_e32 v6, v0, v98
	v_ashrrev_i32_e32 v7, 31, v6
	v_lshlrev_b64 v[6:7], 11, v[6:7]
	v_lshl_add_u64 v[6:7], v[6:7], 0, v[100:101]
	v_lshlrev_b64 v[10:11], 2, v[6:7]
	v_lshl_add_u64 v[6:7], s[20:21], 0, v[10:11]
	global_load_dwordx4 v[6:9], v[6:7], off
	ds_read_b128 v[2:5], v96 offset:2176
	s_waitcnt vmcnt(0) lgkmcnt(0)
	v_pk_add_f32 v[4:5], v[4:5], v[8:9]
	v_pk_add_f32 v[2:3], v[2:3], v[6:7]
	v_lshl_add_u64 v[6:7], s[6:7], 0, v[10:11]
	global_store_dwordx4 v[6:7], v[2:5], off
	v_or_b32_e32 v6, v0, v99
	v_ashrrev_i32_e32 v7, 31, v6
	v_lshlrev_b64 v[6:7], 11, v[6:7]
	v_lshl_add_u64 v[6:7], v[6:7], 0, v[100:101]
	v_lshlrev_b64 v[10:11], 2, v[6:7]
	v_lshl_add_u64 v[6:7], s[20:21], 0, v[10:11]
	global_load_dwordx4 v[6:9], v[6:7], off
	ds_read_b128 v[2:5], v96 offset:3264
	s_waitcnt vmcnt(0) lgkmcnt(0)
	v_pk_add_f32 v[4:5], v[4:5], v[8:9]
	v_pk_add_f32 v[2:3], v[2:3], v[6:7]
	v_lshl_add_u64 v[6:7], s[6:7], 0, v[10:11]
	global_store_dwordx4 v[6:7], v[2:5], off
	v_or_b32_e32 v6, v0, v105
	v_ashrrev_i32_e32 v7, 31, v6
	v_lshlrev_b64 v[6:7], 11, v[6:7]
	v_lshl_add_u64 v[6:7], v[6:7], 0, v[100:101]
	v_lshlrev_b64 v[10:11], 2, v[6:7]
	v_lshl_add_u64 v[6:7], s[20:21], 0, v[10:11]
	global_load_dwordx4 v[6:9], v[6:7], off
	ds_read_b128 v[2:5], v96 offset:4352
	s_waitcnt vmcnt(0) lgkmcnt(0)
	v_pk_add_f32 v[4:5], v[4:5], v[8:9]
	v_pk_add_f32 v[2:3], v[2:3], v[6:7]
	v_lshl_add_u64 v[6:7], s[6:7], 0, v[10:11]
	global_store_dwordx4 v[6:7], v[2:5], off
	v_or_b32_e32 v6, v0, v107
	v_ashrrev_i32_e32 v7, 31, v6
	v_lshlrev_b64 v[6:7], 11, v[6:7]
	v_lshl_add_u64 v[6:7], v[6:7], 0, v[100:101]
	v_lshlrev_b64 v[10:11], 2, v[6:7]
	v_lshl_add_u64 v[6:7], s[20:21], 0, v[10:11]
	global_load_dwordx4 v[6:9], v[6:7], off
	ds_read_b128 v[2:5], v96 offset:5440
	v_or_b32_e32 v0, v0, v108
	v_ashrrev_i32_e32 v1, 31, v0
	v_lshlrev_b64 v[0:1], 11, v[0:1]
	v_lshl_add_u64 v[0:1], v[0:1], 0, v[100:101]
	v_lshlrev_b64 v[0:1], 2, v[0:1]
	s_waitcnt vmcnt(0) lgkmcnt(0)
	v_pk_add_f32 v[4:5], v[4:5], v[8:9]
	v_pk_add_f32 v[2:3], v[2:3], v[6:7]
	v_lshl_add_u64 v[6:7], s[6:7], 0, v[10:11]
	global_store_dwordx4 v[6:7], v[2:5], off
	v_lshl_add_u64 v[6:7], s[20:21], 0, v[0:1]
	global_load_dwordx4 v[6:9], v[6:7], off
	ds_read_b128 v[2:5], v96 offset:6528
	v_lshl_add_u64 v[0:1], s[6:7], 0, v[0:1]
	s_waitcnt vmcnt(0) lgkmcnt(0)
	v_pk_add_f32 v[4:5], v[4:5], v[8:9]
	v_pk_add_f32 v[2:3], v[2:3], v[6:7]
	global_store_dwordx4 v[0:1], v[2:5], off
	s_branch .LBB0_244

; DEV f32x4 mfma16(bf16x8 a, bf16x8 b, f32x4 c) { return __builtin_amdgcn_mfma_f32_16x16x32_bf16(a, b, c, 0, 0, 0); }
; DEV void gemm_tile(const u16* __restrict__ A, size_t lda, const u16* __restrict__ Bt, size_t ldb, int K,
;                    u16* sA, u16* sB, f32x4 (&acc)[8][4]) {
;     ...
;   for (int kt = 0; kt < nk; ++kt) {
;     const int st = kt & 1;
;     if (kt + 1 < nk) S_STORE(st ^ 1)
;     if (kt + 2 < nk) G_LOAD((kt + 2) << 5)
;     {
;       const u16* pa = sAr + st * 12288;
;       const u16* pb = sBr + st * 12288;
;       bf16x8 b[4];
; #pragma unroll
;       for (int ni = 0; ni < 4; ++ni) b[ni] = *(const bf16x8*)(pb + ni * 16 * 32);
; #pragma unroll
;       for (int mh = 0; mh < 2; ++mh) {
;         bf16x8 a[4];
; #pragma unroll
;         for (int mi = 0; mi < 4; ++mi) a[mi] = *(const bf16x8*)(pa + (mh * 64 + mi * 16) * 32);
; #pragma unroll
;         for (int mi = 0; mi < 4; ++mi)
; #pragma unroll
;           for (int ni = 0; ni < 4; ++ni) acc[mh * 4 + mi][ni] = mfma16(a[mi], b[ni], acc[mh * 4 + mi][ni]);
;       }
;     }
;     __syncthreads();
;   }
.LBB0_414:
	v_add_u32_e32 v229, s8, v163
	v_add_u32_e32 v228, s8, v162
	ds_read_b128 v[116:119], v229 offset:16384
	ds_read_b128 v[166:169], v228
	ds_read_b128 v[128:131], v229 offset:17408
	ds_read_b128 v[140:143], v229 offset:18432
	ds_read_b128 v[120:123], v229 offset:19456
	ds_read_b128 v[152:155], v228 offset:1024
	ds_read_b128 v[170:173], v228 offset:2048
	ds_read_b128 v[132:135], v228 offset:3072
	s_waitcnt lgkmcnt(6)
	v_mfma_f32_16x16x32_bf16 v[148:151], v[166:169], v[116:119], v[148:151]
	s_waitcnt lgkmcnt(5)
	v_mfma_f32_16x16x32_bf16 v[144:147], v[166:169], v[128:131], v[144:147]
	s_waitcnt lgkmcnt(4)
	v_mfma_f32_16x16x32_bf16 v[124:127], v[166:169], v[140:143], v[124:127]
	s_waitcnt lgkmcnt(3)
	v_mfma_f32_16x16x32_bf16 v[112:115], v[166:169], v[120:123], v[112:115]
	ds_read_b128 v[232:235], v228 offset:4096
	ds_read_b128 v[236:239], v228 offset:5120
	s_waitcnt lgkmcnt(4)
	v_mfma_f32_16x16x32_bf16 v[108:111], v[152:155], v[116:119], v[108:111]
	s_add_i32 m0, s9, 0x0
	v_mfma_f32_16x16x32_bf16 v[104:107], v[152:155], v[128:131], v[104:107]
	global_load_lds_dwordx4 v[136:137], off
	v_lshl_add_u64 v[136:137], v[136:137], 0, 64
	global_load_dwordx4 v[244:247], v[136:137], off
	v_lshl_add_u64 v[136:137], v[136:137], 0, 64
	v_mfma_f32_16x16x32_bf16 v[100:103], v[152:155], v[140:143], v[100:103]
	s_add_i32 m0, s9, 0x1000
	v_mfma_f32_16x16x32_bf16 v[96:99], v[152:155], v[120:123], v[96:99]
	global_load_lds_dwordx4 v[138:139], off
	v_lshl_add_u64 v[138:139], v[138:139], 0, 64
	global_load_dwordx4 v[252:255], v[138:139], off
	v_lshl_add_u64 v[138:139], v[138:139], 0, 64
	s_waitcnt lgkmcnt(3)
	v_mfma_f32_16x16x32_bf16 v[92:95], v[170:173], v[116:119], v[92:95]
	s_add_i32 m0, s9, 0x2000
	v_mfma_f32_16x16x32_bf16 v[88:91], v[170:173], v[128:131], v[88:91]
	global_load_lds_dwordx4 v[174:175], off
	v_lshl_add_u64 v[174:175], v[174:175], 0, 64
	global_load_dwordx4 v[208:211], v[174:175], off
	v_lshl_add_u64 v[174:175], v[174:175], 0, 64
	v_mfma_f32_16x16x32_bf16 v[84:87], v[170:173], v[140:143], v[84:87]
	s_add_i32 m0, s9, 0x3000
	v_mfma_f32_16x16x32_bf16 v[80:83], v[170:173], v[120:123], v[80:83]
	ds_read_b128 v[240:243], v228 offset:6144
	ds_read_b128 v[166:169], v228 offset:7168
	s_waitcnt lgkmcnt(4)
	v_mfma_f32_16x16x32_bf16 v[76:79], v[132:135], v[116:119], v[76:79]
	global_load_lds_dwordx4 v[176:177], off
	v_lshl_add_u64 v[176:177], v[176:177], 0, 64
	global_load_dwordx4 v[212:215], v[176:177], off
	v_lshl_add_u64 v[176:177], v[176:177], 0, 64
	v_mfma_f32_16x16x32_bf16 v[72:75], v[132:135], v[128:131], v[72:75]
	s_add_i32 m0, s9, 0x4000
	v_mfma_f32_16x16x32_bf16 v[68:71], v[132:135], v[140:143], v[68:71]
	global_load_lds_dwordx4 v[186:187], off
	v_lshl_add_u64 v[186:187], v[186:187], 0, 64
	global_load_dwordx4 v[216:219], v[186:187], off
	v_lshl_add_u64 v[186:187], v[186:187], 0, 64
	v_mfma_f32_16x16x32_bf16 v[64:67], v[132:135], v[120:123], v[64:67]
	s_add_i32 m0, s9, 0x5000
	s_waitcnt lgkmcnt(3)
	v_mfma_f32_16x16x32_bf16 v[60:63], v[232:235], v[116:119], v[60:63]
	global_load_lds_dwordx4 v[188:189], off
	v_lshl_add_u64 v[188:189], v[188:189], 0, 64
	global_load_dwordx4 v[220:223], v[188:189], off
	v_lshl_add_u64 v[188:189], v[188:189], 0, 64
	v_mfma_f32_16x16x32_bf16 v[56:59], v[232:235], v[128:131], v[56:59]
	s_add_i32 s9, s8, s5
	s_add_i32 s8, s8, 0x6000
	v_mfma_f32_16x16x32_bf16 v[52:55], v[232:235], v[140:143], v[52:55]
	s_cmp_eq_u32 s8, 0x12000
	s_cselect_b32 s8, 0, s8
	v_mfma_f32_16x16x32_bf16 v[48:51], v[232:235], v[120:123], v[48:51]
	s_add_u32 s6, s6, 64
	s_addc_u32 s7, s7, 0
	s_cmpk_lg_i32 s6, 0xf80
	s_waitcnt lgkmcnt(2)
	v_mfma_f32_16x16x32_bf16 v[44:47], v[236:239], v[116:119], v[44:47]
	v_mfma_f32_16x16x32_bf16 v[40:43], v[236:239], v[128:131], v[40:43]
	v_mfma_f32_16x16x32_bf16 v[36:39], v[236:239], v[140:143], v[36:39]
	v_mfma_f32_16x16x32_bf16 v[32:35], v[236:239], v[120:123], v[32:35]
	s_waitcnt lgkmcnt(1)
	v_mfma_f32_16x16x32_bf16 v[28:31], v[240:243], v[116:119], v[28:31]
	v_mfma_f32_16x16x32_bf16 v[24:27], v[240:243], v[128:131], v[24:27]
	v_mfma_f32_16x16x32_bf16 v[20:23], v[240:243], v[140:143], v[20:23]
	v_mfma_f32_16x16x32_bf16 v[16:19], v[240:243], v[120:123], v[16:19]
	s_waitcnt lgkmcnt(0)
	s_waitcnt vmcnt(12)
	s_barrier
	v_mfma_f32_16x16x32_bf16 v[12:15], v[166:169], v[116:119], v[12:15]
	v_mfma_f32_16x16x32_bf16 v[8:11], v[166:169], v[128:131], v[8:11]
	v_mfma_f32_16x16x32_bf16 v[4:7], v[166:169], v[140:143], v[4:7]
	v_mfma_f32_16x16x32_bf16 v[0:3], v[166:169], v[120:123], v[0:3]
	v_add_u32_e32 v229, s8, v163
	v_add_u32_e32 v228, s8, v162
	ds_read_b128 v[116:119], v229 offset:16384
	ds_read_b128 v[166:169], v228
	ds_read_b128 v[128:131], v229 offset:17408
	ds_read_b128 v[140:143], v229 offset:18432
	ds_read_b128 v[120:123], v229 offset:19456
	ds_read_b128 v[152:155], v228 offset:1024
	ds_read_b128 v[170:173], v228 offset:2048
	ds_read_b128 v[132:135], v228 offset:3072
	s_waitcnt lgkmcnt(6)
	v_mfma_f32_16x16x32_bf16 v[148:151], v[166:169], v[116:119], v[148:151]
	s_waitcnt lgkmcnt(5)
	v_mfma_f32_16x16x32_bf16 v[144:147], v[166:169], v[128:131], v[144:147]
	s_waitcnt lgkmcnt(4)
	v_mfma_f32_16x16x32_bf16 v[124:127], v[166:169], v[140:143], v[124:127]
	s_waitcnt lgkmcnt(3)
	v_mfma_f32_16x16x32_bf16 v[112:115], v[166:169], v[120:123], v[112:115]
	ds_read_b128 v[232:235], v228 offset:4096
	ds_read_b128 v[236:239], v228 offset:5120
	s_waitcnt lgkmcnt(4)
	v_mfma_f32_16x16x32_bf16 v[108:111], v[152:155], v[116:119], v[108:111]
	v_mfma_f32_16x16x32_bf16 v[104:107], v[152:155], v[128:131], v[104:107]
	v_mfma_f32_16x16x32_bf16 v[100:103], v[152:155], v[140:143], v[100:103]
	v_mfma_f32_16x16x32_bf16 v[96:99], v[152:155], v[120:123], v[96:99]
	s_waitcnt lgkmcnt(3)
; DEV f32x4 mfma16(bf16x8 a, bf16x8 b, f32x4 c) { return __builtin_amdgcn_mfma_f32_16x16x32_bf16(a, b, c, 0, 0, 0); }
; DEV void gemm_tile(const u16* __restrict__ A, size_t lda, const u16* __restrict__ Bt, size_t ldb, int K,
;                    u16* sA, u16* sB, f32x4 (&acc)[8][4]) {
;     ...
;   for (int kt = 0; kt < nk; ++kt) {
;     const int st = kt & 1;
;     if (kt + 1 < nk) S_STORE(st ^ 1)
;     if (kt + 2 < nk) G_LOAD((kt + 2) << 5)
;     {
;       const u16* pa = sAr + st * 12288;
;       const u16* pb = sBr + st * 12288;
;       bf16x8 b[4];
; #pragma unroll
;       for (int ni = 0; ni < 4; ++ni) b[ni] = *(const bf16x8*)(pb + ni * 16 * 32);
; #pragma unroll
;       for (int mh = 0; mh < 2; ++mh) {
;         bf16x8 a[4];
; #pragma unroll
;         for (int mi = 0; mi < 4; ++mi) a[mi] = *(const bf16x8*)(pa + (mh * 64 + mi * 16) * 32);
; #pragma unroll
;         for (int mi = 0; mi < 4; ++mi)
; #pragma unroll
;           for (int ni = 0; ni < 4; ++ni) acc[mh * 4 + mi][ni] = mfma16(a[mi], b[ni], acc[mh * 4 + mi][ni]);
;       }
;     }
;     __syncthreads();
;   }
	v_mfma_f32_16x16x32_bf16 v[92:95], v[170:173], v[116:119], v[92:95]
	v_mfma_f32_16x16x32_bf16 v[88:91], v[170:173], v[128:131], v[88:91]
	v_mfma_f32_16x16x32_bf16 v[84:87], v[170:173], v[140:143], v[84:87]
	v_mfma_f32_16x16x32_bf16 v[80:83], v[170:173], v[120:123], v[80:83]
	ds_read_b128 v[240:243], v228 offset:6144
	ds_read_b128 v[166:169], v228 offset:7168
	s_waitcnt lgkmcnt(4)
	v_mfma_f32_16x16x32_bf16 v[76:79], v[132:135], v[116:119], v[76:79]
	s_waitcnt vmcnt(0)
	v_add_u32_e32 v231, s9, v230
	v_mfma_f32_16x16x32_bf16 v[72:75], v[132:135], v[128:131], v[72:75]
	ds_write_b128 v231, v[244:247]
	v_mfma_f32_16x16x32_bf16 v[68:71], v[132:135], v[140:143], v[68:71]
	ds_write_b128 v231, v[252:255] offset:4096
	v_mfma_f32_16x16x32_bf16 v[64:67], v[132:135], v[120:123], v[64:67]
	ds_write_b128 v231, v[208:211] offset:8192
	s_waitcnt lgkmcnt(6)
	v_mfma_f32_16x16x32_bf16 v[60:63], v[232:235], v[116:119], v[60:63]
	ds_write_b128 v231, v[212:215] offset:12288
	v_mfma_f32_16x16x32_bf16 v[56:59], v[232:235], v[128:131], v[56:59]
	ds_write_b128 v231, v[216:219] offset:16384
	v_mfma_f32_16x16x32_bf16 v[52:55], v[232:235], v[140:143], v[52:55]
	ds_write_b128 v231, v[220:223] offset:20480
	v_mfma_f32_16x16x32_bf16 v[48:51], v[232:235], v[120:123], v[48:51]
	s_add_i32 s9, s8, s5
	s_add_i32 s8, s8, 0x6000
	s_waitcnt lgkmcnt(8)
	v_mfma_f32_16x16x32_bf16 v[44:47], v[236:239], v[116:119], v[44:47]
	s_cmp_eq_u32 s8, 0x12000
	s_cselect_b32 s8, 0, s8
	v_mfma_f32_16x16x32_bf16 v[40:43], v[236:239], v[128:131], v[40:43]
	s_add_u32 s6, s6, 64
	s_addc_u32 s7, s7, 0
	s_cmpk_lg_i32 s6, 0xf80
	v_mfma_f32_16x16x32_bf16 v[36:39], v[236:239], v[140:143], v[36:39]
	v_mfma_f32_16x16x32_bf16 v[32:35], v[236:239], v[120:123], v[32:35]
	s_waitcnt lgkmcnt(7)
	v_mfma_f32_16x16x32_bf16 v[28:31], v[240:243], v[116:119], v[28:31]
	v_mfma_f32_16x16x32_bf16 v[24:27], v[240:243], v[128:131], v[24:27]
	v_mfma_f32_16x16x32_bf16 v[20:23], v[240:243], v[140:143], v[20:23]
	v_mfma_f32_16x16x32_bf16 v[16:19], v[240:243], v[120:123], v[16:19]
	s_waitcnt lgkmcnt(6)
	s_waitcnt lgkmcnt(0)
	s_barrier
	v_mfma_f32_16x16x32_bf16 v[12:15], v[166:169], v[116:119], v[12:15]
	v_mfma_f32_16x16x32_bf16 v[8:11], v[166:169], v[128:131], v[8:11]
	v_mfma_f32_16x16x32_bf16 v[4:7], v[166:169], v[140:143], v[4:7]
	v_mfma_f32_16x16x32_bf16 v[0:3], v[166:169], v[120:123], v[0:3]
	s_cbranch_scc1 .LBB0_414
	ds_read_b128 v[116:119], v163 offset:16384
	ds_read_b128 v[120:123], v163 offset:17408
	ds_read_b128 v[128:131], v163 offset:18432
	ds_read_b128 v[132:135], v163 offset:19456
	ds_read_b128 v[136:139], v162
	ds_read_b128 v[140:143], v162 offset:1024
	ds_read_b128 v[152:155], v162 offset:2048
	ds_read_b128 v[158:161], v162 offset:3072
	s_movk_i32 s5, 0xff9
	s_waitcnt lgkmcnt(3)
	v_mfma_f32_16x16x32_bf16 v[148:151], v[136:139], v[116:119], v[148:151]
	v_mfma_f32_16x16x32_bf16 v[144:147], v[136:139], v[120:123], v[144:147]
	v_mfma_f32_16x16x32_bf16 v[164:167], v[136:139], v[128:131], v[124:127]
	v_mfma_f32_16x16x32_bf16 v[112:115], v[136:139], v[132:135], v[112:115]
	s_waitcnt lgkmcnt(2)
	v_mfma_f32_16x16x32_bf16 v[108:111], v[140:143], v[116:119], v[108:111]
	v_mfma_f32_16x16x32_bf16 v[104:107], v[140:143], v[120:123], v[104:107]
	v_mfma_f32_16x16x32_bf16 v[100:103], v[140:143], v[128:131], v[100:103]
	v_mfma_f32_16x16x32_bf16 v[96:99], v[140:143], v[132:135], v[96:99]
	s_waitcnt lgkmcnt(1)
	v_mfma_f32_16x16x32_bf16 v[92:95], v[152:155], v[116:119], v[92:95]
	v_mfma_f32_16x16x32_bf16 v[88:91], v[152:155], v[120:123], v[88:91]
	v_mfma_f32_16x16x32_bf16 v[84:87], v[152:155], v[128:131], v[84:87]
	v_mfma_f32_16x16x32_bf16 v[80:83], v[152:155], v[132:135], v[80:83]
	ds_read_b128 v[124:127], v162 offset:4096
	ds_read_b128 v[136:139], v162 offset:5120
	ds_read_b128 v[140:143], v162 offset:6144
	ds_read_b128 v[152:155], v162 offset:7168
	s_waitcnt lgkmcnt(0)
	s_waitcnt vmcnt(0)
	s_barrier
	v_mfma_f32_16x16x32_bf16 v[76:79], v[158:161], v[116:119], v[76:79]
	v_mfma_f32_16x16x32_bf16 v[72:75], v[158:161], v[120:123], v[72:75]
	v_mfma_f32_16x16x32_bf16 v[68:71], v[158:161], v[128:131], v[68:71]
	v_mfma_f32_16x16x32_bf16 v[64:67], v[158:161], v[132:135], v[64:67]
	v_mfma_f32_16x16x32_bf16 v[52:55], v[124:127], v[128:131], v[52:55]
	v_mfma_f32_16x16x32_bf16 v[48:51], v[124:127], v[132:135], v[48:51]
	v_mfma_f32_16x16x32_bf16 v[44:47], v[136:139], v[116:119], v[44:47]
	v_mfma_f32_16x16x32_bf16 v[40:43], v[136:139], v[120:123], v[40:43]
	v_mfma_f32_16x16x32_bf16 v[36:39], v[136:139], v[128:131], v[36:39]
	v_mfma_f32_16x16x32_bf16 v[32:35], v[136:139], v[132:135], v[32:35]
	v_mfma_f32_16x16x32_bf16 v[28:31], v[140:143], v[116:119], v[28:31]
	v_mfma_f32_16x16x32_bf16 v[24:27], v[140:143], v[120:123], v[24:27]
	v_mfma_f32_16x16x32_bf16 v[20:23], v[140:143], v[128:131], v[20:23]
	v_mfma_f32_16x16x32_bf16 v[16:19], v[140:143], v[132:135], v[16:19]
	v_mfma_f32_16x16x32_bf16 v[12:15], v[152:155], v[116:119], v[12:15]
	v_mfma_f32_16x16x32_bf16 v[8:11], v[152:155], v[120:123], v[8:11]
	v_mfma_f32_16x16x32_bf16 v[4:7], v[152:155], v[128:131], v[4:7]
	v_mfma_f32_16x16x32_bf16 v[0:3], v[152:155], v[132:135], v[0:3]
	ds_read_b128 v[128:131], v163 offset:40960
	ds_read_b128 v[132:135], v163 offset:41984
	ds_read_b128 v[136:139], v163 offset:43008
	ds_read_b128 v[140:143], v163 offset:44032
	ds_read_b128 v[152:155], v162 offset:24576
	ds_read_b128 v[158:161], v162 offset:25600
	ds_read_b128 v[168:171], v162 offset:26624
	ds_read_b128 v[172:175], v162 offset:27648
	v_mfma_f32_16x16x32_bf16 v[60:63], v[124:127], v[116:119], v[60:63]
	v_mfma_f32_16x16x32_bf16 v[56:59], v[124:127], v[120:123], v[56:59]
	s_waitcnt lgkmcnt(3)
	v_mfma_f32_16x16x32_bf16 v[124:127], v[152:155], v[128:131], v[148:151]
	v_mfma_f32_16x16x32_bf16 v[120:123], v[152:155], v[132:135], v[144:147]
	v_mfma_f32_16x16x32_bf16 v[116:119], v[152:155], v[136:139], v[164:167]
	v_mfma_f32_16x16x32_bf16 v[112:115], v[152:155], v[140:143], v[112:115]
	s_waitcnt lgkmcnt(2)
	v_mfma_f32_16x16x32_bf16 v[108:111], v[158:161], v[128:131], v[108:111]
	v_mfma_f32_16x16x32_bf16 v[104:107], v[158:161], v[132:135], v[104:107]
	v_mfma_f32_16x16x32_bf16 v[100:103], v[158:161], v[136:139], v[100:103]
	v_mfma_f32_16x16x32_bf16 v[96:99], v[158:161], v[140:143], v[96:99]
	ds_read_b128 v[144:147], v162 offset:28672
	ds_read_b128 v[148:151], v162 offset:29696
	ds_read_b128 v[152:155], v162 offset:30720
	ds_read_b128 v[158:161], v162 offset:31744
	s_waitcnt lgkmcnt(0)
	s_barrier
; DEV f32x4 mfma16(bf16x8 a, bf16x8 b, f32x4 c) { return __builtin_amdgcn_mfma_f32_16x16x32_bf16(a, b, c, 0, 0, 0); }
; DEV void gemm_tile(const u16* __restrict__ A, size_t lda, const u16* __restrict__ Bt, size_t ldb, int K,
;                    u16* sA, u16* sB, f32x4 (&acc)[8][4]) {
;     ...
;       for (int ni = 0; ni < 4; ++ni) b[ni] = *(const bf16x8*)(pb + ni * 16 * 32);
; #pragma unroll
;       for (int mh = 0; mh < 2; ++mh) {
;         bf16x8 a[4];
; #pragma unroll
;         for (int mi = 0; mi < 4; ++mi) a[mi] = *(const bf16x8*)(pa + (mh * 64 + mi * 16) * 32);
; #pragma unroll
;         for (int mi = 0; mi < 4; ++mi)
; #pragma unroll
;           for (int ni = 0; ni < 4; ++ni) acc[mh * 4 + mi][ni] = mfma16(a[mi], b[ni], acc[mh * 4 + mi][ni]);
; DEV void store_tile_bf16(const f32x4 (&acc)[8][4], u16* __restrict__ OUT, size_t ld, int m0, int n0, int ncols,
;                          unsigned char* smem) {
;     ...
; #pragma unroll
;   for (int mh = 0; mh < 2; ++mh) {
; #pragma unroll
;     for (int mi = 0; mi < 4; ++mi)
; #pragma unroll
;       for (int ni = 0; ni < 4; ++ni)
; #pragma unroll
;         for (int j = 0; j < 4; ++j) st[(mi * 16 + fq * 4 + j) * 72 + ni * 16 + fr] = f2bf(acc[mh * 4 + mi][ni][j]);
	v_mfma_f32_16x16x32_bf16 v[92:95], v[168:171], v[128:131], v[92:95]
	v_mfma_f32_16x16x32_bf16 v[76:79], v[172:175], v[128:131], v[76:79]
	v_mfma_f32_16x16x32_bf16 v[60:63], v[144:147], v[128:131], v[60:63]
	v_mfma_f32_16x16x32_bf16 v[44:47], v[148:151], v[128:131], v[44:47]
	v_mfma_f32_16x16x32_bf16 v[28:31], v[152:155], v[128:131], v[28:31]
	v_mfma_f32_16x16x32_bf16 v[12:15], v[158:161], v[128:131], v[12:15]
	v_mov_b32_e32 v129, v178
	s_nop 0
	v_lshrrev_b32_e32 v128, 6, v129
	v_mfma_f32_16x16x32_bf16 v[88:91], v[168:171], v[132:135], v[88:91]
	v_mul_lo_u32 v131, v128, s75
	v_lshrrev_b32_e32 v128, 2, v129
	v_and_b32_e32 v130, 15, v129
	v_mfma_f32_16x16x32_bf16 v[72:75], v[172:175], v[132:135], v[72:75]
	v_lshl_or_b32 v130, v130, 1, v131
	v_mfma_f32_16x16x32_bf16 v[56:59], v[144:147], v[132:135], v[56:59]
	v_mfma_f32_16x16x32_bf16 v[40:43], v[148:151], v[132:135], v[40:43]
	v_mfma_f32_16x16x32_bf16 v[24:27], v[152:155], v[132:135], v[24:27]
	v_mfma_f32_16x16x32_bf16 v[8:11], v[158:161], v[132:135], v[8:11]
	v_lshlrev_b32_e32 v133, 3, v129
	v_and_b32_e32 v132, 12, v128
	v_and_b32_e32 v128, 64, v129
	v_and_b32_e32 v133, 56, v133
	v_or3_b32 v128, v128, s14, v133
	v_lshl_or_b32 v131, v133, 1, v131
	v_bfe_u32 v133, v129, 3, 3
	v_and_b32_e32 v129, 0xffffff80, v129
	v_add_u32_e32 v134, s4, v129
	v_bfe_u32 v135, v124, 16, 1
	s_movk_i32 s4, 0x90
	v_add3_u32 v135, v124, v135, s71
	v_mad_u32_u24 v124, v132, s4, v130
	v_bfe_u32 v130, v125, 16, 1
	v_add3_u32 v125, v125, v130, s71
	ds_write_b16_d16_hi v124, v125 offset:144
	v_bfe_u32 v125, v126, 16, 1
	v_add3_u32 v125, v126, v125, s71
	ds_write_b16_d16_hi v124, v125 offset:288
	v_bfe_u32 v125, v127, 16, 1
	v_add3_u32 v125, v127, v125, s71
	ds_write_b16_d16_hi v124, v125 offset:432
	v_bfe_u32 v125, v120, 16, 1
	v_add3_u32 v120, v120, v125, s71
	ds_write_b16_d16_hi v124, v120 offset:32
	v_bfe_u32 v120, v121, 16, 1
	v_add3_u32 v120, v121, v120, s71
	ds_write_b16_d16_hi v124, v120 offset:176
	v_bfe_u32 v120, v122, 16, 1
	v_add3_u32 v120, v122, v120, s71
	ds_write_b16_d16_hi v124, v120 offset:320
	v_bfe_u32 v120, v123, 16, 1
	v_add3_u32 v120, v123, v120, s71
	ds_write_b16_d16_hi v124, v120 offset:464
	v_bfe_u32 v120, v116, 16, 1
	v_add3_u32 v116, v116, v120, s71
	ds_write_b16_d16_hi v124, v116 offset:64
	v_bfe_u32 v116, v117, 16, 1
	v_add3_u32 v116, v117, v116, s71
	ds_write_b16_d16_hi v124, v116 offset:208
	v_bfe_u32 v116, v118, 16, 1
	v_add3_u32 v116, v118, v116, s71
	ds_write_b16_d16_hi v124, v116 offset:352
	v_bfe_u32 v116, v119, 16, 1
	v_add3_u32 v116, v119, v116, s71
	ds_write_b16_d16_hi v124, v116 offset:496
	v_bfe_u32 v116, v112, 16, 1
	v_add3_u32 v112, v112, v116, s71
	ds_write_b16_d16_hi v124, v112 offset:96
	v_bfe_u32 v112, v113, 16, 1
	v_add3_u32 v112, v113, v112, s71
	ds_write_b16_d16_hi v124, v112 offset:240
	v_bfe_u32 v112, v114, 16, 1
	v_add3_u32 v112, v114, v112, s71
	ds_write_b16_d16_hi v124, v112 offset:384
	v_bfe_u32 v112, v115, 16, 1
	v_add3_u32 v112, v115, v112, s71
	ds_write_b16_d16_hi v124, v112 offset:528
	v_bfe_u32 v112, v108, 16, 1
	v_add3_u32 v108, v108, v112, s71
	ds_write_b16_d16_hi v124, v108 offset:2304
	v_bfe_u32 v108, v109, 16, 1
	v_add3_u32 v108, v109, v108, s71
	ds_write_b16_d16_hi v124, v108 offset:2448
	v_bfe_u32 v108, v110, 16, 1
	v_add3_u32 v108, v110, v108, s71
	ds_write_b16_d16_hi v124, v108 offset:2592
	v_bfe_u32 v108, v111, 16, 1
	v_add3_u32 v108, v111, v108, s71
	ds_write_b16_d16_hi v124, v108 offset:2736
	v_bfe_u32 v108, v104, 16, 1
	v_add3_u32 v104, v104, v108, s71
	ds_write_b16_d16_hi v124, v104 offset:2336
	v_bfe_u32 v104, v105, 16, 1
	v_add3_u32 v104, v105, v104, s71
	ds_write_b16_d16_hi v124, v104 offset:2480
	v_bfe_u32 v104, v106, 16, 1
	v_add3_u32 v104, v106, v104, s71
	ds_write_b16_d16_hi v124, v104 offset:2624
	v_bfe_u32 v104, v107, 16, 1
	v_add3_u32 v104, v107, v104, s71
	ds_write_b16_d16_hi v124, v104 offset:2768
	v_bfe_u32 v104, v100, 16, 1
	v_add3_u32 v100, v100, v104, s71
	ds_write_b16_d16_hi v124, v100 offset:2368
	v_bfe_u32 v100, v101, 16, 1
	v_add3_u32 v100, v101, v100, s71
	ds_write_b16_d16_hi v124, v100 offset:2512
	v_bfe_u32 v100, v102, 16, 1
	v_add3_u32 v100, v102, v100, s71
	ds_write_b16_d16_hi v124, v100 offset:2656
	v_bfe_u32 v100, v103, 16, 1
	v_add3_u32 v100, v103, v100, s71
	ds_write_b16_d16_hi v124, v100 offset:2800
	v_bfe_u32 v100, v96, 16, 1
	v_add3_u32 v96, v96, v100, s71
	ds_write_b16_d16_hi v124, v96 offset:2400
	v_bfe_u32 v96, v97, 16, 1
	v_add3_u32 v96, v97, v96, s71
	ds_write_b16_d16_hi v124, v96 offset:2544
	v_bfe_u32 v96, v98, 16, 1
	v_add3_u32 v96, v98, v96, s71
	ds_write_b16_d16_hi v124, v96 offset:2688
	v_bfe_u32 v96, v99, 16, 1
	v_add3_u32 v96, v99, v96, s71
	ds_write_b16_d16_hi v124, v96 offset:2832
	v_bfe_u32 v96, v92, 16, 1
	v_add3_u32 v92, v92, v96, s71
	ds_write_b16_d16_hi v124, v92 offset:4608
	v_bfe_u32 v92, v93, 16, 1
	v_add3_u32 v92, v93, v92, s71
	ds_write_b16_d16_hi v124, v92 offset:4752
	v_bfe_u32 v92, v94, 16, 1
	v_add3_u32 v92, v94, v92, s71
	ds_write_b16_d16_hi v124, v92 offset:4896
	v_bfe_u32 v92, v95, 16, 1
	v_add3_u32 v92, v95, v92, s71
	ds_write_b16_d16_hi v124, v92 offset:5040
	v_bfe_u32 v92, v88, 16, 1
	v_add3_u32 v88, v88, v92, s71
	ds_write_b16_d16_hi v124, v88 offset:4640
	v_bfe_u32 v88, v89, 16, 1
	v_add3_u32 v88, v89, v88, s71
	v_mfma_f32_16x16x32_bf16 v[84:87], v[168:171], v[136:139], v[84:87]
	ds_write_b16_d16_hi v124, v88 offset:4784
	v_bfe_u32 v88, v90, 16, 1
	v_add3_u32 v88, v90, v88, s71
	ds_write_b16_d16_hi v124, v88 offset:4928
	v_bfe_u32 v88, v91, 16, 1
	v_add3_u32 v88, v91, v88, s71
; DEV void store_tile_bf16(const f32x4 (&acc)[8][4], u16* __restrict__ OUT, size_t ld, int m0, int n0, int ncols,
;                          unsigned char* smem) {
;     ...
; #pragma unroll
;   for (int mh = 0; mh < 2; ++mh) {
; #pragma unroll
;     for (int mi = 0; mi < 4; ++mi)
; #pragma unroll
;       for (int ni = 0; ni < 4; ++ni)
; #pragma unroll
;         for (int j = 0; j < 4; ++j) st[(mi * 16 + fq * 4 + j) * 72 + ni * 16 + fr] = f2bf(acc[mh * 4 + mi][ni][j]);
;     const int chunk = lane & 7;
;     const int c0 = n0 + wc * 64 + chunk * 8;
; #pragma unroll
;     for (int itr = 0; itr < 8; ++itr) {
;       const int rl = (lane >> 3) + 8 * itr;
;       const u32x4 v = *(const u32x4*)(st + rl * 72 + chunk * 8);
;       if (c0 + 8 <= ncols) *(u32x4*)(OUT + (size_t)(m0 + wr * 128 + mh * 64 + rl) * ld + c0) = v;
;     }
	ds_write_b16_d16_hi v124, v88 offset:5072
	s_nop 0
	v_bfe_u32 v88, v84, 16, 1
	v_add3_u32 v84, v84, v88, s71
	ds_write_b16_d16_hi v124, v84 offset:4672
	v_bfe_u32 v84, v85, 16, 1
	v_add3_u32 v84, v85, v84, s71
	v_mfma_f32_16x16x32_bf16 v[80:83], v[168:171], v[140:143], v[80:83]
	ds_write_b16_d16_hi v124, v84 offset:4816
	v_bfe_u32 v84, v86, 16, 1
	v_add3_u32 v84, v86, v84, s71
	ds_write_b16_d16_hi v124, v84 offset:4960
	v_bfe_u32 v84, v87, 16, 1
	v_add3_u32 v84, v87, v84, s71
	ds_write_b16_d16_hi v124, v84 offset:5104
	s_nop 0
	v_bfe_u32 v84, v80, 16, 1
	v_add3_u32 v80, v80, v84, s71
	ds_write_b16_d16_hi v124, v80 offset:4704
	v_bfe_u32 v80, v81, 16, 1
	v_add3_u32 v80, v81, v80, s71
	ds_write_b16_d16_hi v124, v80 offset:4848
	v_bfe_u32 v80, v82, 16, 1
	v_add3_u32 v80, v82, v80, s71
	ds_write_b16_d16_hi v124, v80 offset:4992
	v_bfe_u32 v80, v83, 16, 1
	v_add3_u32 v80, v83, v80, s71
	ds_write_b16_d16_hi v124, v80 offset:5136
	v_bfe_u32 v80, v76, 16, 1
	v_add3_u32 v76, v76, v80, s71
	ds_write_b16_d16_hi v124, v76 offset:6912
	v_bfe_u32 v76, v77, 16, 1
	v_add3_u32 v76, v77, v76, s71
	ds_write_b16_d16_hi v124, v76 offset:7056
	v_bfe_u32 v76, v78, 16, 1
	v_add3_u32 v76, v78, v76, s71
	ds_write_b16_d16_hi v124, v76 offset:7200
	v_bfe_u32 v76, v79, 16, 1
	v_add3_u32 v76, v79, v76, s71
	ds_write_b16_d16_hi v124, v76 offset:7344
	v_bfe_u32 v76, v72, 16, 1
	v_add3_u32 v72, v72, v76, s71
	ds_write_b16_d16_hi v124, v72 offset:6944
	v_bfe_u32 v72, v73, 16, 1
	v_add3_u32 v72, v73, v72, s71
	v_mfma_f32_16x16x32_bf16 v[68:71], v[172:175], v[136:139], v[68:71]
	ds_write_b16_d16_hi v124, v72 offset:7088
	v_bfe_u32 v72, v74, 16, 1
	v_add3_u32 v72, v74, v72, s71
	ds_write_b16_d16_hi v124, v72 offset:7232
	v_bfe_u32 v72, v75, 16, 1
	v_add3_u32 v72, v75, v72, s71
	ds_write_b16_d16_hi v124, v72 offset:7376
	s_nop 0
	v_bfe_u32 v72, v68, 16, 1
	v_add3_u32 v68, v68, v72, s71
	ds_write_b16_d16_hi v124, v68 offset:6976
	v_bfe_u32 v68, v69, 16, 1
	v_add3_u32 v68, v69, v68, s71
	v_mfma_f32_16x16x32_bf16 v[64:67], v[172:175], v[140:143], v[64:67]
	ds_write_b16_d16_hi v124, v68 offset:7120
	v_bfe_u32 v68, v70, 16, 1
	v_add3_u32 v68, v70, v68, s71
	ds_write_b16_d16_hi v124, v68 offset:7264
	v_bfe_u32 v68, v71, 16, 1
	v_add3_u32 v68, v71, v68, s71
	ds_write_b16_d16_hi v124, v68 offset:7408
	s_nop 0
	v_bfe_u32 v68, v64, 16, 1
	v_add3_u32 v64, v64, v68, s71
	ds_write_b16_d16_hi v124, v64 offset:7008
	v_bfe_u32 v64, v65, 16, 1
	v_add3_u32 v64, v65, v64, s71
	ds_write_b16_d16_hi v124, v64 offset:7152
	v_bfe_u32 v64, v66, 16, 1
	v_mfma_f32_16x16x32_bf16 v[52:55], v[144:147], v[136:139], v[52:55]
	v_add3_u32 v64, v66, v64, s71
	ds_write_b16_d16_hi v124, v64 offset:7296
	v_bfe_u32 v64, v67, 16, 1
	v_mfma_f32_16x16x32_bf16 v[48:51], v[144:147], v[140:143], v[48:51]
	v_ashrrev_i32_e32 v129, 31, v128
	v_add3_u32 v64, v67, v64, s71
	v_cmp_gt_i32_e32 vcc, s5, v128
	v_mfma_f32_16x16x32_bf16 v[36:39], v[148:151], v[136:139], v[36:39]
	v_lshl_add_u64 v[128:129], v[128:129], 1, s[68:69]
	ds_write_b16_d16_hi v124, v64 offset:7440
	v_mad_u32_u24 v66, v133, s4, v131
	v_mfma_f32_16x16x32_bf16 v[32:35], v[148:151], v[140:143], v[32:35]
	v_or_b32_e32 v64, v134, v133
	ds_write_b16_d16_hi v124, v135
	v_mfma_f32_16x16x32_bf16 v[20:23], v[152:155], v[136:139], v[20:23]
	v_mfma_f32_16x16x32_bf16 v[16:19], v[152:155], v[140:143], v[16:19]
	v_mfma_f32_16x16x32_bf16 v[4:7], v[158:161], v[136:139], v[4:7]
	v_mfma_f32_16x16x32_bf16 v[0:3], v[158:161], v[140:143], v[0:3]
	s_and_saveexec_b64 s[4:5], vcc
	s_cbranch_execz .LBB0_417
	ds_read_b128 v[68:71], v66
	v_ashrrev_i32_e32 v65, 31, v64
	v_lshlrev_b64 v[72:73], 13, v[64:65]
	v_lshl_add_u64 v[72:73], v[128:129], 0, v[72:73]
	s_waitcnt lgkmcnt(0)
	global_store_dwordx4 v[72:73], v[68:71], off
	ds_read_b128 v[68:71], v66 offset:1152
	v_or_b32_e32 v72, 8, v64
	v_ashrrev_i32_e32 v73, 31, v72
	v_lshlrev_b64 v[72:73], 13, v[72:73]
	v_lshl_add_u64 v[72:73], v[128:129], 0, v[72:73]
	s_waitcnt lgkmcnt(0)
	global_store_dwordx4 v[72:73], v[68:71], off
	ds_read_b128 v[68:71], v66 offset:2304
	v_or_b32_e32 v72, 16, v64
	v_ashrrev_i32_e32 v73, 31, v72
	v_lshlrev_b64 v[72:73], 13, v[72:73]
	v_lshl_add_u64 v[72:73], v[128:129], 0, v[72:73]
	s_waitcnt lgkmcnt(0)
	global_store_dwordx4 v[72:73], v[68:71], off
	ds_read_b128 v[68:71], v66 offset:3456
	v_or_b32_e32 v72, 24, v64
	v_ashrrev_i32_e32 v73, 31, v72
	v_lshlrev_b64 v[72:73], 13, v[72:73]
	v_lshl_add_u64 v[72:73], v[128:129], 0, v[72:73]
	s_waitcnt lgkmcnt(0)
	global_store_dwordx4 v[72:73], v[68:71], off
	ds_read_b128 v[68:71], v66 offset:4608
	v_or_b32_e32 v72, 32, v64
	v_ashrrev_i32_e32 v73, 31, v72
	v_lshlrev_b64 v[72:73], 13, v[72:73]
	v_lshl_add_u64 v[72:73], v[128:129], 0, v[72:73]
	s_waitcnt lgkmcnt(0)
	global_store_dwordx4 v[72:73], v[68:71], off
	ds_read_b128 v[68:71], v66 offset:5760
	v_or_b32_e32 v72, 40, v64
	v_ashrrev_i32_e32 v73, 31, v72
	v_lshlrev_b64 v[72:73], 13, v[72:73]
	v_lshl_add_u64 v[72:73], v[128:129], 0, v[72:73]
	s_waitcnt lgkmcnt(0)
	global_store_dwordx4 v[72:73], v[68:71], off
	ds_read_b128 v[68:71], v66 offset:6912
	v_or_b32_e32 v72, 48, v64
	v_ashrrev_i32_e32 v73, 31, v72
	v_lshlrev_b64 v[72:73], 13, v[72:73]
	v_lshl_add_u64 v[72:73], v[128:129], 0, v[72:73]
	s_waitcnt lgkmcnt(0)
	global_store_dwordx4 v[72:73], v[68:71], off
	ds_read_b128 v[68:71], v66 offset:8064
	v_or_b32_e32 v72, 56, v64
	v_ashrrev_i32_e32 v73, 31, v72
	v_lshlrev_b64 v[72:73], 13, v[72:73]
	v_lshl_add_u64 v[72:73], v[128:129], 0, v[72:73]
	s_waitcnt lgkmcnt(0)
	global_store_dwordx4 v[72:73], v[68:71], off
